# DMA piece order swapped: weight-side (B) pieces issued in the early half after the mid barrier, activation-side (A) pieces in the next sub-step
# speedup vs baseline: 1.0072x; 1.0072x over previous
; DI void wait_vm0() { asm volatile("s_waitcnt vmcnt(0)" ::: "memory"); }
;   DI void pre(int grow0, int gcol0, int lane, int w, char* lds) { xpass(0, grow0, gcol0, lane, w, lds); }
; template <int BK> DI int swz(int row) { constexpr int CPR = BK / 8; return (row / (16 / CPR)) % CPR; }
; template <int ROWS, int BK>
; DI void stage_tile(const bf16_t* g, int ld, char* l, int tid) {
;   constexpr int CPR = BK / 8, TOT = ROWS * CPR, N = (TOT + NT - 1) / NT;
;   const int row0 = tid / CPR, pc = tid % CPR; const int c = pc ^ swz<BK>(row0);
;   const unsigned voff = (unsigned)(row0 * ld + c * 8) * 2u;
; #pragma unroll
;   for (int i = 0; i < N; ++i) {
;     if (TOT % NT == 0 || tid + i * NT < TOT) {
;       const char* gb = (const char*)g + (size_t)i * (NT / CPR) * ld * 2;
;       __builtin_amdgcn_global_load_lds((const unsigned*)(gb + voff), (__attribute__((address_space(3))) unsigned*)(l + i * NT * 16 + __builtin_amdgcn_readfirstlane(tid >> 6) * 1024), 16, 0, 0);
;     }
;   }
; }
;     ...
;   const bf16_t* Ag = A + (size_t)row0 * lda; const bf16_t* Bg = Bt + (size_t)col0 * ldb;
;   const int wv = __builtin_amdgcn_readfirstlane(tid >> 6);
;   __syncthreads();
;   if (!pre) { stage_tile<BM, BK>(Ag, lda, lds, tid); stage_tile<BN, BK>(Bg, ldb, lds + ABYTES, tid); }
;   wait_vm0();
;   __syncthreads();
;   const int nk = K / BK;
;   for (int kt = 0; kt < nk; ++kt) {
;     char* cur = lds + (kt & 1) * STG; char* nxt = lds + ((kt + 1) & 1) * STG;
;     const bool more = kt + 1 < nk;
;     const bf16_t* An = Ag + (kt + 1) * BK; const bf16_t* Bn = Bg + (kt + 1) * BK;
;     if (!more) epi.pre(row0 + wm * 64, col0 + wn * (32 * NTW), lane, w, lds);
;     bf16x8 fa[2][2], fb[2][NTW];
; #pragma unroll
;     for (int mt = 0; mt < 2; ++mt) { int row = wm * 64 + mt * 32 + l31; fa[0][mt] = *(const bf16x8*)(cur + row * (BK * 2) + ((hh ^ swz<BK>(row)) << 4)); }
; #pragma unroll
;     for (int nt = 0; nt < NTW; ++nt) { int row = wn * (32 * NTW) + nt * 32 + l31; fb[0][nt] = *(const bf16x8*)(cur + ABYTES + row * (BK * 2) + ((hh ^ swz<BK>(row)) << 4)); }
.LBB0_168:
	s_mov_b64 s[30:31], -1
	s_waitcnt lgkmcnt(0)
	s_mov_b64 s[42:43], 0
	s_cmp_lt_i32 s70, 2
	s_mov_b64 s[6:7], 0
	v_writelane_b32 v255, s71, 50
	s_cbranch_scc1 .LBB0_243
	s_cmp_eq_u32 s70, 2
	s_mov_b64 s[6:7], -1
	s_cbranch_scc0 .LBB0_288
	s_cmp_lt_i32 s71, 1
	s_cbranch_scc1 .LBB0_277
	s_cmp_lg_u32 s71, 1
	s_cbranch_scc0 .LBB0_259
	v_readlane_b32 s2, v254, 61
	v_readlane_b32 s3, v254, 62
	v_mov_b32_e32 v8, v216
	s_load_dwordx2 s[2:3], s[2:3], 0x1f8
	v_readlane_b32 s6, v253, 13
	v_ashrrev_i32_e32 v2, 31, v8
	v_lshrrev_b32_e32 v3, 29, v2
	v_lshrrev_b32_e32 v2, 28, v2
	v_add_u32_e32 v2, v8, v2
	v_ashrrev_i32_e32 v2, 4, v2
	v_lshrrev_b32_e32 v5, 29, v2
	v_add_u32_e32 v3, v8, v3
	v_add_u32_e32 v5, v2, v5
	v_readlane_b32 s7, v253, 14
	s_waitcnt lgkmcnt(0)
	s_add_u32 s2, s2, s6
	v_and_b32_e32 v4, 0xffffff8, v3
	v_and_b32_e32 v5, 0xffffff8, v5
	s_addc_u32 s3, s3, s7
	v_sub_u32_e32 v4, v8, v4
	v_sub_u32_e32 v2, v2, v5
	v_lshlrev_b32_e32 v3, 8, v3
	v_readfirstlane_b32 s7, v8
	v_xor_b32_e32 v2, v2, v4
	v_and_b32_e32 v3, 0xfffff800, v3
	v_readlane_b32 s30, v253, 11
	s_lshl_b32 s7, s7, 4
	v_lshl_add_u32 v2, v2, 4, v3
	v_mov_b32_e32 v3, v1
	v_readlane_b32 s31, v253, 12
	s_and_b32 s7, s7, 0xfffffc00
	s_mov_b32 m0, s7
	v_lshl_add_u64 v[4:5], s[30:31], 0, v[2:3]
	s_barrier
	s_nop 0
	global_load_lds_dwordx4 v2, s[30:31]
	v_lshl_add_u64 v[6:7], v[4:5], 0, s[58:59]
	s_add_i32 m0, s7, 0x2000
	s_waitcnt vmcnt(0)
	v_lshl_add_u64 v[130:131], s[2:3], 0, v[2:3]
	global_load_lds_dwordx4 v[6:7], off
	v_lshl_add_u64 v[6:7], v[4:5], 0, s[48:49]
	s_add_i32 m0, s7, 0x4000
	v_lshl_add_u64 v[4:5], v[4:5], 0, s[50:51]
	global_load_lds_dwordx4 v[6:7], off
	s_add_i32 m0, s7, 0x6000
	v_ashrrev_i32_e32 v134, 6, v8
	global_load_lds_dwordx4 v[4:5], off
	s_add_i32 m0, s7, 0x8000
	v_lshl_add_u64 v[4:5], v[130:131], 0, s[58:59]
	global_load_lds_dwordx4 v2, s[2:3]
	s_add_i32 m0, s7, 0xa000
	v_and_b32_e32 v6, 31, v8
	global_load_lds_dwordx4 v[4:5], off
	v_lshl_add_u64 v[4:5], v[130:131], 0, s[48:49]
	s_add_i32 m0, s7, 0xc000
	v_and_b32_e32 v0, 63, v8
	global_load_lds_dwordx4 v[4:5], off
	v_lshl_add_u64 v[4:5], v[130:131], 0, s[50:51]
	s_add_i32 m0, s7, 0xe000
	v_bfe_u32 v135, v8, 5, 1
	global_load_lds_dwordx4 v[4:5], off
	v_lshrrev_b32_e32 v4, 30, v134
	v_add_u32_e32 v4, v134, v4
	v_ashrrev_i32_e32 v5, 2, v4
	v_mul_i32_i24_e32 v7, 4, v5
	v_sub_u32_e32 v7, v134, v7
	v_lshlrev_b32_e32 v169, 6, v7
	v_lshlrev_b32_e32 v164, 7, v5
	v_or_b32_e32 v5, v169, v6
	v_bfe_u32 v7, v7, 25, 1
	v_lshlrev_b32_e32 v136, 7, v5
	v_add_u32_e32 v8, v5, v7
	v_or_b32_e32 v5, 32, v5
	v_lshlrev_b32_e32 v144, 7, v5
	v_add_u32_e32 v5, v5, v7
	v_ashrrev_i32_e32 v7, 1, v5
	v_ashrrev_i32_e32 v5, 31, v5
	v_ashrrev_i32_e32 v9, 1, v8
	v_ashrrev_i32_e32 v8, 31, v8
	v_lshrrev_b32_e32 v5, 29, v5
	v_lshrrev_b32_e32 v8, 29, v8
	v_add_u32_e32 v5, v7, v5
	v_add_u32_e32 v8, v9, v8
	v_and_b32_e32 v5, -8, v5
	v_and_b32_e32 v8, -8, v8
	v_sub_u32_e32 v5, v7, v5
	v_or_b32_e32 v6, v164, v6
	v_sub_u32_e32 v8, v9, v8
	v_xor_b32_e32 v7, v5, v135
	v_lshrrev_b32_e32 v4, 31, v4
	v_xor_b32_e32 v9, v8, v135
	v_lshlrev_b32_e32 v146, 4, v7
	v_add_u32_e32 v7, v6, v4
	v_lshlrev_b32_e32 v143, 4, v9
	v_ashrrev_i32_e32 v9, 1, v7
	v_ashrrev_i32_e32 v7, 31, v7
	v_lshrrev_b32_e32 v7, 29, v7
	v_add_u32_e32 v7, v9, v7
	v_and_b32_e32 v7, -8, v7
	v_sub_u32_e32 v7, v9, v7
	v_xor_b32_e32 v9, v7, v135
	v_lshlrev_b32_e32 v151, 4, v9
	v_or_b32_e32 v9, 32, v6
	v_lshlrev_b32_e32 v152, 7, v9
	v_add_u32_e32 v9, v9, v4
	v_ashrrev_i32_e32 v10, 1, v9
	v_ashrrev_i32_e32 v9, 31, v9
	v_lshrrev_b32_e32 v9, 29, v9
	v_add_u32_e32 v9, v10, v9
	v_and_b32_e32 v9, -8, v9
	v_sub_u32_e32 v9, v10, v9
	v_xor_b32_e32 v10, v9, v135
	v_lshlrev_b32_e32 v145, 7, v6
	v_lshlrev_b32_e32 v156, 4, v10
	v_or_b32_e32 v10, 64, v6
	v_or_b32_e32 v6, 0x60, v6
	v_lshlrev_b32_e32 v155, 7, v10
	v_add_u32_e32 v10, v10, v4
	v_add_u32_e32 v4, v6, v4
	v_lshlrev_b32_e32 v158, 7, v6
	v_ashrrev_i32_e32 v6, 1, v4
	v_ashrrev_i32_e32 v4, 31, v4
	v_lshrrev_b32_e32 v4, 29, v4
	v_add_u32_e32 v4, v6, v4
	v_and_b32_e32 v4, -8, v4
	v_sub_u32_e32 v4, v6, v4
	v_ashrrev_i32_e32 v11, 1, v10
	v_ashrrev_i32_e32 v10, 31, v10
	v_xor_b32_e32 v6, v4, v135
	v_lshrrev_b32_e32 v10, 29, v10
	v_lshlrev_b32_e32 v168, 4, v6
	v_bitop3_b32 v6, v8, v135, 2 bitop3:0x1e
	v_add_u32_e32 v10, v11, v10
	v_lshlrev_b32_e32 v166, 4, v6
	v_bitop3_b32 v6, v5, v135, 2 bitop3:0x1e
	v_and_b32_e32 v10, -8, v10
	v_lshlrev_b32_e32 v167, 4, v6
	v_bitop3_b32 v6, v7, v135, 2 bitop3:0x1e
	v_sub_u32_e32 v10, v11, v10
	v_lshlrev_b32_e32 v161, 4, v6
	v_bitop3_b32 v6, v9, v135, 2 bitop3:0x1e
	v_lshlrev_b32_e32 v163, 4, v6
	v_bitop3_b32 v6, v10, v135, 2 bitop3:0x1e
	v_lshlrev_b32_e32 v159, 4, v6
	v_bitop3_b32 v6, v4, v135, 2 bitop3:0x1e
	v_lshlrev_b32_e32 v160, 4, v6
	v_bitop3_b32 v6, v8, v135, 4 bitop3:0x1e
	v_lshlrev_b32_e32 v153, 4, v6
	v_bitop3_b32 v6, v5, v135, 4 bitop3:0x1e
	v_lshlrev_b32_e32 v154, 4, v6
	v_bitop3_b32 v6, v7, v135, 4 bitop3:0x1e
	v_readfirstlane_b32 s6, v134
	v_lshlrev_b32_e32 v149, 4, v6
	v_bitop3_b32 v6, v9, v135, 4 bitop3:0x1e
	v_bitop3_b32 v5, v5, v135, 6 bitop3:0x1e
	s_lshl_b32 s2, s6, 10
	v_lshlrev_b32_e32 v150, 4, v6
	v_bitop3_b32 v6, v10, v135, 4 bitop3:0x1e
	v_lshlrev_b32_e32 v142, 4, v5
	v_bitop3_b32 v5, v7, v135, 6 bitop3:0x1e
	v_readlane_b32 s6, v254, 28
	s_waitcnt vmcnt(0)
; DI f32x16 zero16() { f32x16 z; for (int i = 0; i < 16; ++i) z[i] = 0.f; return z; }
; template <int BK> DI int swz(int row) { constexpr int CPR = BK / 8; return (row / (16 / CPR)) % CPR; }
; DI void wait_vm0() { asm volatile("s_waitcnt vmcnt(0)" ::: "memory"); }
;     ...
;   f32x16 acc[2][NTW];
; #pragma unroll
;   for (int a = 0; a < 2; ++a)
; #pragma unroll
;     for (int b = 0; b < NTW; ++b) acc[a][b] = zero16();
;   const bf16_t* Ag = A + (size_t)row0 * lda; const bf16_t* Bg = Bt + (size_t)col0 * ldb;
;   const int wv = __builtin_amdgcn_readfirstlane(tid >> 6);
;   __syncthreads();
;   if (!pre) { stage_tile<BM, BK>(Ag, lda, lds, tid); stage_tile<BN, BK>(Bg, ldb, lds + ABYTES, tid); }
;   wait_vm0();
;   __syncthreads();
;   const int nk = K / BK;
;   for (int kt = 0; kt < nk; ++kt) {
;     char* cur = lds + (kt & 1) * STG; char* nxt = lds + ((kt + 1) & 1) * STG;
;     const bool more = kt + 1 < nk;
;     const bf16_t* An = Ag + (kt + 1) * BK; const bf16_t* Bn = Bg + (kt + 1) * BK;
;     if (!more) epi.pre(row0 + wm * 64, col0 + wn * (32 * NTW), lane, w, lds);
;     bf16x8 fa[2][2], fb[2][NTW];
; #pragma unroll
;     for (int mt = 0; mt < 2; ++mt) { int row = wm * 64 + mt * 32 + l31; fa[0][mt] = *(const bf16x8*)(cur + row * (BK * 2) + ((hh ^ swz<BK>(row)) << 4)); }
; #pragma unroll
;     for (int nt = 0; nt < NTW; ++nt) { int row = wn * (32 * NTW) + nt * 32 + l31; fb[0][nt] = *(const bf16x8*)(cur + ABYTES + row * (BK * 2) + ((hh ^ swz<BK>(row)) << 4)); }
; #pragma unroll
;     for (int kk = 0; kk < NKK; ++kk) {
;       if (kk + 1 < NKK) {
;         const int ch = (kk + 1) * 2 + hh;
; #pragma unroll
;         for (int mt = 0; mt < 2; ++mt) { int row = wm * 64 + mt * 32 + l31; fa[(kk + 1) & 1][mt] = *(const bf16x8*)(cur + row * (BK * 2) + ((ch ^ swz<BK>(row)) << 4)); }
; #pragma unroll
;         for (int nt = 0; nt < NTW; ++nt) { int row = wn * (32 * NTW) + nt * 32 + l31; fb[(kk + 1) & 1][nt] = *(const bf16x8*)(cur + ABYTES + row * (BK * 2) + ((ch ^ swz<BK>(row)) << 4)); }
;       }
;       if (more) {
; #pragma unroll
;         for (int q = 0; q < PPK; ++q) {
;           const int pi = kk * PPK + q;
;           if (pi < NPA) stage_piece<BM, BK>(An, lda, nxt, tid, pi, wv);
;           else if (pi < NP) stage_piece<BN, BK>(Bn, ldb, nxt + ABYTES, tid, pi - NPA, wv);
;         }
;       }
	v_lshlrev_b32_e32 v147, 4, v6
	v_bitop3_b32 v6, v4, v135, 4 bitop3:0x1e
	v_lshlrev_b32_e32 v139, 4, v5
	v_bitop3_b32 v5, v9, v135, 6 bitop3:0x1e
	v_readlane_b32 s7, v254, 29
	v_xor_b32_e32 v11, v10, v135
	v_lshlrev_b32_e32 v148, 4, v6
	v_bitop3_b32 v6, v8, v135, 6 bitop3:0x1e
	v_lshlrev_b32_e32 v140, 4, v5
	v_bitop3_b32 v5, v10, v135, 6 bitop3:0x1e
	v_bitop3_b32 v4, v4, v135, 6 bitop3:0x1e
	v_lshl_add_u64 v[132:133], s[6:7], 0, v[2:3]
	v_mov_b32_e32 v2, 0
	v_lshlrev_b32_e32 v157, 4, v11
	v_lshlrev_b32_e32 v141, 4, v6
	v_lshlrev_b32_e32 v137, 4, v5
	v_lshlrev_b32_e32 v138, 4, v4
	s_mov_b64 s[6:7], 0
	s_mov_b32 s3, 0x10000
	v_mov_b32_e32 v3, v2
	v_mov_b32_e32 v4, v2
	v_mov_b32_e32 v5, v2
	v_mov_b32_e32 v6, v2
	v_mov_b32_e32 v7, v2
	v_mov_b32_e32 v8, v2
	v_mov_b32_e32 v9, v2
	v_mov_b32_e32 v10, v2
	v_mov_b32_e32 v11, v2
	v_mov_b32_e32 v12, v2
	v_mov_b32_e32 v13, v2
	v_mov_b32_e32 v14, v2
	v_mov_b32_e32 v15, v2
	v_mov_b32_e32 v16, v2
	v_mov_b32_e32 v17, v2
	v_mov_b32_e32 v18, v2
	v_mov_b32_e32 v19, v2
	v_mov_b32_e32 v20, v2
	v_mov_b32_e32 v21, v2
	v_mov_b32_e32 v22, v2
	v_mov_b32_e32 v23, v2
	v_mov_b32_e32 v24, v2
	v_mov_b32_e32 v25, v2
	v_mov_b32_e32 v26, v2
	v_mov_b32_e32 v27, v2
	v_mov_b32_e32 v28, v2
	v_mov_b32_e32 v29, v2
	v_mov_b32_e32 v30, v2
	v_mov_b32_e32 v31, v2
	v_mov_b32_e32 v32, v2
	v_mov_b32_e32 v33, v2
	v_mov_b32_e32 v34, v2
	v_mov_b32_e32 v35, v2
	v_mov_b32_e32 v36, v2
	v_mov_b32_e32 v37, v2
	v_mov_b32_e32 v38, v2
	v_mov_b32_e32 v39, v2
	v_mov_b32_e32 v40, v2
	v_mov_b32_e32 v41, v2
	v_mov_b32_e32 v42, v2
	v_mov_b32_e32 v43, v2
	v_mov_b32_e32 v44, v2
	v_mov_b32_e32 v45, v2
	v_mov_b32_e32 v46, v2
	v_mov_b32_e32 v47, v2
	v_mov_b32_e32 v48, v2
	v_mov_b32_e32 v49, v2
	v_mov_b32_e32 v50, v2
	v_mov_b32_e32 v51, v2
	v_mov_b32_e32 v52, v2
	v_mov_b32_e32 v53, v2
	v_mov_b32_e32 v54, v2
	v_mov_b32_e32 v55, v2
	v_mov_b32_e32 v56, v2
	v_mov_b32_e32 v57, v2
	v_mov_b32_e32 v58, v2
	v_mov_b32_e32 v59, v2
	v_mov_b32_e32 v60, v2
	v_mov_b32_e32 v61, v2
	v_mov_b32_e32 v62, v2
	v_mov_b32_e32 v63, v2
	v_mov_b32_e32 v64, v2
	v_mov_b32_e32 v65, v2
	v_mov_b32_e32 v66, v2
	v_mov_b32_e32 v67, v2
	v_mov_b32_e32 v68, v2
	v_mov_b32_e32 v69, v2
	v_mov_b32_e32 v70, v2
	v_mov_b32_e32 v71, v2
	v_mov_b32_e32 v72, v2
	v_mov_b32_e32 v73, v2
	v_mov_b32_e32 v74, v2
	v_mov_b32_e32 v75, v2
	v_mov_b32_e32 v76, v2
	v_mov_b32_e32 v77, v2
	v_mov_b32_e32 v78, v2
	v_mov_b32_e32 v79, v2
	v_mov_b32_e32 v80, v2
	v_mov_b32_e32 v81, v2
	v_mov_b32_e32 v82, v2
	v_mov_b32_e32 v83, v2
	v_mov_b32_e32 v84, v2
	v_mov_b32_e32 v85, v2
	v_mov_b32_e32 v86, v2
	v_mov_b32_e32 v87, v2
	v_mov_b32_e32 v88, v2
	v_mov_b32_e32 v89, v2
	v_mov_b32_e32 v90, v2
	v_mov_b32_e32 v91, v2
	v_mov_b32_e32 v92, v2
	v_mov_b32_e32 v93, v2
	v_mov_b32_e32 v94, v2
	v_mov_b32_e32 v95, v2
	v_mov_b32_e32 v96, v2
	v_mov_b32_e32 v97, v2
	v_mov_b32_e32 v98, v2
	v_mov_b32_e32 v99, v2
	v_mov_b32_e32 v100, v2
	v_mov_b32_e32 v101, v2
	v_mov_b32_e32 v102, v2
	v_mov_b32_e32 v103, v2
	v_mov_b32_e32 v104, v2
	v_mov_b32_e32 v105, v2
	v_mov_b32_e32 v106, v2
	v_mov_b32_e32 v107, v2
	v_mov_b32_e32 v108, v2
	v_mov_b32_e32 v109, v2
	v_mov_b32_e32 v110, v2
	v_mov_b32_e32 v111, v2
	v_mov_b32_e32 v112, v2
	v_mov_b32_e32 v113, v2
	v_mov_b32_e32 v114, v2
	v_mov_b32_e32 v115, v2
	v_mov_b32_e32 v116, v2
	v_mov_b32_e32 v117, v2
	v_mov_b32_e32 v118, v2
	v_mov_b32_e32 v119, v2
	v_mov_b32_e32 v120, v2
	v_mov_b32_e32 v121, v2
	v_mov_b32_e32 v122, v2
	v_mov_b32_e32 v123, v2
	v_mov_b32_e32 v124, v2
	v_mov_b32_e32 v125, v2
	v_mov_b32_e32 v126, v2
	v_mov_b32_e32 v127, v2
	v_mov_b32_e32 v128, v2
	v_mov_b32_e32 v129, v2
	s_waitcnt vmcnt(0) lgkmcnt(0)
	s_barrier
	v_add_u32_e32 v170, v136, v143
	v_add_u32_e32 v174, v144, v146
	ds_read_b128 v[170:173], v170
	v_add_u32_e32 v178, v145, v151
	ds_read_b128 v[174:177], v174
	v_add_u32_e32 v182, v152, v156
	ds_read_b128 v[178:181], v178 offset:32768
	v_add_u32_e32 v186, v155, v157
	ds_read_b128 v[182:185], v182 offset:32768
	v_add_u32_e32 v190, v158, v168
	ds_read_b128 v[186:189], v186 offset:32768
	ds_read_b128 v[190:193], v190 offset:32768
	s_and_b32 s30, s3, 0x10000
	s_add_i32 s31, s30, s2
	v_lshl_add_u64 v[214:215], v[132:133], 0, s[6:7]
	v_lshl_add_u64 v[230:231], v[130:131], 0, s[6:7]
	s_add_i32 m0, s31, 0x8000
	v_lshl_add_u64 v[232:233], v[230:231], 0, s[28:29]
	global_load_lds_dwordx4 v[232:233], off
	s_add_i32 m0, s31, 0xa000
	v_lshl_add_u64 v[232:233], v[230:231], 0, s[24:25]
	global_load_lds_dwordx4 v[232:233], off
	s_add_i32 m0, s31, 0xc000
	v_lshl_add_u64 v[232:233], v[230:231], 0, s[26:27]
	global_load_lds_dwordx4 v[232:233], off
	s_add_i32 m0, s31, 0xe000
	v_lshl_add_u64 v[232:233], v[230:231], 0, s[38:39]
	global_load_lds_dwordx4 v[232:233], off
; DI f32x16 mfma(bf16x8 a, bf16x8 b, f32x16 c) { return __builtin_amdgcn_mfma_f32_32x32x16_bf16(a, b, c, 0, 0, 0); }
; template <int BK> DI int swz(int row) { constexpr int CPR = BK / 8; return (row / (16 / CPR)) % CPR; }
; DI void wait_vm0() { asm volatile("s_waitcnt vmcnt(0)" ::: "memory"); }
;   DI void pre(int grow0, int gcol0, int lane, int w, char* lds) { xpass(0, grow0, gcol0, lane, w, lds); }
;     ...
;   for (int kt = 0; kt < nk; ++kt) {
;     char* cur = lds + (kt & 1) * STG; char* nxt = lds + ((kt + 1) & 1) * STG;
;     const bool more = kt + 1 < nk;
;     const bf16_t* An = Ag + (kt + 1) * BK; const bf16_t* Bn = Bg + (kt + 1) * BK;
;     if (!more) epi.pre(row0 + wm * 64, col0 + wn * (32 * NTW), lane, w, lds);
;     bf16x8 fa[2][2], fb[2][NTW];
; #pragma unroll
;     for (int mt = 0; mt < 2; ++mt) { int row = wm * 64 + mt * 32 + l31; fa[0][mt] = *(const bf16x8*)(cur + row * (BK * 2) + ((hh ^ swz<BK>(row)) << 4)); }
; #pragma unroll
;     for (int nt = 0; nt < NTW; ++nt) { int row = wn * (32 * NTW) + nt * 32 + l31; fb[0][nt] = *(const bf16x8*)(cur + ABYTES + row * (BK * 2) + ((hh ^ swz<BK>(row)) << 4)); }
; #pragma unroll
;     for (int kk = 0; kk < NKK; ++kk) {
;       if (kk + 1 < NKK) {
;         const int ch = (kk + 1) * 2 + hh;
; #pragma unroll
;         for (int mt = 0; mt < 2; ++mt) { int row = wm * 64 + mt * 32 + l31; fa[(kk + 1) & 1][mt] = *(const bf16x8*)(cur + row * (BK * 2) + ((ch ^ swz<BK>(row)) << 4)); }
; #pragma unroll
;         for (int nt = 0; nt < NTW; ++nt) { int row = wn * (32 * NTW) + nt * 32 + l31; fb[(kk + 1) & 1][nt] = *(const bf16x8*)(cur + ABYTES + row * (BK * 2) + ((ch ^ swz<BK>(row)) << 4)); }
;       }
;       if (more) {
; #pragma unroll
;         for (int q = 0; q < PPK; ++q) {
;           const int pi = kk * PPK + q;
;           if (pi < NPA) stage_piece<BM, BK>(An, lda, nxt, tid, pi, wv);
;           else if (pi < NP) stage_piece<BN, BK>(Bn, ldb, nxt + ABYTES, tid, pi - NPA, wv);
;         }
;       }
;       __builtin_amdgcn_s_setprio(1);
; #pragma unroll
;       for (int mt = 0; mt < 2; ++mt)
; #pragma unroll
;         for (int nt = 0; nt < NTW; ++nt) acc[mt][nt] = mfma(fa[kk & 1][mt], fb[kk & 1][nt], acc[mt][nt]);
;       __builtin_amdgcn_s_setprio(0);
;       __builtin_amdgcn_sched_barrier(0);
;     }
;     wait_vm0();
;     __syncthreads();
.LBB0_173:
	s_and_b32 s30, s3, 0x10000
	s_xor_b32 s100, s30, 0x10000
	v_add3_u32 v194, s100, v136, v166
	v_add3_u32 v198, s100, v144, v167
	ds_read_b128 v[194:197], v194
	v_add3_u32 v202, s100, v145, v161
	ds_read_b128 v[198:201], v198
	v_add3_u32 v206, s100, v152, v163
	ds_read_b128 v[202:205], v202 offset:32768
	v_add3_u32 v210, s100, v155, v159
	ds_read_b128 v[206:209], v206 offset:32768
	v_add3_u32 v226, s100, v158, v160
	ds_read_b128 v[210:213], v210 offset:32768
	ds_read_b128 v[226:229], v226 offset:32768
	s_waitcnt lgkmcnt(6)
	s_mov_b32 m0, s31
	v_lshl_add_u64 v[232:233], v[214:215], 0, s[28:29]
	v_mfma_f32_32x32x16_bf16 v[114:129], v[170:173], v[178:181], v[114:129]
	global_load_lds_dwordx4 v[232:233], off
	s_add_i32 m0, s31, 0x2000
	v_lshl_add_u64 v[232:233], v[214:215], 0, s[24:25]
	v_mfma_f32_32x32x16_bf16 v[98:113], v[170:173], v[182:185], v[98:113]
	v_mfma_f32_32x32x16_bf16 v[82:97], v[170:173], v[186:189], v[82:97]
	global_load_lds_dwordx4 v[232:233], off
	s_add_i32 m0, s31, 0x4000
	v_lshl_add_u64 v[232:233], v[214:215], 0, s[26:27]
	v_mfma_f32_32x32x16_bf16 v[66:81], v[170:173], v[190:193], v[66:81]
	v_mfma_f32_32x32x16_bf16 v[50:65], v[174:177], v[178:181], v[50:65]
	global_load_lds_dwordx4 v[232:233], off
	s_add_i32 m0, s31, 0x6000
	v_lshl_add_u64 v[232:233], v[214:215], 0, s[38:39]
	v_mfma_f32_32x32x16_bf16 v[34:49], v[174:177], v[182:185], v[34:49]
	v_mfma_f32_32x32x16_bf16 v[18:33], v[174:177], v[186:189], v[18:33]
	global_load_lds_dwordx4 v[232:233], off
	v_mfma_f32_32x32x16_bf16 v[2:17], v[174:177], v[190:193], v[2:17]
	v_add3_u32 v170, s100, v136, v153
	v_add3_u32 v174, s100, v144, v154
	ds_read_b128 v[170:173], v170
	v_add3_u32 v178, s100, v145, v149
	ds_read_b128 v[174:177], v174
	v_add3_u32 v182, s100, v152, v150
	ds_read_b128 v[178:181], v178 offset:32768
	v_add3_u32 v186, s100, v155, v147
	ds_read_b128 v[182:185], v182 offset:32768
	v_add3_u32 v190, s100, v158, v148
	ds_read_b128 v[186:189], v186 offset:32768
	ds_read_b128 v[190:193], v190 offset:32768
	s_waitcnt lgkmcnt(6)
	v_mfma_f32_32x32x16_bf16 v[114:129], v[194:197], v[202:205], v[114:129]
	v_mfma_f32_32x32x16_bf16 v[98:113], v[194:197], v[206:209], v[98:113]
	v_mfma_f32_32x32x16_bf16 v[82:97], v[194:197], v[210:213], v[82:97]
	v_mfma_f32_32x32x16_bf16 v[66:81], v[194:197], v[226:229], v[66:81]
	v_mfma_f32_32x32x16_bf16 v[50:65], v[198:201], v[202:205], v[50:65]
	v_mfma_f32_32x32x16_bf16 v[34:49], v[198:201], v[206:209], v[34:49]
	v_mfma_f32_32x32x16_bf16 v[18:33], v[198:201], v[210:213], v[18:33]
	v_mfma_f32_32x32x16_bf16 v[2:17], v[198:201], v[226:229], v[2:17]
	v_add3_u32 v194, s100, v136, v141
	v_add3_u32 v198, s100, v144, v142
	ds_read_b128 v[194:197], v194
	v_add3_u32 v202, s100, v145, v139
	ds_read_b128 v[198:201], v198
	v_add3_u32 v206, s100, v152, v140
	ds_read_b128 v[202:205], v202 offset:32768
	v_add3_u32 v210, s100, v155, v137
	ds_read_b128 v[206:209], v206 offset:32768
	v_add3_u32 v226, s100, v158, v138
	ds_read_b128 v[210:213], v210 offset:32768
	ds_read_b128 v[226:229], v226 offset:32768
	s_waitcnt lgkmcnt(6)
	v_mfma_f32_32x32x16_bf16 v[114:129], v[170:173], v[178:181], v[114:129]
	v_mfma_f32_32x32x16_bf16 v[98:113], v[170:173], v[182:185], v[98:113]
	v_mfma_f32_32x32x16_bf16 v[82:97], v[170:173], v[186:189], v[82:97]
	v_mfma_f32_32x32x16_bf16 v[66:81], v[170:173], v[190:193], v[66:81]
	v_mfma_f32_32x32x16_bf16 v[50:65], v[174:177], v[178:181], v[50:65]
	v_mfma_f32_32x32x16_bf16 v[34:49], v[174:177], v[182:185], v[34:49]
	v_mfma_f32_32x32x16_bf16 v[18:33], v[174:177], v[186:189], v[18:33]
	v_mfma_f32_32x32x16_bf16 v[2:17], v[174:177], v[190:193], v[2:17]
	s_add_u32 s6, s6, 0x80
	s_addc_u32 s7, s7, 0
	s_add_i32 s3, s3, 0x10000
	s_waitcnt vmcnt(0) lgkmcnt(0)
	s_barrier
	v_add3_u32 v170, s30, v136, v143
	v_add3_u32 v174, s30, v144, v146
	ds_read_b128 v[170:173], v170
	v_add3_u32 v178, s30, v145, v151
	ds_read_b128 v[174:177], v174
	v_add3_u32 v182, s30, v152, v156
	ds_read_b128 v[178:181], v178 offset:32768
	v_add3_u32 v186, s30, v155, v157
	ds_read_b128 v[182:185], v182 offset:32768
	v_add3_u32 v190, s30, v158, v168
	ds_read_b128 v[186:189], v186 offset:32768
	ds_read_b128 v[190:193], v190 offset:32768
	s_cmpk_lg_i32 s6, 0x780
	s_cbranch_scc0 .Lk173_exit
	s_add_i32 s31, s100, s2
	v_lshl_add_u64 v[214:215], v[132:133], 0, s[6:7]
	v_lshl_add_u64 v[230:231], v[130:131], 0, s[6:7]
	s_add_i32 m0, s31, 0x8000
	v_lshl_add_u64 v[232:233], v[230:231], 0, s[28:29]
	v_mfma_f32_32x32x16_bf16 v[114:129], v[194:197], v[202:205], v[114:129]
	global_load_lds_dwordx4 v[232:233], off
	s_add_i32 m0, s31, 0xa000
	v_lshl_add_u64 v[232:233], v[230:231], 0, s[24:25]
	v_mfma_f32_32x32x16_bf16 v[98:113], v[194:197], v[206:209], v[98:113]
	v_mfma_f32_32x32x16_bf16 v[82:97], v[194:197], v[210:213], v[82:97]
	global_load_lds_dwordx4 v[232:233], off
	s_add_i32 m0, s31, 0xc000
	v_lshl_add_u64 v[232:233], v[230:231], 0, s[26:27]
	v_mfma_f32_32x32x16_bf16 v[66:81], v[194:197], v[226:229], v[66:81]
	v_mfma_f32_32x32x16_bf16 v[50:65], v[198:201], v[202:205], v[50:65]
	global_load_lds_dwordx4 v[232:233], off
	s_add_i32 m0, s31, 0xe000
	v_lshl_add_u64 v[232:233], v[230:231], 0, s[38:39]
	v_mfma_f32_32x32x16_bf16 v[34:49], v[198:201], v[206:209], v[34:49]
	v_mfma_f32_32x32x16_bf16 v[18:33], v[198:201], v[210:213], v[18:33]
	global_load_lds_dwordx4 v[232:233], off
	v_mfma_f32_32x32x16_bf16 v[2:17], v[198:201], v[226:229], v[2:17]
	s_branch .LBB0_173

; DI f32x16 zero16() { f32x16 z; for (int i = 0; i < 16; ++i) z[i] = 0.f; return z; }
; template <int BK> DI int swz(int row) { constexpr int CPR = BK / 8; return (row / (16 / CPR)) % CPR; }
; DI void wait_vm0() { asm volatile("s_waitcnt vmcnt(0)" ::: "memory"); }
;   DI void pre(int grow0, int gcol0, int lane, int w, char* lds) { xpass(0, grow0, gcol0, lane, w, lds); }
;     ...
;   f32x16 acc[2][NTW];
; #pragma unroll
;   for (int a = 0; a < 2; ++a)
; #pragma unroll
;     for (int b = 0; b < NTW; ++b) acc[a][b] = zero16();
;   const bf16_t* Ag = A + (size_t)row0 * lda; const bf16_t* Bg = Bt + (size_t)col0 * ldb;
;   const int wv = __builtin_amdgcn_readfirstlane(tid >> 6);
;   __syncthreads();
;   if (!pre) { stage_tile<BM, BK>(Ag, lda, lds, tid); stage_tile<BN, BK>(Bg, ldb, lds + ABYTES, tid); }
;   wait_vm0();
;   __syncthreads();
;   const int nk = K / BK;
;   for (int kt = 0; kt < nk; ++kt) {
;     char* cur = lds + (kt & 1) * STG; char* nxt = lds + ((kt + 1) & 1) * STG;
;     const bool more = kt + 1 < nk;
;     const bf16_t* An = Ag + (kt + 1) * BK; const bf16_t* Bn = Bg + (kt + 1) * BK;
;     if (!more) epi.pre(row0 + wm * 64, col0 + wn * (32 * NTW), lane, w, lds);
;     bf16x8 fa[2][2], fb[2][NTW];
; #pragma unroll
;     for (int mt = 0; mt < 2; ++mt) { int row = wm * 64 + mt * 32 + l31; fa[0][mt] = *(const bf16x8*)(cur + row * (BK * 2) + ((hh ^ swz<BK>(row)) << 4)); }
; #pragma unroll
;     for (int nt = 0; nt < NTW; ++nt) { int row = wn * (32 * NTW) + nt * 32 + l31; fb[0][nt] = *(const bf16x8*)(cur + ABYTES + row * (BK * 2) + ((hh ^ swz<BK>(row)) << 4)); }
.LBB0_283:
	v_lshrrev_b32_e32 v4, 30, v3
	v_add_u32_e32 v4, v3, v4
	v_ashrrev_i32_e32 v4, 2, v4
	v_mul_i32_i24_e32 v5, 4, v4
	v_sub_u32_e32 v3, v3, v5
	v_and_b32_e32 v5, 31, v2
	v_lshlrev_b32_e32 v7, 6, v3
	v_or_b32_e32 v7, v7, v5
	v_bfe_u32 v3, v3, 25, 1
	s_waitcnt vmcnt(0)
	v_lshlrev_b32_e32 v140, 7, v7
	v_add_u32_e32 v8, v7, v3
	v_or_b32_e32 v7, 32, v7
	v_add_u32_e32 v3, v7, v3
	v_lshlrev_b32_e32 v142, 7, v7
	v_ashrrev_i32_e32 v7, 1, v3
	v_ashrrev_i32_e32 v3, 31, v3
	v_ashrrev_i32_e32 v9, 1, v8
	v_ashrrev_i32_e32 v8, 31, v8
	v_lshrrev_b32_e32 v3, 29, v3
	v_lshrrev_b32_e32 v8, 29, v8
	v_add_u32_e32 v3, v7, v3
	v_add_u32_e32 v8, v9, v8
	v_and_b32_e32 v3, -8, v3
	v_lshrrev_b32_e32 v6, 5, v2
	v_and_b32_e32 v8, -8, v8
	v_sub_u32_e32 v3, v7, v3
	v_lshl_or_b32 v5, v4, 7, v5
	v_sub_u32_e32 v8, v9, v8
	v_bitop3_b32 v7, v3, v6, 1 bitop3:0x78
	v_lshrrev_b32_e32 v4, 31, v4
	v_bitop3_b32 v9, v8, v6, 1 bitop3:0x78
	v_lshlrev_b32_e32 v144, 4, v7
	v_add_u32_e32 v7, v5, v4
	v_lshlrev_b32_e32 v141, 4, v9
	v_ashrrev_i32_e32 v9, 1, v7
	v_ashrrev_i32_e32 v7, 31, v7
	v_lshrrev_b32_e32 v7, 29, v7
	v_add_u32_e32 v7, v9, v7
	v_and_b32_e32 v7, -8, v7
	v_sub_u32_e32 v7, v9, v7
	v_bitop3_b32 v9, v7, v6, 1 bitop3:0x78
	v_lshlrev_b32_e32 v151, 4, v9
	v_or_b32_e32 v9, 32, v5
	v_lshlrev_b32_e32 v152, 7, v9
	v_add_u32_e32 v9, v9, v4
	v_ashrrev_i32_e32 v10, 1, v9
	v_ashrrev_i32_e32 v9, 31, v9
	v_lshrrev_b32_e32 v9, 29, v9
	v_add_u32_e32 v9, v10, v9
	v_and_b32_e32 v9, -8, v9
	v_sub_u32_e32 v9, v10, v9
	v_bitop3_b32 v10, v9, v6, 1 bitop3:0x78
	v_lshlrev_b32_e32 v143, 7, v5
	v_lshlrev_b32_e32 v154, 4, v10
	v_or_b32_e32 v10, 64, v5
	v_or_b32_e32 v5, 0x60, v5
	v_lshlrev_b32_e32 v153, 7, v10
	v_add_u32_e32 v10, v10, v4
	v_add_u32_e32 v4, v5, v4
	v_lshlrev_b32_e32 v156, 7, v5
	v_ashrrev_i32_e32 v5, 1, v4
	v_ashrrev_i32_e32 v4, 31, v4
	v_lshrrev_b32_e32 v4, 29, v4
	v_add_u32_e32 v4, v5, v4
	v_and_b32_e32 v4, -8, v4
	v_sub_u32_e32 v4, v5, v4
	v_bfe_u32 v2, v2, 5, 1
	v_ashrrev_i32_e32 v11, 1, v10
	v_ashrrev_i32_e32 v10, 31, v10
	v_bitop3_b32 v5, v4, v6, 1 bitop3:0x78
	v_lshrrev_b32_e32 v10, 29, v10
	v_lshlrev_b32_e32 v164, 4, v5
	v_bitop3_b32 v5, v8, v2, 2 bitop3:0x1e
	v_add_u32_e32 v10, v11, v10
	v_lshlrev_b32_e32 v161, 4, v5
	v_bitop3_b32 v5, v3, v2, 2 bitop3:0x1e
	v_and_b32_e32 v10, -8, v10
	v_lshlrev_b32_e32 v163, 4, v5
	v_bitop3_b32 v5, v7, v2, 2 bitop3:0x1e
	v_sub_u32_e32 v10, v11, v10
	v_lshlrev_b32_e32 v159, 4, v5
	v_bitop3_b32 v5, v9, v2, 2 bitop3:0x1e
	s_lshr_b32 s7, s44, 3
	v_lshlrev_b32_e32 v160, 4, v5
	v_bitop3_b32 v5, v10, v2, 2 bitop3:0x1e
	s_and_b32 s7, s7, 7
	s_lshl_b32 s30, s37, 19
	v_lshlrev_b32_e32 v157, 4, v5
	v_bitop3_b32 v5, v4, v2, 2 bitop3:0x1e
	s_lshl_b32 s7, s7, 19
	s_and_b32 s30, s30, 0x1c00000
	v_lshlrev_b32_e32 v158, 4, v5
	v_bitop3_b32 v5, v8, v2, 4 bitop3:0x1e
	s_or_b32 s7, s30, s7
	s_and_b32 s30, s36, 0xffffff00
	v_lshlrev_b32_e32 v149, 4, v5
	v_bitop3_b32 v5, v3, v2, 4 bitop3:0x1e
	s_ashr_i32 s31, s30, 31
	v_lshlrev_b32_e32 v150, 4, v5
	v_bitop3_b32 v5, v7, v2, 4 bitop3:0x1e
	s_lshl_b64 s[30:31], s[30:31], 11
	s_lshl_b32 s3, s3, 10
	v_lshlrev_b32_e32 v147, 4, v5
	v_bitop3_b32 v5, v9, v2, 4 bitop3:0x1e
	v_bitop3_b32 v3, v3, v2, 6 bitop3:0x1e
	v_lshlrev_b32_e32 v148, 4, v5
	v_bitop3_b32 v5, v10, v2, 4 bitop3:0x1e
	v_lshlrev_b32_e32 v139, 4, v3
	v_bitop3_b32 v3, v7, v2, 6 bitop3:0x1e
	s_add_u32 s34, s12, s7
	v_lshlrev_b32_e32 v145, 4, v5
	v_bitop3_b32 v5, v4, v2, 4 bitop3:0x1e
	v_lshlrev_b32_e32 v136, 4, v3
	v_bitop3_b32 v3, v9, v2, 6 bitop3:0x1e
	s_addc_u32 s35, s13, 0
	s_waitcnt vmcnt(0)
	v_lshlrev_b32_e32 v146, 4, v5
	v_bitop3_b32 v5, v8, v2, 6 bitop3:0x1e
	v_lshlrev_b32_e32 v137, 4, v3
	v_bitop3_b32 v3, v10, v2, 6 bitop3:0x1e
	v_bitop3_b32 v2, v4, v2, 6 bitop3:0x1e
	s_add_u32 s30, s40, s30
	v_bitop3_b32 v11, v10, v6, 1 bitop3:0x78
	v_lshlrev_b32_e32 v135, 4, v2
	s_addc_u32 s31, s41, s31
	v_mov_b32_e32 v2, 0
	v_lshlrev_b32_e32 v155, 4, v11
	v_lshlrev_b32_e32 v138, 4, v5
	v_lshlrev_b32_e32 v134, 4, v3
	v_lshl_add_u64 v[130:131], s[34:35], 0, v[0:1]
	v_lshl_add_u64 v[132:133], s[30:31], 0, v[0:1]
	s_mov_b64 s[30:31], 0
	s_mov_b32 s7, 0x10000
	v_mov_b32_e32 v3, v2
	v_mov_b32_e32 v4, v2
	v_mov_b32_e32 v5, v2
	v_mov_b32_e32 v6, v2
	v_mov_b32_e32 v7, v2
	v_mov_b32_e32 v8, v2
	v_mov_b32_e32 v9, v2
	v_mov_b32_e32 v10, v2
	v_mov_b32_e32 v11, v2
	v_mov_b32_e32 v12, v2
	v_mov_b32_e32 v13, v2
	v_mov_b32_e32 v14, v2
	v_mov_b32_e32 v15, v2
	v_mov_b32_e32 v16, v2
	v_mov_b32_e32 v17, v2
	v_mov_b32_e32 v18, v2
	v_mov_b32_e32 v19, v2
	v_mov_b32_e32 v20, v2
	v_mov_b32_e32 v21, v2
	v_mov_b32_e32 v22, v2
	v_mov_b32_e32 v23, v2
	v_mov_b32_e32 v24, v2
	v_mov_b32_e32 v25, v2
	v_mov_b32_e32 v26, v2
	v_mov_b32_e32 v27, v2
	v_mov_b32_e32 v28, v2
	v_mov_b32_e32 v29, v2
	v_mov_b32_e32 v30, v2
	v_mov_b32_e32 v31, v2
	v_mov_b32_e32 v32, v2
	v_mov_b32_e32 v33, v2
	v_mov_b32_e32 v34, v2
	v_mov_b32_e32 v35, v2
	v_mov_b32_e32 v36, v2
	v_mov_b32_e32 v37, v2
	v_mov_b32_e32 v38, v2
	v_mov_b32_e32 v39, v2
	v_mov_b32_e32 v40, v2
	v_mov_b32_e32 v41, v2
	v_mov_b32_e32 v42, v2
	v_mov_b32_e32 v43, v2
	v_mov_b32_e32 v44, v2
	v_mov_b32_e32 v45, v2
	v_mov_b32_e32 v46, v2
	v_mov_b32_e32 v47, v2
	v_mov_b32_e32 v48, v2
	v_mov_b32_e32 v49, v2
	v_mov_b32_e32 v50, v2
	v_mov_b32_e32 v51, v2
	v_mov_b32_e32 v52, v2
	v_mov_b32_e32 v53, v2
	v_mov_b32_e32 v54, v2
	v_mov_b32_e32 v55, v2
	v_mov_b32_e32 v56, v2
	v_mov_b32_e32 v57, v2
	v_mov_b32_e32 v58, v2
	v_mov_b32_e32 v59, v2
	v_mov_b32_e32 v60, v2
	v_mov_b32_e32 v61, v2
	v_mov_b32_e32 v62, v2
	v_mov_b32_e32 v63, v2
	v_mov_b32_e32 v64, v2
	v_mov_b32_e32 v65, v2
	v_mov_b32_e32 v66, v2
	v_mov_b32_e32 v67, v2
	v_mov_b32_e32 v68, v2
	v_mov_b32_e32 v69, v2
; DI f32x16 zero16() { f32x16 z; for (int i = 0; i < 16; ++i) z[i] = 0.f; return z; }
; template <int BK> DI int swz(int row) { constexpr int CPR = BK / 8; return (row / (16 / CPR)) % CPR; }
; DI void wait_vm0() { asm volatile("s_waitcnt vmcnt(0)" ::: "memory"); }
;     ...
;   f32x16 acc[2][NTW];
; #pragma unroll
;   for (int a = 0; a < 2; ++a)
; #pragma unroll
;     for (int b = 0; b < NTW; ++b) acc[a][b] = zero16();
;   const bf16_t* Ag = A + (size_t)row0 * lda; const bf16_t* Bg = Bt + (size_t)col0 * ldb;
;   const int wv = __builtin_amdgcn_readfirstlane(tid >> 6);
;   __syncthreads();
;   if (!pre) { stage_tile<BM, BK>(Ag, lda, lds, tid); stage_tile<BN, BK>(Bg, ldb, lds + ABYTES, tid); }
;   wait_vm0();
;   __syncthreads();
;   const int nk = K / BK;
;   for (int kt = 0; kt < nk; ++kt) {
;     char* cur = lds + (kt & 1) * STG; char* nxt = lds + ((kt + 1) & 1) * STG;
;     const bool more = kt + 1 < nk;
;     const bf16_t* An = Ag + (kt + 1) * BK; const bf16_t* Bn = Bg + (kt + 1) * BK;
;     if (!more) epi.pre(row0 + wm * 64, col0 + wn * (32 * NTW), lane, w, lds);
;     bf16x8 fa[2][2], fb[2][NTW];
; #pragma unroll
;     for (int mt = 0; mt < 2; ++mt) { int row = wm * 64 + mt * 32 + l31; fa[0][mt] = *(const bf16x8*)(cur + row * (BK * 2) + ((hh ^ swz<BK>(row)) << 4)); }
; #pragma unroll
;     for (int nt = 0; nt < NTW; ++nt) { int row = wn * (32 * NTW) + nt * 32 + l31; fb[0][nt] = *(const bf16x8*)(cur + ABYTES + row * (BK * 2) + ((hh ^ swz<BK>(row)) << 4)); }
; #pragma unroll
;     for (int kk = 0; kk < NKK; ++kk) {
;       if (kk + 1 < NKK) {
;         const int ch = (kk + 1) * 2 + hh;
; #pragma unroll
;         for (int mt = 0; mt < 2; ++mt) { int row = wm * 64 + mt * 32 + l31; fa[(kk + 1) & 1][mt] = *(const bf16x8*)(cur + row * (BK * 2) + ((ch ^ swz<BK>(row)) << 4)); }
; #pragma unroll
;         for (int nt = 0; nt < NTW; ++nt) { int row = wn * (32 * NTW) + nt * 32 + l31; fb[(kk + 1) & 1][nt] = *(const bf16x8*)(cur + ABYTES + row * (BK * 2) + ((ch ^ swz<BK>(row)) << 4)); }
;       }
;       if (more) {
; #pragma unroll
;         for (int q = 0; q < PPK; ++q) {
;           const int pi = kk * PPK + q;
;           if (pi < NPA) stage_piece<BM, BK>(An, lda, nxt, tid, pi, wv);
;           else if (pi < NP) stage_piece<BN, BK>(Bn, ldb, nxt + ABYTES, tid, pi - NPA, wv);
;         }
;       }
	v_mov_b32_e32 v70, v2
	v_mov_b32_e32 v71, v2
	v_mov_b32_e32 v72, v2
	v_mov_b32_e32 v73, v2
	v_mov_b32_e32 v74, v2
	v_mov_b32_e32 v75, v2
	v_mov_b32_e32 v76, v2
	v_mov_b32_e32 v77, v2
	v_mov_b32_e32 v78, v2
	v_mov_b32_e32 v79, v2
	v_mov_b32_e32 v80, v2
	v_mov_b32_e32 v81, v2
	v_mov_b32_e32 v82, v2
	v_mov_b32_e32 v83, v2
	v_mov_b32_e32 v84, v2
	v_mov_b32_e32 v85, v2
	v_mov_b32_e32 v86, v2
	v_mov_b32_e32 v87, v2
	v_mov_b32_e32 v88, v2
	v_mov_b32_e32 v89, v2
	v_mov_b32_e32 v90, v2
	v_mov_b32_e32 v91, v2
	v_mov_b32_e32 v92, v2
	v_mov_b32_e32 v93, v2
	v_mov_b32_e32 v94, v2
	v_mov_b32_e32 v95, v2
	v_mov_b32_e32 v96, v2
	v_mov_b32_e32 v97, v2
	v_mov_b32_e32 v98, v2
	v_mov_b32_e32 v99, v2
	v_mov_b32_e32 v100, v2
	v_mov_b32_e32 v101, v2
	v_mov_b32_e32 v102, v2
	v_mov_b32_e32 v103, v2
	v_mov_b32_e32 v104, v2
	v_mov_b32_e32 v105, v2
	v_mov_b32_e32 v106, v2
	v_mov_b32_e32 v107, v2
	v_mov_b32_e32 v108, v2
	v_mov_b32_e32 v109, v2
	v_mov_b32_e32 v110, v2
	v_mov_b32_e32 v111, v2
	v_mov_b32_e32 v112, v2
	v_mov_b32_e32 v113, v2
	v_mov_b32_e32 v114, v2
	v_mov_b32_e32 v115, v2
	v_mov_b32_e32 v116, v2
	v_mov_b32_e32 v117, v2
	v_mov_b32_e32 v118, v2
	v_mov_b32_e32 v119, v2
	v_mov_b32_e32 v120, v2
	v_mov_b32_e32 v121, v2
	v_mov_b32_e32 v122, v2
	v_mov_b32_e32 v123, v2
	v_mov_b32_e32 v124, v2
	v_mov_b32_e32 v125, v2
	v_mov_b32_e32 v126, v2
	v_mov_b32_e32 v127, v2
	v_mov_b32_e32 v128, v2
	v_mov_b32_e32 v129, v2
	s_waitcnt vmcnt(0) lgkmcnt(0)
	s_barrier
	v_add_u32_e32 v166, v140, v141
	v_add_u32_e32 v170, v142, v144
	ds_read_b128 v[166:169], v166
	v_add_u32_e32 v174, v143, v151
	ds_read_b128 v[170:173], v170
	v_add_u32_e32 v178, v152, v154
	ds_read_b128 v[174:177], v174 offset:32768
	v_add_u32_e32 v182, v153, v155
	ds_read_b128 v[178:181], v178 offset:32768
	v_add_u32_e32 v186, v156, v164
	ds_read_b128 v[182:185], v182 offset:32768
	ds_read_b128 v[186:189], v186 offset:32768
	s_and_b32 s35, s7, 0x10000
	s_add_i32 s34, s35, s3
	v_lshl_add_u64 v[214:215], v[130:131], 0, s[30:31]
	v_lshl_add_u64 v[226:227], v[132:133], 0, s[30:31]
	s_add_i32 m0, s34, 0x8000
	v_lshl_add_u64 v[228:229], v[226:227], 0, s[28:29]
	global_load_lds_dwordx4 v[228:229], off
	s_add_i32 m0, s34, 0xa000
	v_lshl_add_u64 v[228:229], v[226:227], 0, s[24:25]
	global_load_lds_dwordx4 v[228:229], off
	s_add_i32 m0, s34, 0xc000
	v_lshl_add_u64 v[228:229], v[226:227], 0, s[26:27]
	global_load_lds_dwordx4 v[228:229], off
	s_add_i32 m0, s34, 0xe000
	v_lshl_add_u64 v[228:229], v[226:227], 0, s[38:39]
	global_load_lds_dwordx4 v[228:229], off
; DI f32x16 mfma(bf16x8 a, bf16x8 b, f32x16 c) { return __builtin_amdgcn_mfma_f32_32x32x16_bf16(a, b, c, 0, 0, 0); }
; template <int BK> DI int swz(int row) { constexpr int CPR = BK / 8; return (row / (16 / CPR)) % CPR; }
; DI void wait_vm0() { asm volatile("s_waitcnt vmcnt(0)" ::: "memory"); }
;   DI void pre(int grow0, int gcol0, int lane, int w, char* lds) { xpass(0, grow0, gcol0, lane, w, lds); }
;     ...
;   for (int kt = 0; kt < nk; ++kt) {
;     char* cur = lds + (kt & 1) * STG; char* nxt = lds + ((kt + 1) & 1) * STG;
;     const bool more = kt + 1 < nk;
;     const bf16_t* An = Ag + (kt + 1) * BK; const bf16_t* Bn = Bg + (kt + 1) * BK;
;     if (!more) epi.pre(row0 + wm * 64, col0 + wn * (32 * NTW), lane, w, lds);
;     bf16x8 fa[2][2], fb[2][NTW];
; #pragma unroll
;     for (int mt = 0; mt < 2; ++mt) { int row = wm * 64 + mt * 32 + l31; fa[0][mt] = *(const bf16x8*)(cur + row * (BK * 2) + ((hh ^ swz<BK>(row)) << 4)); }
; #pragma unroll
;     for (int nt = 0; nt < NTW; ++nt) { int row = wn * (32 * NTW) + nt * 32 + l31; fb[0][nt] = *(const bf16x8*)(cur + ABYTES + row * (BK * 2) + ((hh ^ swz<BK>(row)) << 4)); }
; #pragma unroll
;     for (int kk = 0; kk < NKK; ++kk) {
;       if (kk + 1 < NKK) {
;         const int ch = (kk + 1) * 2 + hh;
; #pragma unroll
;         for (int mt = 0; mt < 2; ++mt) { int row = wm * 64 + mt * 32 + l31; fa[(kk + 1) & 1][mt] = *(const bf16x8*)(cur + row * (BK * 2) + ((ch ^ swz<BK>(row)) << 4)); }
; #pragma unroll
;         for (int nt = 0; nt < NTW; ++nt) { int row = wn * (32 * NTW) + nt * 32 + l31; fb[(kk + 1) & 1][nt] = *(const bf16x8*)(cur + ABYTES + row * (BK * 2) + ((ch ^ swz<BK>(row)) << 4)); }
;       }
;       if (more) {
; #pragma unroll
;         for (int q = 0; q < PPK; ++q) {
;           const int pi = kk * PPK + q;
;           if (pi < NPA) stage_piece<BM, BK>(An, lda, nxt, tid, pi, wv);
;           else if (pi < NP) stage_piece<BN, BK>(Bn, ldb, nxt + ABYTES, tid, pi - NPA, wv);
;         }
;       }
;       __builtin_amdgcn_s_setprio(1);
; #pragma unroll
;       for (int mt = 0; mt < 2; ++mt)
; #pragma unroll
;         for (int nt = 0; nt < NTW; ++nt) acc[mt][nt] = mfma(fa[kk & 1][mt], fb[kk & 1][nt], acc[mt][nt]);
;       __builtin_amdgcn_s_setprio(0);
;       __builtin_amdgcn_sched_barrier(0);
;     }
;     wait_vm0();
;     __syncthreads();
.LBB0_284:
	s_and_b32 s35, s7, 0x10000
	s_xor_b32 s100, s35, 0x10000
	v_add3_u32 v190, s100, v140, v161
	v_add3_u32 v194, s100, v142, v163
	ds_read_b128 v[190:193], v190
	v_add3_u32 v198, s100, v143, v159
	ds_read_b128 v[194:197], v194
	v_add3_u32 v202, s100, v152, v160
	ds_read_b128 v[198:201], v198 offset:32768
	v_add3_u32 v206, s100, v153, v157
	ds_read_b128 v[202:205], v202 offset:32768
	v_add3_u32 v210, s100, v156, v158
	ds_read_b128 v[206:209], v206 offset:32768
	ds_read_b128 v[210:213], v210 offset:32768
	s_waitcnt lgkmcnt(6)
	s_mov_b32 m0, s34
	v_lshl_add_u64 v[228:229], v[214:215], 0, s[28:29]
	v_mfma_f32_32x32x16_bf16 v[114:129], v[166:169], v[174:177], v[114:129]
	global_load_lds_dwordx4 v[228:229], off
	s_add_i32 m0, s34, 0x2000
	v_lshl_add_u64 v[228:229], v[214:215], 0, s[24:25]
	v_mfma_f32_32x32x16_bf16 v[98:113], v[166:169], v[178:181], v[98:113]
	v_mfma_f32_32x32x16_bf16 v[82:97], v[166:169], v[182:185], v[82:97]
	global_load_lds_dwordx4 v[228:229], off
	s_add_i32 m0, s34, 0x4000
	v_lshl_add_u64 v[228:229], v[214:215], 0, s[26:27]
	v_mfma_f32_32x32x16_bf16 v[66:81], v[166:169], v[186:189], v[66:81]
	v_mfma_f32_32x32x16_bf16 v[50:65], v[170:173], v[174:177], v[50:65]
	global_load_lds_dwordx4 v[228:229], off
	s_add_i32 m0, s34, 0x6000
	v_lshl_add_u64 v[228:229], v[214:215], 0, s[38:39]
	v_mfma_f32_32x32x16_bf16 v[34:49], v[170:173], v[178:181], v[34:49]
	v_mfma_f32_32x32x16_bf16 v[18:33], v[170:173], v[182:185], v[18:33]
	global_load_lds_dwordx4 v[228:229], off
	v_mfma_f32_32x32x16_bf16 v[2:17], v[170:173], v[186:189], v[2:17]
	v_add3_u32 v166, s100, v140, v149
	v_add3_u32 v170, s100, v142, v150
	ds_read_b128 v[166:169], v166
	v_add3_u32 v174, s100, v143, v147
	ds_read_b128 v[170:173], v170
	v_add3_u32 v178, s100, v152, v148
	ds_read_b128 v[174:177], v174 offset:32768
	v_add3_u32 v182, s100, v153, v145
	ds_read_b128 v[178:181], v178 offset:32768
	v_add3_u32 v186, s100, v156, v146
	ds_read_b128 v[182:185], v182 offset:32768
	ds_read_b128 v[186:189], v186 offset:32768
	s_waitcnt lgkmcnt(6)
	v_mfma_f32_32x32x16_bf16 v[114:129], v[190:193], v[198:201], v[114:129]
	v_mfma_f32_32x32x16_bf16 v[98:113], v[190:193], v[202:205], v[98:113]
	v_mfma_f32_32x32x16_bf16 v[82:97], v[190:193], v[206:209], v[82:97]
	v_mfma_f32_32x32x16_bf16 v[66:81], v[190:193], v[210:213], v[66:81]
	v_mfma_f32_32x32x16_bf16 v[50:65], v[194:197], v[198:201], v[50:65]
	v_mfma_f32_32x32x16_bf16 v[34:49], v[194:197], v[202:205], v[34:49]
	v_mfma_f32_32x32x16_bf16 v[18:33], v[194:197], v[206:209], v[18:33]
	v_mfma_f32_32x32x16_bf16 v[2:17], v[194:197], v[210:213], v[2:17]
	v_add3_u32 v190, s100, v140, v138
	v_add3_u32 v194, s100, v142, v139
	ds_read_b128 v[190:193], v190
	v_add3_u32 v198, s100, v143, v136
	ds_read_b128 v[194:197], v194
	v_add3_u32 v202, s100, v152, v137
	ds_read_b128 v[198:201], v198 offset:32768
	v_add3_u32 v206, s100, v153, v134
	ds_read_b128 v[202:205], v202 offset:32768
	v_add3_u32 v210, s100, v156, v135
	ds_read_b128 v[206:209], v206 offset:32768
	ds_read_b128 v[210:213], v210 offset:32768
	s_waitcnt lgkmcnt(6)
	v_mfma_f32_32x32x16_bf16 v[114:129], v[166:169], v[174:177], v[114:129]
	v_mfma_f32_32x32x16_bf16 v[98:113], v[166:169], v[178:181], v[98:113]
	v_mfma_f32_32x32x16_bf16 v[82:97], v[166:169], v[182:185], v[82:97]
	v_mfma_f32_32x32x16_bf16 v[66:81], v[166:169], v[186:189], v[66:81]
	v_mfma_f32_32x32x16_bf16 v[50:65], v[170:173], v[174:177], v[50:65]
	v_mfma_f32_32x32x16_bf16 v[34:49], v[170:173], v[178:181], v[34:49]
	v_mfma_f32_32x32x16_bf16 v[18:33], v[170:173], v[182:185], v[18:33]
	v_mfma_f32_32x32x16_bf16 v[2:17], v[170:173], v[186:189], v[2:17]
	s_add_u32 s30, s30, 0x80
	s_addc_u32 s31, s31, 0
	s_add_i32 s7, s7, 0x10000
	s_waitcnt vmcnt(0) lgkmcnt(0)
	s_barrier
	v_add3_u32 v166, s35, v140, v141
	v_add3_u32 v170, s35, v142, v144
	ds_read_b128 v[166:169], v166
	v_add3_u32 v174, s35, v143, v151
	ds_read_b128 v[170:173], v170
	v_add3_u32 v178, s35, v152, v154
	ds_read_b128 v[174:177], v174 offset:32768
	v_add3_u32 v182, s35, v153, v155
	ds_read_b128 v[178:181], v178 offset:32768
	v_add3_u32 v186, s35, v156, v164
	ds_read_b128 v[182:185], v182 offset:32768
	ds_read_b128 v[186:189], v186 offset:32768
	s_cmpk_eq_i32 s30, 0x780
	s_cbranch_scc1 .Lk284_exit
	s_add_i32 s34, s100, s3
	v_lshl_add_u64 v[214:215], v[130:131], 0, s[30:31]
	v_lshl_add_u64 v[226:227], v[132:133], 0, s[30:31]
	s_add_i32 m0, s34, 0x8000
	v_lshl_add_u64 v[228:229], v[226:227], 0, s[28:29]
	v_mfma_f32_32x32x16_bf16 v[114:129], v[190:193], v[198:201], v[114:129]
	global_load_lds_dwordx4 v[228:229], off
	s_add_i32 m0, s34, 0xa000
	v_lshl_add_u64 v[228:229], v[226:227], 0, s[24:25]
	v_mfma_f32_32x32x16_bf16 v[98:113], v[190:193], v[202:205], v[98:113]
	v_mfma_f32_32x32x16_bf16 v[82:97], v[190:193], v[206:209], v[82:97]
	global_load_lds_dwordx4 v[228:229], off
	s_add_i32 m0, s34, 0xc000
	v_lshl_add_u64 v[228:229], v[226:227], 0, s[26:27]
	v_mfma_f32_32x32x16_bf16 v[66:81], v[190:193], v[210:213], v[66:81]
	v_mfma_f32_32x32x16_bf16 v[50:65], v[194:197], v[198:201], v[50:65]
	global_load_lds_dwordx4 v[228:229], off
	s_add_i32 m0, s34, 0xe000
	v_lshl_add_u64 v[228:229], v[226:227], 0, s[38:39]
	v_mfma_f32_32x32x16_bf16 v[34:49], v[194:197], v[202:205], v[34:49]
	v_mfma_f32_32x32x16_bf16 v[18:33], v[194:197], v[206:209], v[18:33]
	global_load_lds_dwordx4 v[228:229], off
	v_mfma_f32_32x32x16_bf16 v[2:17], v[194:197], v[210:213], v[2:17]
	s_branch .LBB0_284

; DI void wait_vm0() { asm volatile("s_waitcnt vmcnt(0)" ::: "memory"); }
;   DI void pre(int grow0, int gcol0, int lane, int w, char* lds) { xpass(0, grow0, gcol0, lane, w, lds); }
; template <int BK> DI int swz(int row) { constexpr int CPR = BK / 8; return (row / (16 / CPR)) % CPR; }
; template <int ROWS, int BK>
; DI void stage_tile(const bf16_t* g, int ld, char* l, int tid) {
;   constexpr int CPR = BK / 8, TOT = ROWS * CPR, N = (TOT + NT - 1) / NT;
;   const int row0 = tid / CPR, pc = tid % CPR; const int c = pc ^ swz<BK>(row0);
;   const unsigned voff = (unsigned)(row0 * ld + c * 8) * 2u;
; #pragma unroll
;   for (int i = 0; i < N; ++i) {
;     if (TOT % NT == 0 || tid + i * NT < TOT) {
;       const char* gb = (const char*)g + (size_t)i * (NT / CPR) * ld * 2;
;       __builtin_amdgcn_global_load_lds((const unsigned*)(gb + voff), (__attribute__((address_space(3))) unsigned*)(l + i * NT * 16 + __builtin_amdgcn_readfirstlane(tid >> 6) * 1024), 16, 0, 0);
;     }
;   }
; }
;     ...
;   const bf16_t* Ag = A + (size_t)row0 * lda; const bf16_t* Bg = Bt + (size_t)col0 * ldb;
;   const int wv = __builtin_amdgcn_readfirstlane(tid >> 6);
;   __syncthreads();
;   if (!pre) { stage_tile<BM, BK>(Ag, lda, lds, tid); stage_tile<BN, BK>(Bg, ldb, lds + ABYTES, tid); }
;   wait_vm0();
;   __syncthreads();
;   const int nk = K / BK;
;   for (int kt = 0; kt < nk; ++kt) {
;     char* cur = lds + (kt & 1) * STG; char* nxt = lds + ((kt + 1) & 1) * STG;
;     const bool more = kt + 1 < nk;
;     const bf16_t* An = Ag + (kt + 1) * BK; const bf16_t* Bn = Bg + (kt + 1) * BK;
;     if (!more) epi.pre(row0 + wm * 64, col0 + wn * (32 * NTW), lane, w, lds);
;     bf16x8 fa[2][2], fb[2][NTW];
; #pragma unroll
;     for (int mt = 0; mt < 2; ++mt) { int row = wm * 64 + mt * 32 + l31; fa[0][mt] = *(const bf16x8*)(cur + row * (BK * 2) + ((hh ^ swz<BK>(row)) << 4)); }
; #pragma unroll
;     for (int nt = 0; nt < NTW; ++nt) { int row = wn * (32 * NTW) + nt * 32 + l31; fb[0][nt] = *(const bf16x8*)(cur + ABYTES + row * (BK * 2) + ((hh ^ swz<BK>(row)) << 4)); }
.LBB0_290:
	s_cmp_lg_u32 s71, 0
	s_cbranch_scc0 .LBB0_369
	v_readlane_b32 s2, v255, 39
	v_readlane_b32 s3, v255, 40
	v_mov_b32_e32 v8, v216
	s_load_dwordx2 s[2:3], s[2:3], 0x140
	v_readlane_b32 s30, v253, 27
	v_ashrrev_i32_e32 v2, 31, v8
	v_lshrrev_b32_e32 v3, 29, v2
	v_lshrrev_b32_e32 v2, 28, v2
	v_add_u32_e32 v2, v8, v2
	v_ashrrev_i32_e32 v2, 4, v2
	v_lshrrev_b32_e32 v5, 29, v2
	v_add_u32_e32 v3, v8, v3
	v_add_u32_e32 v5, v2, v5
	v_lshrrev_b32_e32 v4, 3, v3
	v_and_b32_e32 v3, 0xffffff8, v3
	v_and_b32_e32 v5, 0xffffff8, v5
	s_mul_i32 s6, s30, 0x1600
	v_sub_u32_e32 v3, v8, v3
	v_sub_u32_e32 v2, v2, v5
	s_movk_i32 s7, 0x1600
	s_waitcnt lgkmcnt(0)
	s_add_u32 s2, s2, s6
	s_mul_hi_i32 s6, s30, 0x1600
	v_xor_b32_e32 v2, v2, v3
	v_mul_lo_u32 v3, v4, s7
	v_readfirstlane_b32 s7, v8
	v_readlane_b32 s31, v253, 28
	s_addc_u32 s3, s3, s6
	s_lshl_b32 s7, s7, 4
	v_readlane_b32 s30, v253, 37
	s_and_b32 s7, s7, 0xfffffc00
	v_lshl_add_u32 v2, v2, 4, v3
	v_mov_b32_e32 v3, v1
	v_readlane_b32 s31, v253, 38
	s_mov_b32 m0, s7
	s_waitcnt vmcnt(0)
	s_barrier
	v_lshl_add_u64 v[4:5], s[30:31], 0, v[2:3]
	s_nop 0
	global_load_lds_dwordx4 v2, s[30:31]
	s_mov_b64 s[30:31], 0x58000
	v_lshl_add_u64 v[6:7], v[4:5], 0, s[30:31]
	s_add_i32 m0, s7, 0x2000
	s_mov_b64 s[34:35], 0xb0000
	global_load_lds_dwordx4 v[6:7], off
	v_lshl_add_u64 v[6:7], v[4:5], 0, s[34:35]
	s_add_i32 m0, s7, 0x4000
	s_mov_b64 s[36:37], 0x108000
	global_load_lds_dwordx4 v[6:7], off
	v_lshl_add_u64 v[4:5], v[4:5], 0, s[36:37]
	s_add_i32 m0, s7, 0x6000
	v_lshl_add_u64 v[130:131], s[2:3], 0, v[2:3]
	global_load_lds_dwordx4 v[4:5], off
	s_add_i32 m0, s7, 0x8000
	v_lshl_add_u64 v[4:5], v[130:131], 0, s[30:31]
	global_load_lds_dwordx4 v2, s[2:3]
	s_add_i32 m0, s7, 0xa000
	v_ashrrev_i32_e32 v134, 6, v8
	global_load_lds_dwordx4 v[4:5], off
	v_lshl_add_u64 v[4:5], v[130:131], 0, s[34:35]
	s_add_i32 m0, s7, 0xc000
	v_and_b32_e32 v6, 31, v8
	global_load_lds_dwordx4 v[4:5], off
	v_lshl_add_u64 v[4:5], v[130:131], 0, s[36:37]
	s_add_i32 m0, s7, 0xe000
	v_and_b32_e32 v0, 63, v8
	global_load_lds_dwordx4 v[4:5], off
	v_lshrrev_b32_e32 v4, 30, v134
	v_add_u32_e32 v4, v134, v4
	v_ashrrev_i32_e32 v5, 2, v4
	v_mul_i32_i24_e32 v7, 4, v5
	v_sub_u32_e32 v7, v134, v7
	v_lshlrev_b32_e32 v169, 6, v7
	v_lshlrev_b32_e32 v168, 7, v5
	v_or_b32_e32 v5, v169, v6
	v_bfe_u32 v7, v7, 25, 1
	v_bfe_u32 v135, v8, 5, 1
	v_lshlrev_b32_e32 v136, 7, v5
	v_add_u32_e32 v8, v5, v7
	v_or_b32_e32 v5, 32, v5
	v_lshlrev_b32_e32 v144, 7, v5
	v_add_u32_e32 v5, v5, v7
	v_ashrrev_i32_e32 v7, 1, v5
	v_ashrrev_i32_e32 v5, 31, v5
	v_ashrrev_i32_e32 v9, 1, v8
	v_ashrrev_i32_e32 v8, 31, v8
	v_lshrrev_b32_e32 v5, 29, v5
	v_lshrrev_b32_e32 v8, 29, v8
	v_add_u32_e32 v5, v7, v5
	v_add_u32_e32 v8, v9, v8
	v_and_b32_e32 v5, -8, v5
	v_and_b32_e32 v8, -8, v8
	v_sub_u32_e32 v5, v7, v5
	v_or_b32_e32 v6, v168, v6
	v_sub_u32_e32 v8, v9, v8
	v_xor_b32_e32 v7, v5, v135
	v_lshrrev_b32_e32 v4, 31, v4
	v_xor_b32_e32 v9, v8, v135
	v_lshlrev_b32_e32 v146, 4, v7
	v_add_u32_e32 v7, v6, v4
	v_lshlrev_b32_e32 v143, 4, v9
	v_ashrrev_i32_e32 v9, 1, v7
	v_ashrrev_i32_e32 v7, 31, v7
	v_lshrrev_b32_e32 v7, 29, v7
	v_add_u32_e32 v7, v9, v7
	v_and_b32_e32 v7, -8, v7
	v_sub_u32_e32 v7, v9, v7
	v_xor_b32_e32 v9, v7, v135
	v_lshlrev_b32_e32 v151, 4, v9
	v_or_b32_e32 v9, 32, v6
	v_lshlrev_b32_e32 v152, 7, v9
	v_add_u32_e32 v9, v9, v4
	v_ashrrev_i32_e32 v10, 1, v9
	v_ashrrev_i32_e32 v9, 31, v9
	v_lshrrev_b32_e32 v9, 29, v9
	v_add_u32_e32 v9, v10, v9
	v_and_b32_e32 v9, -8, v9
	v_sub_u32_e32 v9, v10, v9
	v_xor_b32_e32 v10, v9, v135
	v_lshlrev_b32_e32 v145, 7, v6
	v_lshlrev_b32_e32 v156, 4, v10
	v_or_b32_e32 v10, 64, v6
	v_or_b32_e32 v6, 0x60, v6
	v_lshlrev_b32_e32 v155, 7, v10
	v_add_u32_e32 v10, v10, v4
	v_add_u32_e32 v4, v6, v4
	v_lshlrev_b32_e32 v158, 7, v6
	v_ashrrev_i32_e32 v6, 1, v4
	v_ashrrev_i32_e32 v4, 31, v4
	v_lshrrev_b32_e32 v4, 29, v4
	v_add_u32_e32 v4, v6, v4
	v_and_b32_e32 v4, -8, v4
	v_sub_u32_e32 v4, v6, v4
	v_ashrrev_i32_e32 v11, 1, v10
	v_ashrrev_i32_e32 v10, 31, v10
	v_xor_b32_e32 v6, v4, v135
	v_lshrrev_b32_e32 v10, 29, v10
	v_lshlrev_b32_e32 v167, 4, v6
	v_bitop3_b32 v6, v8, v135, 2 bitop3:0x1e
	v_add_u32_e32 v10, v11, v10
	v_lshlrev_b32_e32 v164, 4, v6
	v_bitop3_b32 v6, v5, v135, 2 bitop3:0x1e
	v_and_b32_e32 v10, -8, v10
	v_lshlrev_b32_e32 v166, 4, v6
	v_bitop3_b32 v6, v7, v135, 2 bitop3:0x1e
	v_sub_u32_e32 v10, v11, v10
	v_lshlrev_b32_e32 v161, 4, v6
	v_bitop3_b32 v6, v9, v135, 2 bitop3:0x1e
	v_lshlrev_b32_e32 v163, 4, v6
	v_bitop3_b32 v6, v10, v135, 2 bitop3:0x1e
	v_lshlrev_b32_e32 v159, 4, v6
	v_bitop3_b32 v6, v4, v135, 2 bitop3:0x1e
	v_lshlrev_b32_e32 v160, 4, v6
	v_bitop3_b32 v6, v8, v135, 4 bitop3:0x1e
	v_lshlrev_b32_e32 v153, 4, v6
	v_bitop3_b32 v6, v5, v135, 4 bitop3:0x1e
	v_lshlrev_b32_e32 v154, 4, v6
	v_bitop3_b32 v6, v7, v135, 4 bitop3:0x1e
	v_readfirstlane_b32 s6, v134
	v_lshlrev_b32_e32 v149, 4, v6
	v_bitop3_b32 v6, v9, v135, 4 bitop3:0x1e
	v_bitop3_b32 v5, v5, v135, 6 bitop3:0x1e
	s_lshl_b32 s2, s6, 10
	v_lshlrev_b32_e32 v150, 4, v6
	v_bitop3_b32 v6, v10, v135, 4 bitop3:0x1e
	v_lshlrev_b32_e32 v142, 4, v5
	v_bitop3_b32 v5, v7, v135, 6 bitop3:0x1e
	v_readlane_b32 s6, v254, 36
	s_waitcnt vmcnt(0)
; DI f32x16 zero16() { f32x16 z; for (int i = 0; i < 16; ++i) z[i] = 0.f; return z; }
; template <int BK> DI int swz(int row) { constexpr int CPR = BK / 8; return (row / (16 / CPR)) % CPR; }
; DI void wait_vm0() { asm volatile("s_waitcnt vmcnt(0)" ::: "memory"); }
;     ...
;   f32x16 acc[2][NTW];
; #pragma unroll
;   for (int a = 0; a < 2; ++a)
; #pragma unroll
;     for (int b = 0; b < NTW; ++b) acc[a][b] = zero16();
;   const bf16_t* Ag = A + (size_t)row0 * lda; const bf16_t* Bg = Bt + (size_t)col0 * ldb;
;   const int wv = __builtin_amdgcn_readfirstlane(tid >> 6);
;   __syncthreads();
;   if (!pre) { stage_tile<BM, BK>(Ag, lda, lds, tid); stage_tile<BN, BK>(Bg, ldb, lds + ABYTES, tid); }
;   wait_vm0();
;   __syncthreads();
;   const int nk = K / BK;
;   for (int kt = 0; kt < nk; ++kt) {
;     char* cur = lds + (kt & 1) * STG; char* nxt = lds + ((kt + 1) & 1) * STG;
;     const bool more = kt + 1 < nk;
;     const bf16_t* An = Ag + (kt + 1) * BK; const bf16_t* Bn = Bg + (kt + 1) * BK;
;     if (!more) epi.pre(row0 + wm * 64, col0 + wn * (32 * NTW), lane, w, lds);
;     bf16x8 fa[2][2], fb[2][NTW];
; #pragma unroll
;     for (int mt = 0; mt < 2; ++mt) { int row = wm * 64 + mt * 32 + l31; fa[0][mt] = *(const bf16x8*)(cur + row * (BK * 2) + ((hh ^ swz<BK>(row)) << 4)); }
; #pragma unroll
;     for (int nt = 0; nt < NTW; ++nt) { int row = wn * (32 * NTW) + nt * 32 + l31; fb[0][nt] = *(const bf16x8*)(cur + ABYTES + row * (BK * 2) + ((hh ^ swz<BK>(row)) << 4)); }
; #pragma unroll
;     for (int kk = 0; kk < NKK; ++kk) {
;       if (kk + 1 < NKK) {
;         const int ch = (kk + 1) * 2 + hh;
; #pragma unroll
;         for (int mt = 0; mt < 2; ++mt) { int row = wm * 64 + mt * 32 + l31; fa[(kk + 1) & 1][mt] = *(const bf16x8*)(cur + row * (BK * 2) + ((ch ^ swz<BK>(row)) << 4)); }
; #pragma unroll
;         for (int nt = 0; nt < NTW; ++nt) { int row = wn * (32 * NTW) + nt * 32 + l31; fb[(kk + 1) & 1][nt] = *(const bf16x8*)(cur + ABYTES + row * (BK * 2) + ((ch ^ swz<BK>(row)) << 4)); }
;       }
;       if (more) {
; #pragma unroll
;         for (int q = 0; q < PPK; ++q) {
;           const int pi = kk * PPK + q;
;           if (pi < NPA) stage_piece<BM, BK>(An, lda, nxt, tid, pi, wv);
;           else if (pi < NP) stage_piece<BN, BK>(Bn, ldb, nxt + ABYTES, tid, pi - NPA, wv);
;         }
;       }
	v_lshlrev_b32_e32 v147, 4, v6
	v_bitop3_b32 v6, v4, v135, 4 bitop3:0x1e
	v_lshlrev_b32_e32 v139, 4, v5
	v_bitop3_b32 v5, v9, v135, 6 bitop3:0x1e
	v_readlane_b32 s7, v254, 37
	v_xor_b32_e32 v11, v10, v135
	v_lshlrev_b32_e32 v148, 4, v6
	v_bitop3_b32 v6, v8, v135, 6 bitop3:0x1e
	v_lshlrev_b32_e32 v140, 4, v5
	v_bitop3_b32 v5, v10, v135, 6 bitop3:0x1e
	v_bitop3_b32 v4, v4, v135, 6 bitop3:0x1e
	v_lshl_add_u64 v[132:133], s[6:7], 0, v[2:3]
	v_mov_b32_e32 v2, 0
	v_lshlrev_b32_e32 v157, 4, v11
	v_lshlrev_b32_e32 v141, 4, v6
	v_lshlrev_b32_e32 v137, 4, v5
	v_lshlrev_b32_e32 v138, 4, v4
	s_mov_b64 s[6:7], 0
	s_mov_b32 s3, 0x10000
	v_mov_b32_e32 v3, v2
	v_mov_b32_e32 v4, v2
	v_mov_b32_e32 v5, v2
	v_mov_b32_e32 v6, v2
	v_mov_b32_e32 v7, v2
	v_mov_b32_e32 v8, v2
	v_mov_b32_e32 v9, v2
	v_mov_b32_e32 v10, v2
	v_mov_b32_e32 v11, v2
	v_mov_b32_e32 v12, v2
	v_mov_b32_e32 v13, v2
	v_mov_b32_e32 v14, v2
	v_mov_b32_e32 v15, v2
	v_mov_b32_e32 v16, v2
	v_mov_b32_e32 v17, v2
	v_mov_b32_e32 v18, v2
	v_mov_b32_e32 v19, v2
	v_mov_b32_e32 v20, v2
	v_mov_b32_e32 v21, v2
	v_mov_b32_e32 v22, v2
	v_mov_b32_e32 v23, v2
	v_mov_b32_e32 v24, v2
	v_mov_b32_e32 v25, v2
	v_mov_b32_e32 v26, v2
	v_mov_b32_e32 v27, v2
	v_mov_b32_e32 v28, v2
	v_mov_b32_e32 v29, v2
	v_mov_b32_e32 v30, v2
	v_mov_b32_e32 v31, v2
	v_mov_b32_e32 v32, v2
	v_mov_b32_e32 v33, v2
	v_mov_b32_e32 v34, v2
	v_mov_b32_e32 v35, v2
	v_mov_b32_e32 v36, v2
	v_mov_b32_e32 v37, v2
	v_mov_b32_e32 v38, v2
	v_mov_b32_e32 v39, v2
	v_mov_b32_e32 v40, v2
	v_mov_b32_e32 v41, v2
	v_mov_b32_e32 v42, v2
	v_mov_b32_e32 v43, v2
	v_mov_b32_e32 v44, v2
	v_mov_b32_e32 v45, v2
	v_mov_b32_e32 v46, v2
	v_mov_b32_e32 v47, v2
	v_mov_b32_e32 v48, v2
	v_mov_b32_e32 v49, v2
	v_mov_b32_e32 v50, v2
	v_mov_b32_e32 v51, v2
	v_mov_b32_e32 v52, v2
	v_mov_b32_e32 v53, v2
	v_mov_b32_e32 v54, v2
	v_mov_b32_e32 v55, v2
	v_mov_b32_e32 v56, v2
	v_mov_b32_e32 v57, v2
	v_mov_b32_e32 v58, v2
	v_mov_b32_e32 v59, v2
	v_mov_b32_e32 v60, v2
	v_mov_b32_e32 v61, v2
	v_mov_b32_e32 v62, v2
	v_mov_b32_e32 v63, v2
	v_mov_b32_e32 v64, v2
	v_mov_b32_e32 v65, v2
	v_mov_b32_e32 v66, v2
	v_mov_b32_e32 v67, v2
	v_mov_b32_e32 v68, v2
	v_mov_b32_e32 v69, v2
	v_mov_b32_e32 v70, v2
	v_mov_b32_e32 v71, v2
	v_mov_b32_e32 v72, v2
	v_mov_b32_e32 v73, v2
	v_mov_b32_e32 v74, v2
	v_mov_b32_e32 v75, v2
	v_mov_b32_e32 v76, v2
	v_mov_b32_e32 v77, v2
	v_mov_b32_e32 v78, v2
	v_mov_b32_e32 v79, v2
	v_mov_b32_e32 v80, v2
	v_mov_b32_e32 v81, v2
	v_mov_b32_e32 v82, v2
	v_mov_b32_e32 v83, v2
	v_mov_b32_e32 v84, v2
	v_mov_b32_e32 v85, v2
	v_mov_b32_e32 v86, v2
	v_mov_b32_e32 v87, v2
	v_mov_b32_e32 v88, v2
	v_mov_b32_e32 v89, v2
	v_mov_b32_e32 v90, v2
	v_mov_b32_e32 v91, v2
	v_mov_b32_e32 v92, v2
	v_mov_b32_e32 v93, v2
	v_mov_b32_e32 v94, v2
	v_mov_b32_e32 v95, v2
	v_mov_b32_e32 v96, v2
	v_mov_b32_e32 v97, v2
	v_mov_b32_e32 v98, v2
	v_mov_b32_e32 v99, v2
	v_mov_b32_e32 v100, v2
	v_mov_b32_e32 v101, v2
	v_mov_b32_e32 v102, v2
	v_mov_b32_e32 v103, v2
	v_mov_b32_e32 v104, v2
	v_mov_b32_e32 v105, v2
	v_mov_b32_e32 v106, v2
	v_mov_b32_e32 v107, v2
	v_mov_b32_e32 v108, v2
	v_mov_b32_e32 v109, v2
	v_mov_b32_e32 v110, v2
	v_mov_b32_e32 v111, v2
	v_mov_b32_e32 v112, v2
	v_mov_b32_e32 v113, v2
	v_mov_b32_e32 v114, v2
	v_mov_b32_e32 v115, v2
	v_mov_b32_e32 v116, v2
	v_mov_b32_e32 v117, v2
	v_mov_b32_e32 v118, v2
	v_mov_b32_e32 v119, v2
	v_mov_b32_e32 v120, v2
	v_mov_b32_e32 v121, v2
	v_mov_b32_e32 v122, v2
	v_mov_b32_e32 v123, v2
	v_mov_b32_e32 v124, v2
	v_mov_b32_e32 v125, v2
	v_mov_b32_e32 v126, v2
	v_mov_b32_e32 v127, v2
	v_mov_b32_e32 v128, v2
	v_mov_b32_e32 v129, v2
	s_mov_b64 s[36:37], 0x58080
	s_mov_b64 s[40:41], 0xb0080
	s_mov_b64 s[42:43], 0x108080
	s_waitcnt vmcnt(0) lgkmcnt(0)
	s_barrier
	v_add_u32_e32 v170, v136, v143
	v_add_u32_e32 v174, v144, v146
	ds_read_b128 v[170:173], v170
	v_add_u32_e32 v178, v145, v151
	ds_read_b128 v[174:177], v174
	v_add_u32_e32 v182, v152, v156
	ds_read_b128 v[178:181], v178 offset:32768
	v_add_u32_e32 v186, v155, v157
	ds_read_b128 v[182:185], v182 offset:32768
	v_add_u32_e32 v190, v158, v167
	ds_read_b128 v[186:189], v186 offset:32768
	ds_read_b128 v[190:193], v190 offset:32768
	s_and_b32 s30, s3, 0x10000
	s_add_i32 s31, s30, s2
	v_lshl_add_u64 v[214:215], v[132:133], 0, s[6:7]
	v_lshl_add_u64 v[230:231], v[130:131], 0, s[6:7]
	s_add_i32 m0, s31, 0x8000
	v_lshl_add_u64 v[232:233], v[230:231], 0, s[28:29]
	global_load_lds_dwordx4 v[232:233], off
	s_add_i32 m0, s31, 0xa000
	v_lshl_add_u64 v[232:233], v[230:231], 0, s[36:37]
	global_load_lds_dwordx4 v[232:233], off
	s_add_i32 m0, s31, 0xc000
	v_lshl_add_u64 v[232:233], v[230:231], 0, s[40:41]
	global_load_lds_dwordx4 v[232:233], off
	s_add_i32 m0, s31, 0xe000
	v_lshl_add_u64 v[232:233], v[230:231], 0, s[42:43]
	global_load_lds_dwordx4 v[232:233], off
; DI f32x16 mfma(bf16x8 a, bf16x8 b, f32x16 c) { return __builtin_amdgcn_mfma_f32_32x32x16_bf16(a, b, c, 0, 0, 0); }
; template <int BK> DI int swz(int row) { constexpr int CPR = BK / 8; return (row / (16 / CPR)) % CPR; }
; DI void wait_vm0() { asm volatile("s_waitcnt vmcnt(0)" ::: "memory"); }
;   DI void pre(int grow0, int gcol0, int lane, int w, char* lds) { xpass(0, grow0, gcol0, lane, w, lds); }
;     ...
;   for (int kt = 0; kt < nk; ++kt) {
;     char* cur = lds + (kt & 1) * STG; char* nxt = lds + ((kt + 1) & 1) * STG;
;     const bool more = kt + 1 < nk;
;     const bf16_t* An = Ag + (kt + 1) * BK; const bf16_t* Bn = Bg + (kt + 1) * BK;
;     if (!more) epi.pre(row0 + wm * 64, col0 + wn * (32 * NTW), lane, w, lds);
;     bf16x8 fa[2][2], fb[2][NTW];
; #pragma unroll
;     for (int mt = 0; mt < 2; ++mt) { int row = wm * 64 + mt * 32 + l31; fa[0][mt] = *(const bf16x8*)(cur + row * (BK * 2) + ((hh ^ swz<BK>(row)) << 4)); }
; #pragma unroll
;     for (int nt = 0; nt < NTW; ++nt) { int row = wn * (32 * NTW) + nt * 32 + l31; fb[0][nt] = *(const bf16x8*)(cur + ABYTES + row * (BK * 2) + ((hh ^ swz<BK>(row)) << 4)); }
; #pragma unroll
;     for (int kk = 0; kk < NKK; ++kk) {
;       if (kk + 1 < NKK) {
;         const int ch = (kk + 1) * 2 + hh;
; #pragma unroll
;         for (int mt = 0; mt < 2; ++mt) { int row = wm * 64 + mt * 32 + l31; fa[(kk + 1) & 1][mt] = *(const bf16x8*)(cur + row * (BK * 2) + ((ch ^ swz<BK>(row)) << 4)); }
; #pragma unroll
;         for (int nt = 0; nt < NTW; ++nt) { int row = wn * (32 * NTW) + nt * 32 + l31; fb[(kk + 1) & 1][nt] = *(const bf16x8*)(cur + ABYTES + row * (BK * 2) + ((ch ^ swz<BK>(row)) << 4)); }
;       }
;       if (more) {
; #pragma unroll
;         for (int q = 0; q < PPK; ++q) {
;           const int pi = kk * PPK + q;
;           if (pi < NPA) stage_piece<BM, BK>(An, lda, nxt, tid, pi, wv);
;           else if (pi < NP) stage_piece<BN, BK>(Bn, ldb, nxt + ABYTES, tid, pi - NPA, wv);
;         }
;       }
;       __builtin_amdgcn_s_setprio(1);
; #pragma unroll
;       for (int mt = 0; mt < 2; ++mt)
; #pragma unroll
;         for (int nt = 0; nt < NTW; ++nt) acc[mt][nt] = mfma(fa[kk & 1][mt], fb[kk & 1][nt], acc[mt][nt]);
;       __builtin_amdgcn_s_setprio(0);
;       __builtin_amdgcn_sched_barrier(0);
;     }
;     wait_vm0();
;     __syncthreads();
.LBB0_292:
	s_and_b32 s30, s3, 0x10000
	s_xor_b32 s100, s30, 0x10000
	v_add3_u32 v194, s100, v136, v164
	v_add3_u32 v198, s100, v144, v166
	ds_read_b128 v[194:197], v194
	v_add3_u32 v202, s100, v145, v161
	ds_read_b128 v[198:201], v198
	v_add3_u32 v206, s100, v152, v163
	ds_read_b128 v[202:205], v202 offset:32768
	v_add3_u32 v210, s100, v155, v159
	ds_read_b128 v[206:209], v206 offset:32768
	v_add3_u32 v226, s100, v158, v160
	ds_read_b128 v[210:213], v210 offset:32768
	ds_read_b128 v[226:229], v226 offset:32768
	s_waitcnt lgkmcnt(6)
	s_mov_b32 m0, s31
	v_lshl_add_u64 v[232:233], v[214:215], 0, s[28:29]
	v_mfma_f32_32x32x16_bf16 v[114:129], v[170:173], v[178:181], v[114:129]
	global_load_lds_dwordx4 v[232:233], off
	s_add_i32 m0, s31, 0x2000
	v_lshl_add_u64 v[232:233], v[214:215], 0, s[36:37]
	v_mfma_f32_32x32x16_bf16 v[98:113], v[170:173], v[182:185], v[98:113]
	v_mfma_f32_32x32x16_bf16 v[82:97], v[170:173], v[186:189], v[82:97]
	global_load_lds_dwordx4 v[232:233], off
	s_add_i32 m0, s31, 0x4000
	v_lshl_add_u64 v[232:233], v[214:215], 0, s[40:41]
	v_mfma_f32_32x32x16_bf16 v[66:81], v[170:173], v[190:193], v[66:81]
	v_mfma_f32_32x32x16_bf16 v[50:65], v[174:177], v[178:181], v[50:65]
	global_load_lds_dwordx4 v[232:233], off
	s_add_i32 m0, s31, 0x6000
	v_lshl_add_u64 v[232:233], v[214:215], 0, s[42:43]
	v_mfma_f32_32x32x16_bf16 v[34:49], v[174:177], v[182:185], v[34:49]
	v_mfma_f32_32x32x16_bf16 v[18:33], v[174:177], v[186:189], v[18:33]
	global_load_lds_dwordx4 v[232:233], off
	v_mfma_f32_32x32x16_bf16 v[2:17], v[174:177], v[190:193], v[2:17]
	v_add3_u32 v170, s100, v136, v153
	v_add3_u32 v174, s100, v144, v154
	ds_read_b128 v[170:173], v170
	v_add3_u32 v178, s100, v145, v149
	ds_read_b128 v[174:177], v174
	v_add3_u32 v182, s100, v152, v150
	ds_read_b128 v[178:181], v178 offset:32768
	v_add3_u32 v186, s100, v155, v147
	ds_read_b128 v[182:185], v182 offset:32768
	v_add3_u32 v190, s100, v158, v148
	ds_read_b128 v[186:189], v186 offset:32768
	ds_read_b128 v[190:193], v190 offset:32768
	s_waitcnt lgkmcnt(6)
	v_mfma_f32_32x32x16_bf16 v[114:129], v[194:197], v[202:205], v[114:129]
	v_mfma_f32_32x32x16_bf16 v[98:113], v[194:197], v[206:209], v[98:113]
	v_mfma_f32_32x32x16_bf16 v[82:97], v[194:197], v[210:213], v[82:97]
	v_mfma_f32_32x32x16_bf16 v[66:81], v[194:197], v[226:229], v[66:81]
	v_mfma_f32_32x32x16_bf16 v[50:65], v[198:201], v[202:205], v[50:65]
	v_mfma_f32_32x32x16_bf16 v[34:49], v[198:201], v[206:209], v[34:49]
	v_mfma_f32_32x32x16_bf16 v[18:33], v[198:201], v[210:213], v[18:33]
	v_mfma_f32_32x32x16_bf16 v[2:17], v[198:201], v[226:229], v[2:17]
	v_add3_u32 v194, s100, v136, v141
	v_add3_u32 v198, s100, v144, v142
	ds_read_b128 v[194:197], v194
	v_add3_u32 v202, s100, v145, v139
	ds_read_b128 v[198:201], v198
	v_add3_u32 v206, s100, v152, v140
	ds_read_b128 v[202:205], v202 offset:32768
	v_add3_u32 v210, s100, v155, v137
	ds_read_b128 v[206:209], v206 offset:32768
	v_add3_u32 v226, s100, v158, v138
	ds_read_b128 v[210:213], v210 offset:32768
	ds_read_b128 v[226:229], v226 offset:32768
	s_waitcnt lgkmcnt(6)
	v_mfma_f32_32x32x16_bf16 v[114:129], v[170:173], v[178:181], v[114:129]
	v_mfma_f32_32x32x16_bf16 v[98:113], v[170:173], v[182:185], v[98:113]
	v_mfma_f32_32x32x16_bf16 v[82:97], v[170:173], v[186:189], v[82:97]
	v_mfma_f32_32x32x16_bf16 v[66:81], v[170:173], v[190:193], v[66:81]
	v_mfma_f32_32x32x16_bf16 v[50:65], v[174:177], v[178:181], v[50:65]
	v_mfma_f32_32x32x16_bf16 v[34:49], v[174:177], v[182:185], v[34:49]
	v_mfma_f32_32x32x16_bf16 v[18:33], v[174:177], v[186:189], v[18:33]
	v_mfma_f32_32x32x16_bf16 v[2:17], v[174:177], v[190:193], v[2:17]
	s_add_u32 s6, s6, 0x80
	s_addc_u32 s7, s7, 0
	s_add_i32 s3, s3, 0x10000
	s_waitcnt vmcnt(0) lgkmcnt(0)
	s_barrier
	v_add3_u32 v170, s30, v136, v143
	v_add3_u32 v174, s30, v144, v146
	ds_read_b128 v[170:173], v170
	v_add3_u32 v178, s30, v145, v151
	ds_read_b128 v[174:177], v174
	v_add3_u32 v182, s30, v152, v156
	ds_read_b128 v[178:181], v178 offset:32768
	v_add3_u32 v186, s30, v155, v157
	ds_read_b128 v[182:185], v182 offset:32768
	v_add3_u32 v190, s30, v158, v167
	ds_read_b128 v[186:189], v186 offset:32768
	ds_read_b128 v[190:193], v190 offset:32768
	s_cmpk_lg_i32 s6, 0x1580
	s_cbranch_scc0 .Lk292_exit
	s_add_i32 s31, s100, s2
	v_lshl_add_u64 v[214:215], v[132:133], 0, s[6:7]
	v_lshl_add_u64 v[230:231], v[130:131], 0, s[6:7]
	s_add_i32 m0, s31, 0x8000
	v_lshl_add_u64 v[232:233], v[230:231], 0, s[28:29]
	v_mfma_f32_32x32x16_bf16 v[114:129], v[194:197], v[202:205], v[114:129]
	global_load_lds_dwordx4 v[232:233], off
	s_add_i32 m0, s31, 0xa000
	v_lshl_add_u64 v[232:233], v[230:231], 0, s[36:37]
	v_mfma_f32_32x32x16_bf16 v[98:113], v[194:197], v[206:209], v[98:113]
	v_mfma_f32_32x32x16_bf16 v[82:97], v[194:197], v[210:213], v[82:97]
	global_load_lds_dwordx4 v[232:233], off
	s_add_i32 m0, s31, 0xc000
	v_lshl_add_u64 v[232:233], v[230:231], 0, s[40:41]
	v_mfma_f32_32x32x16_bf16 v[66:81], v[194:197], v[226:229], v[66:81]
	v_mfma_f32_32x32x16_bf16 v[50:65], v[198:201], v[202:205], v[50:65]
	global_load_lds_dwordx4 v[232:233], off
	s_add_i32 m0, s31, 0xe000
	v_lshl_add_u64 v[232:233], v[230:231], 0, s[42:43]
	v_mfma_f32_32x32x16_bf16 v[34:49], v[198:201], v[206:209], v[34:49]
	v_mfma_f32_32x32x16_bf16 v[18:33], v[198:201], v[210:213], v[18:33]
	global_load_lds_dwordx4 v[232:233], off
	v_mfma_f32_32x32x16_bf16 v[2:17], v[198:201], v[226:229], v[2:17]
	s_branch .LBB0_292

; DI f32x16 zero16() { f32x16 z; for (int i = 0; i < 16; ++i) z[i] = 0.f; return z; }
; template <int BK> DI int swz(int row) { constexpr int CPR = BK / 8; return (row / (16 / CPR)) % CPR; }
; DI void wait_vm0() { asm volatile("s_waitcnt vmcnt(0)" ::: "memory"); }
;   DI void pre(int grow0, int gcol0, int lane, int w, char* lds) { xpass(0, grow0, gcol0, lane, w, lds); }
;     ...
;   f32x16 acc[2][NTW];
; #pragma unroll
;   for (int a = 0; a < 2; ++a)
; #pragma unroll
;     for (int b = 0; b < NTW; ++b) acc[a][b] = zero16();
;   const bf16_t* Ag = A + (size_t)row0 * lda; const bf16_t* Bg = Bt + (size_t)col0 * ldb;
;   const int wv = __builtin_amdgcn_readfirstlane(tid >> 6);
;   __syncthreads();
;   if (!pre) { stage_tile<BM, BK>(Ag, lda, lds, tid); stage_tile<BN, BK>(Bg, ldb, lds + ABYTES, tid); }
;   wait_vm0();
;   __syncthreads();
;   const int nk = K / BK;
;   for (int kt = 0; kt < nk; ++kt) {
;     char* cur = lds + (kt & 1) * STG; char* nxt = lds + ((kt + 1) & 1) * STG;
;     const bool more = kt + 1 < nk;
;     const bf16_t* An = Ag + (kt + 1) * BK; const bf16_t* Bn = Bg + (kt + 1) * BK;
;     if (!more) epi.pre(row0 + wm * 64, col0 + wn * (32 * NTW), lane, w, lds);
;     bf16x8 fa[2][2], fb[2][NTW];
; #pragma unroll
;     for (int mt = 0; mt < 2; ++mt) { int row = wm * 64 + mt * 32 + l31; fa[0][mt] = *(const bf16x8*)(cur + row * (BK * 2) + ((hh ^ swz<BK>(row)) << 4)); }
; #pragma unroll
;     for (int nt = 0; nt < NTW; ++nt) { int row = wn * (32 * NTW) + nt * 32 + l31; fb[0][nt] = *(const bf16x8*)(cur + ABYTES + row * (BK * 2) + ((hh ^ swz<BK>(row)) << 4)); }
.LBB0_381:
	v_lshrrev_b32_e32 v4, 30, v3
	v_add_u32_e32 v4, v3, v4
	v_ashrrev_i32_e32 v4, 2, v4
	v_mul_i32_i24_e32 v5, 4, v4
	v_sub_u32_e32 v3, v3, v5
	v_and_b32_e32 v5, 31, v2
	v_lshlrev_b32_e32 v7, 6, v3
	v_or_b32_e32 v7, v7, v5
	v_bfe_u32 v3, v3, 25, 1
	v_lshlrev_b32_e32 v140, 7, v7
	v_add_u32_e32 v8, v7, v3
	v_or_b32_e32 v7, 32, v7
	v_add_u32_e32 v3, v7, v3
	v_lshlrev_b32_e32 v142, 7, v7
	v_ashrrev_i32_e32 v7, 1, v3
	v_ashrrev_i32_e32 v3, 31, v3
	v_ashrrev_i32_e32 v9, 1, v8
	v_ashrrev_i32_e32 v8, 31, v8
	v_lshrrev_b32_e32 v3, 29, v3
	v_lshrrev_b32_e32 v8, 29, v8
	v_add_u32_e32 v3, v7, v3
	v_add_u32_e32 v8, v9, v8
	v_and_b32_e32 v3, -8, v3
	v_lshrrev_b32_e32 v6, 5, v2
	v_and_b32_e32 v8, -8, v8
	v_sub_u32_e32 v3, v7, v3
	v_lshl_or_b32 v5, v4, 7, v5
	v_sub_u32_e32 v8, v9, v8
	v_bitop3_b32 v7, v3, v6, 1 bitop3:0x78
	v_lshrrev_b32_e32 v4, 31, v4
	v_bitop3_b32 v9, v8, v6, 1 bitop3:0x78
	v_lshlrev_b32_e32 v144, 4, v7
	v_add_u32_e32 v7, v5, v4
	v_lshlrev_b32_e32 v141, 4, v9
	v_ashrrev_i32_e32 v9, 1, v7
	v_ashrrev_i32_e32 v7, 31, v7
	v_lshrrev_b32_e32 v7, 29, v7
	v_add_u32_e32 v7, v9, v7
	v_and_b32_e32 v7, -8, v7
	v_sub_u32_e32 v7, v9, v7
	v_bitop3_b32 v9, v7, v6, 1 bitop3:0x78
	v_lshlrev_b32_e32 v151, 4, v9
	v_or_b32_e32 v9, 32, v5
	v_lshlrev_b32_e32 v152, 7, v9
	v_add_u32_e32 v9, v9, v4
	v_ashrrev_i32_e32 v10, 1, v9
	v_ashrrev_i32_e32 v9, 31, v9
	v_lshrrev_b32_e32 v9, 29, v9
	v_add_u32_e32 v9, v10, v9
	v_and_b32_e32 v9, -8, v9
	v_sub_u32_e32 v9, v10, v9
	v_bitop3_b32 v10, v9, v6, 1 bitop3:0x78
	v_lshlrev_b32_e32 v143, 7, v5
	v_lshlrev_b32_e32 v154, 4, v10
	v_or_b32_e32 v10, 64, v5
	v_or_b32_e32 v5, 0x60, v5
	v_lshlrev_b32_e32 v153, 7, v10
	v_add_u32_e32 v10, v10, v4
	v_add_u32_e32 v4, v5, v4
	v_lshlrev_b32_e32 v156, 7, v5
	v_ashrrev_i32_e32 v5, 1, v4
	v_ashrrev_i32_e32 v4, 31, v4
	v_lshrrev_b32_e32 v4, 29, v4
	v_add_u32_e32 v4, v5, v4
	v_and_b32_e32 v4, -8, v4
	v_sub_u32_e32 v4, v5, v4
	v_bfe_u32 v2, v2, 5, 1
	v_ashrrev_i32_e32 v11, 1, v10
	v_ashrrev_i32_e32 v10, 31, v10
	v_bitop3_b32 v5, v4, v6, 1 bitop3:0x78
	v_lshrrev_b32_e32 v10, 29, v10
	v_lshlrev_b32_e32 v164, 4, v5
	v_bitop3_b32 v5, v8, v2, 2 bitop3:0x1e
	v_add_u32_e32 v10, v11, v10
	v_lshlrev_b32_e32 v161, 4, v5
	v_bitop3_b32 v5, v3, v2, 2 bitop3:0x1e
	v_and_b32_e32 v10, -8, v10
	v_lshlrev_b32_e32 v163, 4, v5
	v_bitop3_b32 v5, v7, v2, 2 bitop3:0x1e
	v_sub_u32_e32 v10, v11, v10
	v_lshlrev_b32_e32 v159, 4, v5
	v_bitop3_b32 v5, v9, v2, 2 bitop3:0x1e
	s_lshr_b32 s7, s36, 3
	v_lshlrev_b32_e32 v160, 4, v5
	v_bitop3_b32 v5, v10, v2, 2 bitop3:0x1e
	s_and_b32 s7, s7, 7
	s_lshl_b32 s30, s35, 19
	v_lshlrev_b32_e32 v157, 4, v5
	v_bitop3_b32 v5, v4, v2, 2 bitop3:0x1e
	s_lshl_b32 s7, s7, 19
	s_and_b32 s30, s30, 0x1c00000
	v_lshlrev_b32_e32 v158, 4, v5
	v_bitop3_b32 v5, v8, v2, 4 bitop3:0x1e
	s_or_b32 s7, s30, s7
	s_and_b32 s30, s34, 0xffffff00
	v_lshlrev_b32_e32 v149, 4, v5
	v_bitop3_b32 v5, v3, v2, 4 bitop3:0x1e
	s_ashr_i32 s31, s30, 31
	v_lshlrev_b32_e32 v150, 4, v5
	v_bitop3_b32 v5, v7, v2, 4 bitop3:0x1e
	s_lshl_b64 s[30:31], s[30:31], 11
	s_lshl_b32 s3, s3, 10
	v_lshlrev_b32_e32 v147, 4, v5
	v_bitop3_b32 v5, v9, v2, 4 bitop3:0x1e
	v_bitop3_b32 v3, v3, v2, 6 bitop3:0x1e
	v_lshlrev_b32_e32 v148, 4, v5
	v_bitop3_b32 v5, v10, v2, 4 bitop3:0x1e
	v_lshlrev_b32_e32 v139, 4, v3
	v_bitop3_b32 v3, v7, v2, 6 bitop3:0x1e
	s_add_u32 s42, s12, s7
	v_lshlrev_b32_e32 v145, 4, v5
	v_bitop3_b32 v5, v4, v2, 4 bitop3:0x1e
	v_lshlrev_b32_e32 v136, 4, v3
	v_bitop3_b32 v3, v9, v2, 6 bitop3:0x1e
	s_addc_u32 s43, s13, 0
	s_waitcnt vmcnt(0)
	v_lshlrev_b32_e32 v146, 4, v5
	v_bitop3_b32 v5, v8, v2, 6 bitop3:0x1e
	v_lshlrev_b32_e32 v137, 4, v3
	v_bitop3_b32 v3, v10, v2, 6 bitop3:0x1e
	v_bitop3_b32 v2, v4, v2, 6 bitop3:0x1e
	s_add_u32 s30, s40, s30
	v_bitop3_b32 v11, v10, v6, 1 bitop3:0x78
	v_lshlrev_b32_e32 v135, 4, v2
	s_addc_u32 s31, s41, s31
	v_mov_b32_e32 v2, 0
	v_lshlrev_b32_e32 v155, 4, v11
	v_lshlrev_b32_e32 v138, 4, v5
	v_lshlrev_b32_e32 v134, 4, v3
	v_lshl_add_u64 v[130:131], s[42:43], 0, v[0:1]
	v_lshl_add_u64 v[132:133], s[30:31], 0, v[0:1]
	s_mov_b64 s[30:31], 0
	s_mov_b32 s7, 0x10000
	v_mov_b32_e32 v3, v2
	v_mov_b32_e32 v4, v2
	v_mov_b32_e32 v5, v2
	v_mov_b32_e32 v6, v2
	v_mov_b32_e32 v7, v2
	v_mov_b32_e32 v8, v2
	v_mov_b32_e32 v9, v2
	v_mov_b32_e32 v10, v2
	v_mov_b32_e32 v11, v2
	v_mov_b32_e32 v12, v2
	v_mov_b32_e32 v13, v2
	v_mov_b32_e32 v14, v2
	v_mov_b32_e32 v15, v2
	v_mov_b32_e32 v16, v2
	v_mov_b32_e32 v17, v2
	v_mov_b32_e32 v18, v2
	v_mov_b32_e32 v19, v2
	v_mov_b32_e32 v20, v2
	v_mov_b32_e32 v21, v2
	v_mov_b32_e32 v22, v2
	v_mov_b32_e32 v23, v2
	v_mov_b32_e32 v24, v2
	v_mov_b32_e32 v25, v2
	v_mov_b32_e32 v26, v2
	v_mov_b32_e32 v27, v2
	v_mov_b32_e32 v28, v2
	v_mov_b32_e32 v29, v2
	v_mov_b32_e32 v30, v2
	v_mov_b32_e32 v31, v2
	v_mov_b32_e32 v32, v2
	v_mov_b32_e32 v33, v2
	v_mov_b32_e32 v34, v2
	v_mov_b32_e32 v35, v2
	v_mov_b32_e32 v36, v2
	v_mov_b32_e32 v37, v2
	v_mov_b32_e32 v38, v2
	v_mov_b32_e32 v39, v2
	v_mov_b32_e32 v40, v2
	v_mov_b32_e32 v41, v2
	v_mov_b32_e32 v42, v2
	v_mov_b32_e32 v43, v2
	v_mov_b32_e32 v44, v2
	v_mov_b32_e32 v45, v2
	v_mov_b32_e32 v46, v2
	v_mov_b32_e32 v47, v2
	v_mov_b32_e32 v48, v2
	v_mov_b32_e32 v49, v2
	v_mov_b32_e32 v50, v2
	v_mov_b32_e32 v51, v2
	v_mov_b32_e32 v52, v2
	v_mov_b32_e32 v53, v2
	v_mov_b32_e32 v54, v2
	v_mov_b32_e32 v55, v2
	v_mov_b32_e32 v56, v2
	v_mov_b32_e32 v57, v2
	v_mov_b32_e32 v58, v2
	v_mov_b32_e32 v59, v2
	v_mov_b32_e32 v60, v2
	v_mov_b32_e32 v61, v2
	v_mov_b32_e32 v62, v2
	v_mov_b32_e32 v63, v2
	v_mov_b32_e32 v64, v2
	v_mov_b32_e32 v65, v2
	v_mov_b32_e32 v66, v2
	v_mov_b32_e32 v67, v2
	v_mov_b32_e32 v68, v2
	v_mov_b32_e32 v69, v2
	v_mov_b32_e32 v70, v2
; DI f32x16 zero16() { f32x16 z; for (int i = 0; i < 16; ++i) z[i] = 0.f; return z; }
; template <int BK> DI int swz(int row) { constexpr int CPR = BK / 8; return (row / (16 / CPR)) % CPR; }
; DI void wait_vm0() { asm volatile("s_waitcnt vmcnt(0)" ::: "memory"); }
;     ...
;   f32x16 acc[2][NTW];
; #pragma unroll
;   for (int a = 0; a < 2; ++a)
; #pragma unroll
;     for (int b = 0; b < NTW; ++b) acc[a][b] = zero16();
;   const bf16_t* Ag = A + (size_t)row0 * lda; const bf16_t* Bg = Bt + (size_t)col0 * ldb;
;   const int wv = __builtin_amdgcn_readfirstlane(tid >> 6);
;   __syncthreads();
;   if (!pre) { stage_tile<BM, BK>(Ag, lda, lds, tid); stage_tile<BN, BK>(Bg, ldb, lds + ABYTES, tid); }
;   wait_vm0();
;   __syncthreads();
;   const int nk = K / BK;
;   for (int kt = 0; kt < nk; ++kt) {
;     char* cur = lds + (kt & 1) * STG; char* nxt = lds + ((kt + 1) & 1) * STG;
;     const bool more = kt + 1 < nk;
;     const bf16_t* An = Ag + (kt + 1) * BK; const bf16_t* Bn = Bg + (kt + 1) * BK;
;     if (!more) epi.pre(row0 + wm * 64, col0 + wn * (32 * NTW), lane, w, lds);
;     bf16x8 fa[2][2], fb[2][NTW];
; #pragma unroll
;     for (int mt = 0; mt < 2; ++mt) { int row = wm * 64 + mt * 32 + l31; fa[0][mt] = *(const bf16x8*)(cur + row * (BK * 2) + ((hh ^ swz<BK>(row)) << 4)); }
; #pragma unroll
;     for (int nt = 0; nt < NTW; ++nt) { int row = wn * (32 * NTW) + nt * 32 + l31; fb[0][nt] = *(const bf16x8*)(cur + ABYTES + row * (BK * 2) + ((hh ^ swz<BK>(row)) << 4)); }
; #pragma unroll
;     for (int kk = 0; kk < NKK; ++kk) {
;       if (kk + 1 < NKK) {
;         const int ch = (kk + 1) * 2 + hh;
; #pragma unroll
;         for (int mt = 0; mt < 2; ++mt) { int row = wm * 64 + mt * 32 + l31; fa[(kk + 1) & 1][mt] = *(const bf16x8*)(cur + row * (BK * 2) + ((ch ^ swz<BK>(row)) << 4)); }
; #pragma unroll
;         for (int nt = 0; nt < NTW; ++nt) { int row = wn * (32 * NTW) + nt * 32 + l31; fb[(kk + 1) & 1][nt] = *(const bf16x8*)(cur + ABYTES + row * (BK * 2) + ((ch ^ swz<BK>(row)) << 4)); }
;       }
;       if (more) {
; #pragma unroll
;         for (int q = 0; q < PPK; ++q) {
;           const int pi = kk * PPK + q;
;           if (pi < NPA) stage_piece<BM, BK>(An, lda, nxt, tid, pi, wv);
;           else if (pi < NP) stage_piece<BN, BK>(Bn, ldb, nxt + ABYTES, tid, pi - NPA, wv);
;         }
;       }
	v_mov_b32_e32 v71, v2
	v_mov_b32_e32 v72, v2
	v_mov_b32_e32 v73, v2
	v_mov_b32_e32 v74, v2
	v_mov_b32_e32 v75, v2
	v_mov_b32_e32 v76, v2
	v_mov_b32_e32 v77, v2
	v_mov_b32_e32 v78, v2
	v_mov_b32_e32 v79, v2
	v_mov_b32_e32 v80, v2
	v_mov_b32_e32 v81, v2
	v_mov_b32_e32 v82, v2
	v_mov_b32_e32 v83, v2
	v_mov_b32_e32 v84, v2
	v_mov_b32_e32 v85, v2
	v_mov_b32_e32 v86, v2
	v_mov_b32_e32 v87, v2
	v_mov_b32_e32 v88, v2
	v_mov_b32_e32 v89, v2
	v_mov_b32_e32 v90, v2
	v_mov_b32_e32 v91, v2
	v_mov_b32_e32 v92, v2
	v_mov_b32_e32 v93, v2
	v_mov_b32_e32 v94, v2
	v_mov_b32_e32 v95, v2
	v_mov_b32_e32 v96, v2
	v_mov_b32_e32 v97, v2
	v_mov_b32_e32 v98, v2
	v_mov_b32_e32 v99, v2
	v_mov_b32_e32 v100, v2
	v_mov_b32_e32 v101, v2
	v_mov_b32_e32 v102, v2
	v_mov_b32_e32 v103, v2
	v_mov_b32_e32 v104, v2
	v_mov_b32_e32 v105, v2
	v_mov_b32_e32 v106, v2
	v_mov_b32_e32 v107, v2
	v_mov_b32_e32 v108, v2
	v_mov_b32_e32 v109, v2
	v_mov_b32_e32 v110, v2
	v_mov_b32_e32 v111, v2
	v_mov_b32_e32 v112, v2
	v_mov_b32_e32 v113, v2
	v_mov_b32_e32 v114, v2
	v_mov_b32_e32 v115, v2
	v_mov_b32_e32 v116, v2
	v_mov_b32_e32 v117, v2
	v_mov_b32_e32 v118, v2
	v_mov_b32_e32 v119, v2
	v_mov_b32_e32 v120, v2
	v_mov_b32_e32 v121, v2
	v_mov_b32_e32 v122, v2
	v_mov_b32_e32 v123, v2
	v_mov_b32_e32 v124, v2
	v_mov_b32_e32 v125, v2
	v_mov_b32_e32 v126, v2
	v_mov_b32_e32 v127, v2
	v_mov_b32_e32 v128, v2
	v_mov_b32_e32 v129, v2
	s_waitcnt vmcnt(0) lgkmcnt(0)
	s_barrier
	v_add_u32_e32 v166, v140, v141
	v_add_u32_e32 v170, v142, v144
	ds_read_b128 v[166:169], v166
	v_add_u32_e32 v174, v143, v151
	ds_read_b128 v[170:173], v170
	v_add_u32_e32 v178, v152, v154
	ds_read_b128 v[174:177], v174 offset:32768
	v_add_u32_e32 v182, v153, v155
	ds_read_b128 v[178:181], v178 offset:32768
	v_add_u32_e32 v186, v156, v164
	ds_read_b128 v[182:185], v182 offset:32768
	ds_read_b128 v[186:189], v186 offset:32768
	s_and_b32 s42, s7, 0x10000
	s_add_i32 s37, s42, s3
	v_lshl_add_u64 v[214:215], v[130:131], 0, s[30:31]
	v_lshl_add_u64 v[226:227], v[132:133], 0, s[30:31]
	s_add_i32 m0, s37, 0x8000
	v_lshl_add_u64 v[228:229], v[226:227], 0, s[28:29]
	global_load_lds_dwordx4 v[228:229], off
	s_add_i32 m0, s37, 0xa000
	v_lshl_add_u64 v[228:229], v[226:227], 0, s[24:25]
	global_load_lds_dwordx4 v[228:229], off
	s_add_i32 m0, s37, 0xc000
	v_lshl_add_u64 v[228:229], v[226:227], 0, s[26:27]
	global_load_lds_dwordx4 v[228:229], off
	s_add_i32 m0, s37, 0xe000
	v_lshl_add_u64 v[228:229], v[226:227], 0, s[38:39]
	global_load_lds_dwordx4 v[228:229], off
; DI f32x16 mfma(bf16x8 a, bf16x8 b, f32x16 c) { return __builtin_amdgcn_mfma_f32_32x32x16_bf16(a, b, c, 0, 0, 0); }
; template <int BK> DI int swz(int row) { constexpr int CPR = BK / 8; return (row / (16 / CPR)) % CPR; }
; DI void wait_vm0() { asm volatile("s_waitcnt vmcnt(0)" ::: "memory"); }
;   DI void pre(int grow0, int gcol0, int lane, int w, char* lds) { xpass(0, grow0, gcol0, lane, w, lds); }
;     ...
;   for (int kt = 0; kt < nk; ++kt) {
;     char* cur = lds + (kt & 1) * STG; char* nxt = lds + ((kt + 1) & 1) * STG;
;     const bool more = kt + 1 < nk;
;     const bf16_t* An = Ag + (kt + 1) * BK; const bf16_t* Bn = Bg + (kt + 1) * BK;
;     if (!more) epi.pre(row0 + wm * 64, col0 + wn * (32 * NTW), lane, w, lds);
;     bf16x8 fa[2][2], fb[2][NTW];
; #pragma unroll
;     for (int mt = 0; mt < 2; ++mt) { int row = wm * 64 + mt * 32 + l31; fa[0][mt] = *(const bf16x8*)(cur + row * (BK * 2) + ((hh ^ swz<BK>(row)) << 4)); }
; #pragma unroll
;     for (int nt = 0; nt < NTW; ++nt) { int row = wn * (32 * NTW) + nt * 32 + l31; fb[0][nt] = *(const bf16x8*)(cur + ABYTES + row * (BK * 2) + ((hh ^ swz<BK>(row)) << 4)); }
; #pragma unroll
;     for (int kk = 0; kk < NKK; ++kk) {
;       if (kk + 1 < NKK) {
;         const int ch = (kk + 1) * 2 + hh;
; #pragma unroll
;         for (int mt = 0; mt < 2; ++mt) { int row = wm * 64 + mt * 32 + l31; fa[(kk + 1) & 1][mt] = *(const bf16x8*)(cur + row * (BK * 2) + ((ch ^ swz<BK>(row)) << 4)); }
; #pragma unroll
;         for (int nt = 0; nt < NTW; ++nt) { int row = wn * (32 * NTW) + nt * 32 + l31; fb[(kk + 1) & 1][nt] = *(const bf16x8*)(cur + ABYTES + row * (BK * 2) + ((ch ^ swz<BK>(row)) << 4)); }
;       }
;       if (more) {
; #pragma unroll
;         for (int q = 0; q < PPK; ++q) {
;           const int pi = kk * PPK + q;
;           if (pi < NPA) stage_piece<BM, BK>(An, lda, nxt, tid, pi, wv);
;           else if (pi < NP) stage_piece<BN, BK>(Bn, ldb, nxt + ABYTES, tid, pi - NPA, wv);
;         }
;       }
;       __builtin_amdgcn_s_setprio(1);
; #pragma unroll
;       for (int mt = 0; mt < 2; ++mt)
; #pragma unroll
;         for (int nt = 0; nt < NTW; ++nt) acc[mt][nt] = mfma(fa[kk & 1][mt], fb[kk & 1][nt], acc[mt][nt]);
;       __builtin_amdgcn_s_setprio(0);
;       __builtin_amdgcn_sched_barrier(0);
;     }
;     wait_vm0();
;     __syncthreads();
.LBB0_382:
	s_and_b32 s42, s7, 0x10000
	s_xor_b32 s100, s42, 0x10000
	v_add3_u32 v190, s100, v140, v161
	v_add3_u32 v194, s100, v142, v163
	ds_read_b128 v[190:193], v190
	v_add3_u32 v198, s100, v143, v159
	ds_read_b128 v[194:197], v194
	v_add3_u32 v202, s100, v152, v160
	ds_read_b128 v[198:201], v198 offset:32768
	v_add3_u32 v206, s100, v153, v157
	ds_read_b128 v[202:205], v202 offset:32768
	v_add3_u32 v210, s100, v156, v158
	ds_read_b128 v[206:209], v206 offset:32768
	ds_read_b128 v[210:213], v210 offset:32768
	s_waitcnt lgkmcnt(6)
	s_mov_b32 m0, s37
	v_lshl_add_u64 v[228:229], v[214:215], 0, s[28:29]
	v_mfma_f32_32x32x16_bf16 v[114:129], v[166:169], v[174:177], v[114:129]
	global_load_lds_dwordx4 v[228:229], off
	s_add_i32 m0, s37, 0x2000
	v_lshl_add_u64 v[228:229], v[214:215], 0, s[24:25]
	v_mfma_f32_32x32x16_bf16 v[98:113], v[166:169], v[178:181], v[98:113]
	v_mfma_f32_32x32x16_bf16 v[82:97], v[166:169], v[182:185], v[82:97]
	global_load_lds_dwordx4 v[228:229], off
	s_add_i32 m0, s37, 0x4000
	v_lshl_add_u64 v[228:229], v[214:215], 0, s[26:27]
	v_mfma_f32_32x32x16_bf16 v[66:81], v[166:169], v[186:189], v[66:81]
	v_mfma_f32_32x32x16_bf16 v[50:65], v[170:173], v[174:177], v[50:65]
	global_load_lds_dwordx4 v[228:229], off
	s_add_i32 m0, s37, 0x6000
	v_lshl_add_u64 v[228:229], v[214:215], 0, s[38:39]
	v_mfma_f32_32x32x16_bf16 v[34:49], v[170:173], v[178:181], v[34:49]
	v_mfma_f32_32x32x16_bf16 v[18:33], v[170:173], v[182:185], v[18:33]
	global_load_lds_dwordx4 v[228:229], off
	v_mfma_f32_32x32x16_bf16 v[2:17], v[170:173], v[186:189], v[2:17]
	v_add3_u32 v166, s100, v140, v149
	v_add3_u32 v170, s100, v142, v150
	ds_read_b128 v[166:169], v166
	v_add3_u32 v174, s100, v143, v147
	ds_read_b128 v[170:173], v170
	v_add3_u32 v178, s100, v152, v148
	ds_read_b128 v[174:177], v174 offset:32768
	v_add3_u32 v182, s100, v153, v145
	ds_read_b128 v[178:181], v178 offset:32768
	v_add3_u32 v186, s100, v156, v146
	ds_read_b128 v[182:185], v182 offset:32768
	ds_read_b128 v[186:189], v186 offset:32768
	s_waitcnt lgkmcnt(6)
	v_mfma_f32_32x32x16_bf16 v[114:129], v[190:193], v[198:201], v[114:129]
	v_mfma_f32_32x32x16_bf16 v[98:113], v[190:193], v[202:205], v[98:113]
	v_mfma_f32_32x32x16_bf16 v[82:97], v[190:193], v[206:209], v[82:97]
	v_mfma_f32_32x32x16_bf16 v[66:81], v[190:193], v[210:213], v[66:81]
	v_mfma_f32_32x32x16_bf16 v[50:65], v[194:197], v[198:201], v[50:65]
	v_mfma_f32_32x32x16_bf16 v[34:49], v[194:197], v[202:205], v[34:49]
	v_mfma_f32_32x32x16_bf16 v[18:33], v[194:197], v[206:209], v[18:33]
	v_mfma_f32_32x32x16_bf16 v[2:17], v[194:197], v[210:213], v[2:17]
	v_add3_u32 v190, s100, v140, v138
	v_add3_u32 v194, s100, v142, v139
	ds_read_b128 v[190:193], v190
	v_add3_u32 v198, s100, v143, v136
	ds_read_b128 v[194:197], v194
	v_add3_u32 v202, s100, v152, v137
	ds_read_b128 v[198:201], v198 offset:32768
	v_add3_u32 v206, s100, v153, v134
	ds_read_b128 v[202:205], v202 offset:32768
	v_add3_u32 v210, s100, v156, v135
	ds_read_b128 v[206:209], v206 offset:32768
	ds_read_b128 v[210:213], v210 offset:32768
	s_waitcnt lgkmcnt(6)
	v_mfma_f32_32x32x16_bf16 v[114:129], v[166:169], v[174:177], v[114:129]
	v_mfma_f32_32x32x16_bf16 v[98:113], v[166:169], v[178:181], v[98:113]
	v_mfma_f32_32x32x16_bf16 v[82:97], v[166:169], v[182:185], v[82:97]
	v_mfma_f32_32x32x16_bf16 v[66:81], v[166:169], v[186:189], v[66:81]
	v_mfma_f32_32x32x16_bf16 v[50:65], v[170:173], v[174:177], v[50:65]
	v_mfma_f32_32x32x16_bf16 v[34:49], v[170:173], v[178:181], v[34:49]
	v_mfma_f32_32x32x16_bf16 v[18:33], v[170:173], v[182:185], v[18:33]
	v_mfma_f32_32x32x16_bf16 v[2:17], v[170:173], v[186:189], v[2:17]
	s_add_u32 s30, s30, 0x80
	s_addc_u32 s31, s31, 0
	s_add_i32 s7, s7, 0x10000
	s_waitcnt vmcnt(0) lgkmcnt(0)
	s_barrier
	v_add3_u32 v166, s42, v140, v141
	v_add3_u32 v170, s42, v142, v144
	ds_read_b128 v[166:169], v166
	v_add3_u32 v174, s42, v143, v151
	ds_read_b128 v[170:173], v170
	v_add3_u32 v178, s42, v152, v154
	ds_read_b128 v[174:177], v174 offset:32768
	v_add3_u32 v182, s42, v153, v155
	ds_read_b128 v[178:181], v178 offset:32768
	v_add3_u32 v186, s42, v156, v164
	ds_read_b128 v[182:185], v182 offset:32768
	ds_read_b128 v[186:189], v186 offset:32768
	s_cmpk_eq_i32 s30, 0x780
	s_cbranch_scc1 .Lk382_exit
	s_add_i32 s37, s100, s3
	v_lshl_add_u64 v[214:215], v[130:131], 0, s[30:31]
	v_lshl_add_u64 v[226:227], v[132:133], 0, s[30:31]
	s_add_i32 m0, s37, 0x8000
	v_lshl_add_u64 v[228:229], v[226:227], 0, s[28:29]
	v_mfma_f32_32x32x16_bf16 v[114:129], v[190:193], v[198:201], v[114:129]
	global_load_lds_dwordx4 v[228:229], off
	s_add_i32 m0, s37, 0xa000
	v_lshl_add_u64 v[228:229], v[226:227], 0, s[24:25]
	v_mfma_f32_32x32x16_bf16 v[98:113], v[190:193], v[202:205], v[98:113]
	v_mfma_f32_32x32x16_bf16 v[82:97], v[190:193], v[206:209], v[82:97]
	global_load_lds_dwordx4 v[228:229], off
	s_add_i32 m0, s37, 0xc000
	v_lshl_add_u64 v[228:229], v[226:227], 0, s[26:27]
	v_mfma_f32_32x32x16_bf16 v[66:81], v[190:193], v[210:213], v[66:81]
	v_mfma_f32_32x32x16_bf16 v[50:65], v[194:197], v[198:201], v[50:65]
	global_load_lds_dwordx4 v[228:229], off
	s_add_i32 m0, s37, 0xe000
	v_lshl_add_u64 v[228:229], v[226:227], 0, s[38:39]
	v_mfma_f32_32x32x16_bf16 v[34:49], v[194:197], v[202:205], v[34:49]
	v_mfma_f32_32x32x16_bf16 v[18:33], v[194:197], v[206:209], v[18:33]
	global_load_lds_dwordx4 v[228:229], off
	v_mfma_f32_32x32x16_bf16 v[2:17], v[194:197], v[210:213], v[2:17]
	s_branch .LBB0_382

; DI f32x16 zero16() { f32x16 z; for (int i = 0; i < 16; ++i) z[i] = 0.f; return z; }
; DI int launder(int x) { asm volatile("" : "+v"(x)); return x; }
; template <int BK> DI int swz(int row) { constexpr int CPR = BK / 8; return (row / (16 / CPR)) % CPR; }
; DI void wait_vm0() { asm volatile("s_waitcnt vmcnt(0)" ::: "memory"); }
; template <int ROWS, int BK>
; DI void stage_tile(const bf16_t* g, int ld, char* l, int tid) {
;   constexpr int CPR = BK / 8, TOT = ROWS * CPR, N = (TOT + NT - 1) / NT;
;   const int row0 = tid / CPR, pc = tid % CPR; const int c = pc ^ swz<BK>(row0);
;   const unsigned voff = (unsigned)(row0 * ld + c * 8) * 2u;
; #pragma unroll
;   for (int i = 0; i < N; ++i) {
;     if (TOT % NT == 0 || tid + i * NT < TOT) {
;       const char* gb = (const char*)g + (size_t)i * (NT / CPR) * ld * 2;
;       __builtin_amdgcn_global_load_lds((const unsigned*)(gb + voff), (__attribute__((address_space(3))) unsigned*)(l + i * NT * 16 + __builtin_amdgcn_readfirstlane(tid >> 6) * 1024), 16, 0, 0);
;     }
;   }
; }
;     ...
;   const int tid = launder(threadIdx.x), lane = tid & 63, w = tid >> 6, wm = w % WM, wn = w / WM;
;   const int l31 = lane & 31, hh = lane >> 5;
;   f32x16 acc[2][NTW];
; #pragma unroll
;   for (int a = 0; a < 2; ++a)
; #pragma unroll
;     for (int b = 0; b < NTW; ++b) acc[a][b] = zero16();
;   const bf16_t* Ag = A + (size_t)row0 * lda; const bf16_t* Bg = Bt + (size_t)col0 * ldb;
;   const int wv = __builtin_amdgcn_readfirstlane(tid >> 6);
;   __syncthreads();
;   if (!pre) { stage_tile<BM, BK>(Ag, lda, lds, tid); stage_tile<BN, BK>(Bg, ldb, lds + ABYTES, tid); }
;   wait_vm0();
;   __syncthreads();
;   const int nk = K / BK;
;   for (int kt = 0; kt < nk; ++kt) {
;     char* cur = lds + (kt & 1) * STG; char* nxt = lds + ((kt + 1) & 1) * STG;
;     const bool more = kt + 1 < nk;
;     const bf16_t* An = Ag + (kt + 1) * BK; const bf16_t* Bn = Bg + (kt + 1) * BK;
;     if (!more) epi.pre(row0 + wm * 64, col0 + wn * (32 * NTW), lane, w, lds);
;     bf16x8 fa[2][2], fb[2][NTW];
; #pragma unroll
;     for (int mt = 0; mt < 2; ++mt) { int row = wm * 64 + mt * 32 + l31; fa[0][mt] = *(const bf16x8*)(cur + row * (BK * 2) + ((hh ^ swz<BK>(row)) << 4)); }
; #pragma unroll
;     for (int nt = 0; nt < NTW; ++nt) { int row = wn * (32 * NTW) + nt * 32 + l31; fb[0][nt] = *(const bf16x8*)(cur + ABYTES + row * (BK * 2) + ((hh ^ swz<BK>(row)) << 4)); }
.LBB0_387:
	s_bfe_u32 s6, s36, 0x30003
	s_lshl_b32 s3, s35, 19
	s_lshl_b32 s2, s6, 19
	s_and_b32 s3, s3, 0x1c00000
	s_or_b32 s37, s3, s2
	s_and_b32 s2, s34, 0xffffff80
	s_addk_i32 s2, 0x1400
	s_ashr_i32 s3, s2, 31
	s_lshl_b64 s[30:31], s[2:3], 11
	s_lshl_b32 s2, s36, 3
	s_and_b32 s2, s2, 56
	v_mov_b32_e32 v4, v216
	s_or_b32 s2, s2, s6
	s_lshl_b32 s6, s36, 1
	s_and_b32 s6, s6, 0xffffff80
	v_ashrrev_i32_e32 v0, 6, v4
	v_lshrrev_b32_e32 v2, 30, v0
	s_addk_i32 s6, 0x1400
	v_add_u32_e32 v6, v0, v2
	s_lshl_b32 s7, s2, 19
	v_ashrrev_i32_e32 v7, 2, v6
	s_add_u32 s42, s12, s7
	v_mul_i32_i24_e32 v2, 4, v7
	s_addc_u32 s43, s13, 0
	s_ashr_i32 s7, s6, 31
	v_sub_u32_e32 v9, v0, v2
	s_lshl_b64 s[44:45], s[6:7], 11
	v_readfirstlane_b32 s7, v0
	v_ashrrev_i32_e32 v0, 31, v4
	v_lshrrev_b32_e32 v2, 29, v0
	v_lshrrev_b32_e32 v0, 28, v0
	v_add_u32_e32 v0, v4, v0
	v_ashrrev_i32_e32 v0, 4, v0
	v_lshrrev_b32_e32 v5, 29, v0
	v_add_u32_e32 v2, v4, v2
	v_add_u32_e32 v5, v0, v5
	v_and_b32_e32 v3, 0xffffff8, v2
	v_and_b32_e32 v5, 0xffffff8, v5
	s_waitcnt lgkmcnt(0)
	s_add_u32 s44, s40, s44
	v_sub_u32_e32 v3, v4, v3
	v_sub_u32_e32 v0, v0, v5
	v_lshlrev_b32_e32 v2, 8, v2
	v_readfirstlane_b32 s46, v4
	s_addc_u32 s45, s41, s45
	v_xor_b32_e32 v0, v0, v3
	v_and_b32_e32 v2, 0xfffff800, v2
	s_lshl_b32 s46, s46, 4
	v_lshl_add_u32 v0, v0, 4, v2
	s_and_b32 s46, s46, 0xfffffc00
	v_lshl_add_u64 v[2:3], s[42:43], 0, v[0:1]
	s_mov_b32 m0, s46
	v_lshrrev_b32_e32 v8, 5, v4
	v_and_b32_e32 v10, 31, v4
	v_bfe_u32 v11, v4, 5, 1
	s_waitcnt vmcnt(0)
	s_barrier
	global_load_lds_dwordx4 v0, s[42:43]
	v_lshl_add_u64 v[4:5], v[2:3], 0, s[58:59]
	s_add_i32 m0, s46, 0x2000
	s_lshl_b32 s7, s7, 10
	global_load_lds_dwordx4 v[4:5], off
	v_lshl_add_u64 v[4:5], v[2:3], 0, s[48:49]
	s_add_i32 m0, s46, 0x4000
	v_lshl_add_u64 v[2:3], v[2:3], 0, s[50:51]
	global_load_lds_dwordx4 v[4:5], off
	s_add_i32 m0, s46, 0x6000
	v_bfe_u32 v4, v9, 25, 1
	global_load_lds_dwordx4 v[2:3], off
	v_lshl_add_u64 v[2:3], s[44:45], 0, v[0:1]
	s_add_i32 m0, s46, 0x8000
	v_lshl_add_u64 v[2:3], v[2:3], 0, s[58:59]
	global_load_lds_dwordx4 v0, s[44:45]
	s_add_i32 m0, s46, 0xa000
	s_add_u32 s42, s12, s37
	global_load_lds_dwordx4 v[2:3], off
	v_lshlrev_b32_e32 v2, 6, v9
	v_or_b32_e32 v2, v2, v10
	v_lshlrev_b32_e32 v70, 7, v2
	v_add_u32_e32 v5, v2, v4
	v_or_b32_e32 v2, 32, v2
	v_lshlrev_b32_e32 v71, 7, v2
	v_add_u32_e32 v2, v2, v4
	v_ashrrev_i32_e32 v4, 1, v2
	v_ashrrev_i32_e32 v2, 31, v2
	v_lshrrev_b32_e32 v2, 29, v2
	v_add_u32_e32 v2, v4, v2
	v_and_b32_e32 v2, -8, v2
	v_sub_u32_e32 v2, v4, v2
	v_bitop3_b32 v4, v2, v8, 1 bitop3:0x78
	v_lshl_or_b32 v3, v7, 6, v10
	v_ashrrev_i32_e32 v7, 1, v5
	v_ashrrev_i32_e32 v5, 31, v5
	v_lshlrev_b32_e32 v80, 4, v4
	v_lshrrev_b32_e32 v4, 31, v6
	v_lshrrev_b32_e32 v5, 29, v5
	v_lshlrev_b32_e32 v77, 7, v3
	v_add_u32_e32 v6, v3, v4
	v_or_b32_e32 v3, 32, v3
	v_add_u32_e32 v5, v7, v5
	v_lshlrev_b32_e32 v84, 7, v3
	v_add_u32_e32 v3, v3, v4
	v_and_b32_e32 v5, -8, v5
	v_ashrrev_i32_e32 v4, 1, v3
	v_ashrrev_i32_e32 v3, 31, v3
	v_sub_u32_e32 v5, v7, v5
	v_lshrrev_b32_e32 v3, 29, v3
	v_bitop3_b32 v7, v5, v8, 1 bitop3:0x78
	v_add_u32_e32 v3, v4, v3
	v_lshlrev_b32_e32 v76, 4, v7
	v_ashrrev_i32_e32 v7, 1, v6
	v_ashrrev_i32_e32 v6, 31, v6
	v_and_b32_e32 v3, -8, v3
	v_lshrrev_b32_e32 v6, 29, v6
	v_sub_u32_e32 v3, v4, v3
	v_add_u32_e32 v6, v7, v6
	v_bitop3_b32 v4, v3, v8, 1 bitop3:0x78
	v_and_b32_e32 v6, -8, v6
	v_lshlrev_b32_e32 v89, 4, v4
	v_bitop3_b32 v4, v5, v11, 2 bitop3:0x1e
	v_sub_u32_e32 v6, v7, v6
	v_lshlrev_b32_e32 v87, 4, v4
	v_bitop3_b32 v4, v2, v11, 2 bitop3:0x1e
	v_lshlrev_b32_e32 v88, 4, v4
	v_bitop3_b32 v4, v6, v11, 2 bitop3:0x1e
	v_lshlrev_b32_e32 v85, 4, v4
	v_bitop3_b32 v4, v3, v11, 2 bitop3:0x1e
	v_lshlrev_b32_e32 v86, 4, v4
	v_bitop3_b32 v4, v5, v11, 4 bitop3:0x1e
	v_lshlrev_b32_e32 v81, 4, v4
	v_bitop3_b32 v4, v2, v11, 4 bitop3:0x1e
	v_bitop3_b32 v2, v2, v11, 6 bitop3:0x1e
	v_lshlrev_b32_e32 v82, 4, v4
	v_bitop3_b32 v4, v6, v11, 4 bitop3:0x1e
	v_lshlrev_b32_e32 v75, 4, v2
	v_bitop3_b32 v2, v6, v11, 6 bitop3:0x1e
	s_addc_u32 s43, s13, 0
	s_waitcnt vmcnt(0)
	v_lshlrev_b32_e32 v78, 4, v4
	v_bitop3_b32 v4, v3, v11, 4 bitop3:0x1e
	v_lshlrev_b32_e32 v72, 4, v2
	v_bitop3_b32 v2, v3, v11, 6 bitop3:0x1e
	s_add_u32 s30, s40, s30
	v_bitop3_b32 v7, v6, v8, 1 bitop3:0x78
	v_lshlrev_b32_e32 v79, 4, v4
	v_bitop3_b32 v4, v5, v11, 6 bitop3:0x1e
	v_lshlrev_b32_e32 v73, 4, v2
	s_addc_u32 s31, s41, s31
	v_mov_b32_e32 v2, 0
	s_mov_b32 s3, 1
	v_lshlrev_b32_e32 v83, 4, v7
	v_lshlrev_b32_e32 v74, 4, v4
	v_lshl_add_u64 v[66:67], s[42:43], 0, v[0:1]
	v_lshl_add_u64 v[68:69], s[30:31], 0, v[0:1]
	s_mov_b64 s[30:31], 0
	v_mov_b32_e32 v3, v2
	v_mov_b32_e32 v4, v2
	v_mov_b32_e32 v5, v2
	v_mov_b32_e32 v6, v2
	v_mov_b32_e32 v7, v2
	v_mov_b32_e32 v8, v2
	v_mov_b32_e32 v9, v2
	v_mov_b32_e32 v10, v2
	v_mov_b32_e32 v11, v2
	v_mov_b32_e32 v12, v2
	v_mov_b32_e32 v13, v2
	v_mov_b32_e32 v14, v2
	v_mov_b32_e32 v15, v2
	v_mov_b32_e32 v16, v2
	v_mov_b32_e32 v17, v2
	v_mov_b32_e32 v18, v2
	v_mov_b32_e32 v19, v2
	v_mov_b32_e32 v20, v2
	v_mov_b32_e32 v21, v2
	v_mov_b32_e32 v22, v2
	v_mov_b32_e32 v23, v2
	v_mov_b32_e32 v24, v2
	v_mov_b32_e32 v25, v2
	v_mov_b32_e32 v26, v2
	v_mov_b32_e32 v27, v2
	v_mov_b32_e32 v28, v2
	v_mov_b32_e32 v29, v2
	v_mov_b32_e32 v30, v2
	v_mov_b32_e32 v31, v2
	v_mov_b32_e32 v32, v2
	v_mov_b32_e32 v33, v2
	v_mov_b32_e32 v34, v2
	v_mov_b32_e32 v35, v2
	v_mov_b32_e32 v36, v2
	v_mov_b32_e32 v37, v2
	v_mov_b32_e32 v38, v2
	v_mov_b32_e32 v39, v2
	v_mov_b32_e32 v40, v2
	v_mov_b32_e32 v41, v2
	v_mov_b32_e32 v42, v2
	v_mov_b32_e32 v43, v2
	v_mov_b32_e32 v44, v2
	v_mov_b32_e32 v45, v2
	v_mov_b32_e32 v46, v2
	v_mov_b32_e32 v47, v2
	v_mov_b32_e32 v48, v2
	v_mov_b32_e32 v49, v2
	v_mov_b32_e32 v50, v2
	v_mov_b32_e32 v51, v2
	v_mov_b32_e32 v52, v2
	v_mov_b32_e32 v53, v2
	v_mov_b32_e32 v54, v2
	v_mov_b32_e32 v55, v2
	v_mov_b32_e32 v56, v2
	v_mov_b32_e32 v57, v2
	v_mov_b32_e32 v58, v2
	v_mov_b32_e32 v59, v2
	v_mov_b32_e32 v60, v2
	v_mov_b32_e32 v61, v2
	v_mov_b32_e32 v62, v2
	v_mov_b32_e32 v63, v2
	v_mov_b32_e32 v64, v2
	v_mov_b32_e32 v65, v2
	s_waitcnt vmcnt(0) lgkmcnt(0)
	s_barrier
	v_add_u32_e32 v90, v70, v76
	v_add_u32_e32 v94, v71, v80
	ds_read_b128 v[90:93], v90
	v_add_u32_e32 v98, v77, v83
	ds_read_b128 v[94:97], v94
	v_add_u32_e32 v102, v84, v89
	ds_read_b128 v[98:101], v98 offset:32768
	ds_read_b128 v[102:105], v102 offset:32768
	s_bitcmp1_b32 s3, 0
	s_cselect_b32 s42, 0xc000, 0
	s_add_i32 s37, s7, s42
	v_lshl_add_u64 v[122:123], v[66:67], 0, s[30:31]
	v_lshl_add_u64 v[124:125], v[68:69], 0, s[30:31]
	s_add_i32 m0, s37, 0x6000
	v_lshl_add_u64 v[126:127], v[122:123], 0, s[38:39]
	global_load_lds_dwordx4 v[126:127], off
	s_add_i32 m0, s37, 0x8000
	v_lshl_add_u64 v[126:127], v[124:125], 0, s[28:29]
	global_load_lds_dwordx4 v[126:127], off
	s_add_i32 m0, s37, 0xa000
	v_lshl_add_u64 v[126:127], v[124:125], 0, s[24:25]
	global_load_lds_dwordx4 v[126:127], off
; DI f32x16 mfma(bf16x8 a, bf16x8 b, f32x16 c) { return __builtin_amdgcn_mfma_f32_32x32x16_bf16(a, b, c, 0, 0, 0); }
; template <int BK> DI int swz(int row) { constexpr int CPR = BK / 8; return (row / (16 / CPR)) % CPR; }
; DI void wait_vm0() { asm volatile("s_waitcnt vmcnt(0)" ::: "memory"); }
;   DI void pre(int grow0, int gcol0, int lane, int w, char* lds) { xpass(0, grow0, gcol0, lane, w, lds); }
;     ...
;   for (int kt = 0; kt < nk; ++kt) {
;     char* cur = lds + (kt & 1) * STG; char* nxt = lds + ((kt + 1) & 1) * STG;
;     const bool more = kt + 1 < nk;
;     const bf16_t* An = Ag + (kt + 1) * BK; const bf16_t* Bn = Bg + (kt + 1) * BK;
;     if (!more) epi.pre(row0 + wm * 64, col0 + wn * (32 * NTW), lane, w, lds);
;     bf16x8 fa[2][2], fb[2][NTW];
; #pragma unroll
;     for (int mt = 0; mt < 2; ++mt) { int row = wm * 64 + mt * 32 + l31; fa[0][mt] = *(const bf16x8*)(cur + row * (BK * 2) + ((hh ^ swz<BK>(row)) << 4)); }
; #pragma unroll
;     for (int nt = 0; nt < NTW; ++nt) { int row = wn * (32 * NTW) + nt * 32 + l31; fb[0][nt] = *(const bf16x8*)(cur + ABYTES + row * (BK * 2) + ((hh ^ swz<BK>(row)) << 4)); }
; #pragma unroll
;     for (int kk = 0; kk < NKK; ++kk) {
;       if (kk + 1 < NKK) {
;         const int ch = (kk + 1) * 2 + hh;
; #pragma unroll
;         for (int mt = 0; mt < 2; ++mt) { int row = wm * 64 + mt * 32 + l31; fa[(kk + 1) & 1][mt] = *(const bf16x8*)(cur + row * (BK * 2) + ((ch ^ swz<BK>(row)) << 4)); }
; #pragma unroll
;         for (int nt = 0; nt < NTW; ++nt) { int row = wn * (32 * NTW) + nt * 32 + l31; fb[(kk + 1) & 1][nt] = *(const bf16x8*)(cur + ABYTES + row * (BK * 2) + ((ch ^ swz<BK>(row)) << 4)); }
;       }
;       if (more) {
; #pragma unroll
;         for (int q = 0; q < PPK; ++q) {
;           const int pi = kk * PPK + q;
;           if (pi < NPA) stage_piece<BM, BK>(An, lda, nxt, tid, pi, wv);
;           else if (pi < NP) stage_piece<BN, BK>(Bn, ldb, nxt + ABYTES, tid, pi - NPA, wv);
;         }
;       }
;       __builtin_amdgcn_s_setprio(1);
; #pragma unroll
;       for (int mt = 0; mt < 2; ++mt)
; #pragma unroll
;         for (int nt = 0; nt < NTW; ++nt) acc[mt][nt] = mfma(fa[kk & 1][mt], fb[kk & 1][nt], acc[mt][nt]);
;       __builtin_amdgcn_s_setprio(0);
;       __builtin_amdgcn_sched_barrier(0);
;     }
;     wait_vm0();
;     __syncthreads();
.LBB0_388:
	s_bitcmp1_b32 s3, 0
	s_cselect_b32 s100, 0, 0xc000
	s_cselect_b32 s42, 0xc000, 0
	v_add3_u32 v106, s100, v70, v87
	v_add3_u32 v110, s100, v71, v88
	ds_read_b128 v[106:109], v106
	v_add3_u32 v114, s100, v77, v85
	ds_read_b128 v[110:113], v110
	v_add3_u32 v118, s100, v84, v86
	ds_read_b128 v[114:117], v114 offset:32768
	ds_read_b128 v[118:121], v118 offset:32768
	s_waitcnt lgkmcnt(4)
	s_mov_b32 m0, s37
	v_lshl_add_u64 v[126:127], v[122:123], 0, s[28:29]
	v_mfma_f32_32x32x16_bf16 v[50:65], v[90:93], v[98:101], v[50:65]
	global_load_lds_dwordx4 v[126:127], off
	s_add_i32 m0, s37, 0x2000
	v_lshl_add_u64 v[126:127], v[122:123], 0, s[24:25]
	v_mfma_f32_32x32x16_bf16 v[34:49], v[90:93], v[102:105], v[34:49]
	global_load_lds_dwordx4 v[126:127], off
	s_add_i32 m0, s37, 0x4000
	v_lshl_add_u64 v[126:127], v[122:123], 0, s[26:27]
	v_mfma_f32_32x32x16_bf16 v[18:33], v[94:97], v[98:101], v[18:33]
	global_load_lds_dwordx4 v[126:127], off
	v_mfma_f32_32x32x16_bf16 v[2:17], v[94:97], v[102:105], v[2:17]
	v_add3_u32 v90, s100, v70, v81
	v_add3_u32 v94, s100, v71, v82
	ds_read_b128 v[90:93], v90
	v_add3_u32 v98, s100, v77, v78
	ds_read_b128 v[94:97], v94
	v_add3_u32 v102, s100, v84, v79
	ds_read_b128 v[98:101], v98 offset:32768
	ds_read_b128 v[102:105], v102 offset:32768
	s_waitcnt lgkmcnt(4)
	v_mfma_f32_32x32x16_bf16 v[50:65], v[106:109], v[114:117], v[50:65]
	v_mfma_f32_32x32x16_bf16 v[34:49], v[106:109], v[118:121], v[34:49]
	v_mfma_f32_32x32x16_bf16 v[18:33], v[110:113], v[114:117], v[18:33]
	v_mfma_f32_32x32x16_bf16 v[2:17], v[110:113], v[118:121], v[2:17]
	v_add3_u32 v106, s100, v70, v74
	v_add3_u32 v110, s100, v71, v75
	ds_read_b128 v[106:109], v106
	v_add3_u32 v114, s100, v77, v72
	ds_read_b128 v[110:113], v110
	v_add3_u32 v118, s100, v84, v73
	ds_read_b128 v[114:117], v114 offset:32768
	ds_read_b128 v[118:121], v118 offset:32768
	s_waitcnt lgkmcnt(4)
	v_mfma_f32_32x32x16_bf16 v[50:65], v[90:93], v[98:101], v[50:65]
	v_mfma_f32_32x32x16_bf16 v[34:49], v[90:93], v[102:105], v[34:49]
	v_mfma_f32_32x32x16_bf16 v[18:33], v[94:97], v[98:101], v[18:33]
	v_mfma_f32_32x32x16_bf16 v[2:17], v[94:97], v[102:105], v[2:17]
	s_add_u32 s30, s30, 0x80
	s_addc_u32 s31, s31, 0
	s_add_i32 s3, s3, 1
	s_waitcnt vmcnt(0) lgkmcnt(0)
	s_barrier
	v_add3_u32 v90, s42, v70, v76
	v_add3_u32 v94, s42, v71, v80
	ds_read_b128 v[90:93], v90
	v_add3_u32 v98, s42, v77, v83
	ds_read_b128 v[94:97], v94
	v_add3_u32 v102, s42, v84, v89
	ds_read_b128 v[98:101], v98 offset:32768
	ds_read_b128 v[102:105], v102 offset:32768
	s_cmpk_lg_i32 s30, 0x780
	s_cbranch_scc0 .Lk388_exit
	s_add_i32 s37, s7, s100
	v_lshl_add_u64 v[122:123], v[66:67], 0, s[30:31]
	v_lshl_add_u64 v[124:125], v[68:69], 0, s[30:31]
	s_add_i32 m0, s37, 0x6000
	v_lshl_add_u64 v[126:127], v[122:123], 0, s[38:39]
	v_mfma_f32_32x32x16_bf16 v[50:65], v[106:109], v[114:117], v[50:65]
	global_load_lds_dwordx4 v[126:127], off
	s_add_i32 m0, s37, 0x8000
	v_lshl_add_u64 v[126:127], v[124:125], 0, s[28:29]
	v_mfma_f32_32x32x16_bf16 v[34:49], v[106:109], v[118:121], v[34:49]
	global_load_lds_dwordx4 v[126:127], off
	s_add_i32 m0, s37, 0xa000
	v_lshl_add_u64 v[126:127], v[124:125], 0, s[24:25]
	v_mfma_f32_32x32x16_bf16 v[18:33], v[110:113], v[114:117], v[18:33]
	global_load_lds_dwordx4 v[126:127], off
	v_mfma_f32_32x32x16_bf16 v[2:17], v[110:113], v[118:121], v[2:17]
	s_branch .LBB0_388

; DI f32x16 zero16() { f32x16 z; for (int i = 0; i < 16; ++i) z[i] = 0.f; return z; }
; DI int launder(int x) { asm volatile("" : "+v"(x)); return x; }
; template <int BK> DI int swz(int row) { constexpr int CPR = BK / 8; return (row / (16 / CPR)) % CPR; }
; DI void wait_vm0() { asm volatile("s_waitcnt vmcnt(0)" ::: "memory"); }
;   DI void pre(int grow0, int gcol0, int lane, int w, char* lds) { xpass(0, grow0, gcol0, lane, w, lds); }
;     ...
;   const int tid = launder(threadIdx.x), lane = tid & 63, w = tid >> 6, wm = w % WM, wn = w / WM;
;   const int l31 = lane & 31, hh = lane >> 5;
;   f32x16 acc[2][NTW];
; #pragma unroll
;   for (int a = 0; a < 2; ++a)
; #pragma unroll
;     for (int b = 0; b < NTW; ++b) acc[a][b] = zero16();
;   const bf16_t* Ag = A + (size_t)row0 * lda; const bf16_t* Bg = Bt + (size_t)col0 * ldb;
;   const int wv = __builtin_amdgcn_readfirstlane(tid >> 6);
;   __syncthreads();
;   if (!pre) { stage_tile<BM, BK>(Ag, lda, lds, tid); stage_tile<BN, BK>(Bg, ldb, lds + ABYTES, tid); }
;   wait_vm0();
;   __syncthreads();
;   const int nk = K / BK;
;   for (int kt = 0; kt < nk; ++kt) {
;     char* cur = lds + (kt & 1) * STG; char* nxt = lds + ((kt + 1) & 1) * STG;
;     const bool more = kt + 1 < nk;
;     const bf16_t* An = Ag + (kt + 1) * BK; const bf16_t* Bn = Bg + (kt + 1) * BK;
;     if (!more) epi.pre(row0 + wm * 64, col0 + wn * (32 * NTW), lane, w, lds);
;     bf16x8 fa[2][2], fb[2][NTW];
; #pragma unroll
;     for (int mt = 0; mt < 2; ++mt) { int row = wm * 64 + mt * 32 + l31; fa[0][mt] = *(const bf16x8*)(cur + row * (BK * 2) + ((hh ^ swz<BK>(row)) << 4)); }
; #pragma unroll
;     for (int nt = 0; nt < NTW; ++nt) { int row = wn * (32 * NTW) + nt * 32 + l31; fb[0][nt] = *(const bf16x8*)(cur + ABYTES + row * (BK * 2) + ((hh ^ swz<BK>(row)) << 4)); }
.LBB0_438:
	v_lshrrev_b32_e32 v4, 30, v3
	v_add_u32_e32 v4, v3, v4
	v_ashrrev_i32_e32 v4, 2, v4
	v_mul_i32_i24_e32 v5, 4, v4
	v_sub_u32_e32 v3, v3, v5
	v_and_b32_e32 v5, 31, v2
	v_lshlrev_b32_e32 v7, 6, v3
	v_or_b32_e32 v7, v7, v5
	v_bfe_u32 v3, v3, 25, 1
	v_lshlrev_b32_e32 v140, 7, v7
	v_add_u32_e32 v8, v7, v3
	v_or_b32_e32 v7, 32, v7
	v_add_u32_e32 v3, v7, v3
	v_lshlrev_b32_e32 v142, 7, v7
	v_ashrrev_i32_e32 v7, 1, v3
	v_ashrrev_i32_e32 v3, 31, v3
	v_ashrrev_i32_e32 v9, 1, v8
	v_ashrrev_i32_e32 v8, 31, v8
	v_lshrrev_b32_e32 v3, 29, v3
	v_lshrrev_b32_e32 v8, 29, v8
	v_add_u32_e32 v3, v7, v3
	v_add_u32_e32 v8, v9, v8
	v_and_b32_e32 v3, -8, v3
	v_lshrrev_b32_e32 v6, 5, v2
	v_and_b32_e32 v8, -8, v8
	v_sub_u32_e32 v3, v7, v3
	v_lshl_or_b32 v5, v4, 7, v5
	v_sub_u32_e32 v8, v9, v8
	v_bitop3_b32 v7, v3, v6, 1 bitop3:0x78
	v_lshrrev_b32_e32 v4, 31, v4
	v_bitop3_b32 v9, v8, v6, 1 bitop3:0x78
	v_lshlrev_b32_e32 v144, 4, v7
	v_add_u32_e32 v7, v5, v4
	v_lshlrev_b32_e32 v141, 4, v9
	v_ashrrev_i32_e32 v9, 1, v7
	v_ashrrev_i32_e32 v7, 31, v7
	v_lshrrev_b32_e32 v7, 29, v7
	v_add_u32_e32 v7, v9, v7
	v_and_b32_e32 v7, -8, v7
	v_sub_u32_e32 v7, v9, v7
	v_bitop3_b32 v9, v7, v6, 1 bitop3:0x78
	v_lshlrev_b32_e32 v151, 4, v9
	v_or_b32_e32 v9, 32, v5
	v_lshlrev_b32_e32 v152, 7, v9
	v_add_u32_e32 v9, v9, v4
	v_ashrrev_i32_e32 v10, 1, v9
	v_ashrrev_i32_e32 v9, 31, v9
	v_lshrrev_b32_e32 v9, 29, v9
	v_add_u32_e32 v9, v10, v9
	v_and_b32_e32 v9, -8, v9
	v_sub_u32_e32 v9, v10, v9
	v_bitop3_b32 v10, v9, v6, 1 bitop3:0x78
	v_lshlrev_b32_e32 v143, 7, v5
	v_lshlrev_b32_e32 v154, 4, v10
	v_or_b32_e32 v10, 64, v5
	v_or_b32_e32 v5, 0x60, v5
	v_lshlrev_b32_e32 v153, 7, v10
	v_add_u32_e32 v10, v10, v4
	v_add_u32_e32 v4, v5, v4
	v_lshlrev_b32_e32 v156, 7, v5
	v_ashrrev_i32_e32 v5, 1, v4
	v_ashrrev_i32_e32 v4, 31, v4
	v_lshrrev_b32_e32 v4, 29, v4
	v_add_u32_e32 v4, v5, v4
	v_and_b32_e32 v4, -8, v4
	v_sub_u32_e32 v4, v5, v4
	s_lshr_b32 s7, s36, 3
	v_bfe_u32 v2, v2, 5, 1
	v_ashrrev_i32_e32 v11, 1, v10
	v_ashrrev_i32_e32 v10, 31, v10
	v_bitop3_b32 v5, v4, v6, 1 bitop3:0x78
	s_and_b32 s7, s7, 7
	s_lshl_b32 s30, s35, 19
	v_lshrrev_b32_e32 v10, 29, v10
	v_lshlrev_b32_e32 v164, 4, v5
	v_bitop3_b32 v5, v8, v2, 2 bitop3:0x1e
	s_lshl_b32 s7, s7, 19
	s_and_b32 s30, s30, 0x1c00000
	v_add_u32_e32 v10, v11, v10
	v_lshlrev_b32_e32 v161, 4, v5
	v_bitop3_b32 v5, v3, v2, 2 bitop3:0x1e
	s_or_b32 s7, s30, s7
	s_and_b32 s30, s34, 0xffffff00
	v_and_b32_e32 v10, -8, v10
	v_lshlrev_b32_e32 v163, 4, v5
	v_bitop3_b32 v5, v7, v2, 2 bitop3:0x1e
	s_ashr_i32 s31, s30, 31
	v_sub_u32_e32 v10, v11, v10
	v_lshlrev_b32_e32 v159, 4, v5
	v_bitop3_b32 v5, v9, v2, 2 bitop3:0x1e
	s_lshl_b64 s[30:31], s[30:31], 11
	s_lshl_b32 s3, s3, 10
	v_lshlrev_b32_e32 v160, 4, v5
	v_bitop3_b32 v5, v10, v2, 2 bitop3:0x1e
	v_lshlrev_b32_e32 v157, 4, v5
	v_bitop3_b32 v5, v4, v2, 2 bitop3:0x1e
	s_add_u32 s40, s12, s7
	v_lshlrev_b32_e32 v158, 4, v5
	v_bitop3_b32 v5, v8, v2, 4 bitop3:0x1e
	s_addc_u32 s41, s13, 0
	s_waitcnt vmcnt(0)
	s_waitcnt vmcnt(0) lgkmcnt(0)
	s_barrier
	v_lshlrev_b32_e32 v149, 4, v5
	v_bitop3_b32 v5, v3, v2, 4 bitop3:0x1e
	v_lshl_add_u64 v[130:131], s[40:41], 0, v[0:1]
	s_load_dwordx4 s[40:43], s[0:1], 0x1a0
	v_lshlrev_b32_e32 v150, 4, v5
	v_bitop3_b32 v5, v7, v2, 4 bitop3:0x1e
	v_lshlrev_b32_e32 v147, 4, v5
	v_bitop3_b32 v5, v9, v2, 4 bitop3:0x1e
	v_bitop3_b32 v3, v3, v2, 6 bitop3:0x1e
	v_lshlrev_b32_e32 v148, 4, v5
	v_bitop3_b32 v5, v10, v2, 4 bitop3:0x1e
	v_lshlrev_b32_e32 v139, 4, v3
	v_bitop3_b32 v3, v7, v2, 6 bitop3:0x1e
	v_lshlrev_b32_e32 v145, 4, v5
	v_bitop3_b32 v5, v4, v2, 4 bitop3:0x1e
	v_lshlrev_b32_e32 v136, 4, v3
	v_bitop3_b32 v3, v9, v2, 6 bitop3:0x1e
	v_lshlrev_b32_e32 v146, 4, v5
	v_bitop3_b32 v5, v8, v2, 6 bitop3:0x1e
	v_lshlrev_b32_e32 v137, 4, v3
	v_bitop3_b32 v3, v10, v2, 6 bitop3:0x1e
	v_bitop3_b32 v2, v4, v2, 6 bitop3:0x1e
	s_waitcnt lgkmcnt(0)
	s_add_u32 s30, s42, s30
	v_bitop3_b32 v11, v10, v6, 1 bitop3:0x78
	v_lshlrev_b32_e32 v135, 4, v2
	s_addc_u32 s31, s43, s31
	v_mov_b32_e32 v2, 0
	v_lshlrev_b32_e32 v155, 4, v11
	v_lshlrev_b32_e32 v138, 4, v5
	v_lshlrev_b32_e32 v134, 4, v3
	v_lshl_add_u64 v[132:133], s[30:31], 0, v[0:1]
	s_mov_b64 s[30:31], 0
	s_mov_b32 s7, 0x10000
	v_mov_b32_e32 v3, v2
	v_mov_b32_e32 v4, v2
	v_mov_b32_e32 v5, v2
	v_mov_b32_e32 v6, v2
	v_mov_b32_e32 v7, v2
	v_mov_b32_e32 v8, v2
	v_mov_b32_e32 v9, v2
	v_mov_b32_e32 v10, v2
	v_mov_b32_e32 v11, v2
	v_mov_b32_e32 v12, v2
	v_mov_b32_e32 v13, v2
	v_mov_b32_e32 v14, v2
	v_mov_b32_e32 v15, v2
	v_mov_b32_e32 v16, v2
	v_mov_b32_e32 v17, v2
	v_mov_b32_e32 v18, v2
	v_mov_b32_e32 v19, v2
	v_mov_b32_e32 v20, v2
	v_mov_b32_e32 v21, v2
	v_mov_b32_e32 v22, v2
	v_mov_b32_e32 v23, v2
	v_mov_b32_e32 v24, v2
	v_mov_b32_e32 v25, v2
	v_mov_b32_e32 v26, v2
	v_mov_b32_e32 v27, v2
	v_mov_b32_e32 v28, v2
	v_mov_b32_e32 v29, v2
	v_mov_b32_e32 v30, v2
	v_mov_b32_e32 v31, v2
	v_mov_b32_e32 v32, v2
	v_mov_b32_e32 v33, v2
	v_mov_b32_e32 v66, v2
	v_mov_b32_e32 v67, v2
	v_mov_b32_e32 v68, v2
	v_mov_b32_e32 v69, v2
	v_mov_b32_e32 v70, v2
	v_mov_b32_e32 v71, v2
	v_mov_b32_e32 v72, v2
	v_mov_b32_e32 v73, v2
	v_mov_b32_e32 v74, v2
	v_mov_b32_e32 v75, v2
	v_mov_b32_e32 v76, v2
	v_mov_b32_e32 v77, v2
	v_mov_b32_e32 v78, v2
	v_mov_b32_e32 v79, v2
	v_mov_b32_e32 v80, v2
	v_mov_b32_e32 v81, v2
	v_mov_b32_e32 v82, v2
	v_mov_b32_e32 v83, v2
	v_mov_b32_e32 v84, v2
	v_mov_b32_e32 v85, v2
	v_mov_b32_e32 v86, v2
	v_mov_b32_e32 v87, v2
	v_mov_b32_e32 v88, v2
	v_mov_b32_e32 v89, v2
	v_mov_b32_e32 v90, v2
	v_mov_b32_e32 v91, v2
	v_mov_b32_e32 v92, v2
	v_mov_b32_e32 v93, v2
	v_mov_b32_e32 v94, v2
	v_mov_b32_e32 v95, v2
	v_mov_b32_e32 v96, v2
	v_mov_b32_e32 v97, v2
; DI f32x16 zero16() { f32x16 z; for (int i = 0; i < 16; ++i) z[i] = 0.f; return z; }
; template <int BK> DI int swz(int row) { constexpr int CPR = BK / 8; return (row / (16 / CPR)) % CPR; }
; DI void wait_vm0() { asm volatile("s_waitcnt vmcnt(0)" ::: "memory"); }
;     ...
;   f32x16 acc[2][NTW];
; #pragma unroll
;   for (int a = 0; a < 2; ++a)
; #pragma unroll
;     for (int b = 0; b < NTW; ++b) acc[a][b] = zero16();
;   const bf16_t* Ag = A + (size_t)row0 * lda; const bf16_t* Bg = Bt + (size_t)col0 * ldb;
;   const int wv = __builtin_amdgcn_readfirstlane(tid >> 6);
;   __syncthreads();
;   if (!pre) { stage_tile<BM, BK>(Ag, lda, lds, tid); stage_tile<BN, BK>(Bg, ldb, lds + ABYTES, tid); }
;   wait_vm0();
;   __syncthreads();
;   const int nk = K / BK;
;   for (int kt = 0; kt < nk; ++kt) {
;     char* cur = lds + (kt & 1) * STG; char* nxt = lds + ((kt + 1) & 1) * STG;
;     const bool more = kt + 1 < nk;
;     const bf16_t* An = Ag + (kt + 1) * BK; const bf16_t* Bn = Bg + (kt + 1) * BK;
;     if (!more) epi.pre(row0 + wm * 64, col0 + wn * (32 * NTW), lane, w, lds);
;     bf16x8 fa[2][2], fb[2][NTW];
; #pragma unroll
;     for (int mt = 0; mt < 2; ++mt) { int row = wm * 64 + mt * 32 + l31; fa[0][mt] = *(const bf16x8*)(cur + row * (BK * 2) + ((hh ^ swz<BK>(row)) << 4)); }
; #pragma unroll
;     for (int nt = 0; nt < NTW; ++nt) { int row = wn * (32 * NTW) + nt * 32 + l31; fb[0][nt] = *(const bf16x8*)(cur + ABYTES + row * (BK * 2) + ((hh ^ swz<BK>(row)) << 4)); }
; #pragma unroll
;     for (int kk = 0; kk < NKK; ++kk) {
;       if (kk + 1 < NKK) {
;         const int ch = (kk + 1) * 2 + hh;
; #pragma unroll
;         for (int mt = 0; mt < 2; ++mt) { int row = wm * 64 + mt * 32 + l31; fa[(kk + 1) & 1][mt] = *(const bf16x8*)(cur + row * (BK * 2) + ((ch ^ swz<BK>(row)) << 4)); }
; #pragma unroll
;         for (int nt = 0; nt < NTW; ++nt) { int row = wn * (32 * NTW) + nt * 32 + l31; fb[(kk + 1) & 1][nt] = *(const bf16x8*)(cur + ABYTES + row * (BK * 2) + ((ch ^ swz<BK>(row)) << 4)); }
;       }
;       if (more) {
; #pragma unroll
;         for (int q = 0; q < PPK; ++q) {
;           const int pi = kk * PPK + q;
;           if (pi < NPA) stage_piece<BM, BK>(An, lda, nxt, tid, pi, wv);
;           else if (pi < NP) stage_piece<BN, BK>(Bn, ldb, nxt + ABYTES, tid, pi - NPA, wv);
;         }
	v_mov_b32_e32 v34, v2
	v_mov_b32_e32 v35, v2
	v_mov_b32_e32 v36, v2
	v_mov_b32_e32 v37, v2
	v_mov_b32_e32 v38, v2
	v_mov_b32_e32 v39, v2
	v_mov_b32_e32 v40, v2
	v_mov_b32_e32 v41, v2
	v_mov_b32_e32 v42, v2
	v_mov_b32_e32 v43, v2
	v_mov_b32_e32 v44, v2
	v_mov_b32_e32 v45, v2
	v_mov_b32_e32 v46, v2
	v_mov_b32_e32 v47, v2
	v_mov_b32_e32 v48, v2
	v_mov_b32_e32 v49, v2
	v_mov_b32_e32 v50, v2
	v_mov_b32_e32 v51, v2
	v_mov_b32_e32 v52, v2
	v_mov_b32_e32 v53, v2
	v_mov_b32_e32 v54, v2
	v_mov_b32_e32 v55, v2
	v_mov_b32_e32 v56, v2
	v_mov_b32_e32 v57, v2
	v_mov_b32_e32 v58, v2
	v_mov_b32_e32 v59, v2
	v_mov_b32_e32 v60, v2
	v_mov_b32_e32 v61, v2
	v_mov_b32_e32 v62, v2
	v_mov_b32_e32 v63, v2
	v_mov_b32_e32 v64, v2
	v_mov_b32_e32 v65, v2
	v_mov_b32_e32 v98, v2
	v_mov_b32_e32 v99, v2
	v_mov_b32_e32 v100, v2
	v_mov_b32_e32 v101, v2
	v_mov_b32_e32 v102, v2
	v_mov_b32_e32 v103, v2
	v_mov_b32_e32 v104, v2
	v_mov_b32_e32 v105, v2
	v_mov_b32_e32 v106, v2
	v_mov_b32_e32 v107, v2
	v_mov_b32_e32 v108, v2
	v_mov_b32_e32 v109, v2
	v_mov_b32_e32 v110, v2
	v_mov_b32_e32 v111, v2
	v_mov_b32_e32 v112, v2
	v_mov_b32_e32 v113, v2
	v_mov_b32_e32 v114, v2
	v_mov_b32_e32 v115, v2
	v_mov_b32_e32 v116, v2
	v_mov_b32_e32 v117, v2
	v_mov_b32_e32 v118, v2
	v_mov_b32_e32 v119, v2
	v_mov_b32_e32 v120, v2
	v_mov_b32_e32 v121, v2
	v_mov_b32_e32 v122, v2
	v_mov_b32_e32 v123, v2
	v_mov_b32_e32 v124, v2
	v_mov_b32_e32 v125, v2
	v_mov_b32_e32 v126, v2
	v_mov_b32_e32 v127, v2
	v_mov_b32_e32 v128, v2
	v_mov_b32_e32 v129, v2
	v_add_u32_e32 v166, v140, v141
	v_add_u32_e32 v170, v142, v144
	ds_read_b128 v[166:169], v166
	v_add_u32_e32 v174, v143, v151
	ds_read_b128 v[170:173], v170
	v_add_u32_e32 v178, v152, v154
	ds_read_b128 v[174:177], v174 offset:32768
	v_add_u32_e32 v182, v153, v155
	ds_read_b128 v[178:181], v178 offset:32768
	v_add_u32_e32 v186, v156, v164
	ds_read_b128 v[182:185], v182 offset:32768
	ds_read_b128 v[186:189], v186 offset:32768
	s_and_b32 s40, s7, 0x10000
	s_add_i32 s37, s40, s3
	v_lshl_add_u64 v[214:215], v[130:131], 0, s[30:31]
	v_lshl_add_u64 v[226:227], v[132:133], 0, s[30:31]
	s_add_i32 m0, s37, 0x8000
	v_lshl_add_u64 v[228:229], v[226:227], 0, s[28:29]
	global_load_lds_dwordx4 v[228:229], off
	s_add_i32 m0, s37, 0xa000
	v_lshl_add_u64 v[228:229], v[226:227], 0, s[24:25]
	global_load_lds_dwordx4 v[228:229], off
	s_add_i32 m0, s37, 0xc000
	v_lshl_add_u64 v[228:229], v[226:227], 0, s[26:27]
	global_load_lds_dwordx4 v[228:229], off
	s_add_i32 m0, s37, 0xe000
	v_lshl_add_u64 v[228:229], v[226:227], 0, s[38:39]
	global_load_lds_dwordx4 v[228:229], off
; DI f32x16 mfma(bf16x8 a, bf16x8 b, f32x16 c) { return __builtin_amdgcn_mfma_f32_32x32x16_bf16(a, b, c, 0, 0, 0); }
; template <int BK> DI int swz(int row) { constexpr int CPR = BK / 8; return (row / (16 / CPR)) % CPR; }
; DI void wait_vm0() { asm volatile("s_waitcnt vmcnt(0)" ::: "memory"); }
;   DI void pre(int grow0, int gcol0, int lane, int w, char* lds) { xpass(0, grow0, gcol0, lane, w, lds); }
;     ...
;   for (int kt = 0; kt < nk; ++kt) {
;     char* cur = lds + (kt & 1) * STG; char* nxt = lds + ((kt + 1) & 1) * STG;
;     const bool more = kt + 1 < nk;
;     const bf16_t* An = Ag + (kt + 1) * BK; const bf16_t* Bn = Bg + (kt + 1) * BK;
;     if (!more) epi.pre(row0 + wm * 64, col0 + wn * (32 * NTW), lane, w, lds);
;     bf16x8 fa[2][2], fb[2][NTW];
; #pragma unroll
;     for (int mt = 0; mt < 2; ++mt) { int row = wm * 64 + mt * 32 + l31; fa[0][mt] = *(const bf16x8*)(cur + row * (BK * 2) + ((hh ^ swz<BK>(row)) << 4)); }
; #pragma unroll
;     for (int nt = 0; nt < NTW; ++nt) { int row = wn * (32 * NTW) + nt * 32 + l31; fb[0][nt] = *(const bf16x8*)(cur + ABYTES + row * (BK * 2) + ((hh ^ swz<BK>(row)) << 4)); }
; #pragma unroll
;     for (int kk = 0; kk < NKK; ++kk) {
;       if (kk + 1 < NKK) {
;         const int ch = (kk + 1) * 2 + hh;
; #pragma unroll
;         for (int mt = 0; mt < 2; ++mt) { int row = wm * 64 + mt * 32 + l31; fa[(kk + 1) & 1][mt] = *(const bf16x8*)(cur + row * (BK * 2) + ((ch ^ swz<BK>(row)) << 4)); }
; #pragma unroll
;         for (int nt = 0; nt < NTW; ++nt) { int row = wn * (32 * NTW) + nt * 32 + l31; fb[(kk + 1) & 1][nt] = *(const bf16x8*)(cur + ABYTES + row * (BK * 2) + ((ch ^ swz<BK>(row)) << 4)); }
;       }
;       if (more) {
; #pragma unroll
;         for (int q = 0; q < PPK; ++q) {
;           const int pi = kk * PPK + q;
;           if (pi < NPA) stage_piece<BM, BK>(An, lda, nxt, tid, pi, wv);
;           else if (pi < NP) stage_piece<BN, BK>(Bn, ldb, nxt + ABYTES, tid, pi - NPA, wv);
;         }
;       }
;       __builtin_amdgcn_s_setprio(1);
; #pragma unroll
;       for (int mt = 0; mt < 2; ++mt)
; #pragma unroll
;         for (int nt = 0; nt < NTW; ++nt) acc[mt][nt] = mfma(fa[kk & 1][mt], fb[kk & 1][nt], acc[mt][nt]);
;       __builtin_amdgcn_s_setprio(0);
;       __builtin_amdgcn_sched_barrier(0);
;     }
;     wait_vm0();
;     __syncthreads();
.LBB0_439:
	s_and_b32 s40, s7, 0x10000
	s_xor_b32 s100, s40, 0x10000
	v_add3_u32 v190, s100, v140, v161
	v_add3_u32 v194, s100, v142, v163
	ds_read_b128 v[190:193], v190
	v_add3_u32 v198, s100, v143, v159
	ds_read_b128 v[194:197], v194
	v_add3_u32 v202, s100, v152, v160
	ds_read_b128 v[198:201], v198 offset:32768
	v_add3_u32 v206, s100, v153, v157
	ds_read_b128 v[202:205], v202 offset:32768
	v_add3_u32 v210, s100, v156, v158
	ds_read_b128 v[206:209], v206 offset:32768
	ds_read_b128 v[210:213], v210 offset:32768
	s_waitcnt lgkmcnt(6)
	s_mov_b32 m0, s37
	v_lshl_add_u64 v[228:229], v[214:215], 0, s[28:29]
	v_mfma_f32_32x32x16_bf16 v[114:129], v[166:169], v[174:177], v[114:129]
	global_load_lds_dwordx4 v[228:229], off
	s_add_i32 m0, s37, 0x2000
	v_lshl_add_u64 v[228:229], v[214:215], 0, s[24:25]
	v_mfma_f32_32x32x16_bf16 v[98:113], v[166:169], v[178:181], v[98:113]
	v_mfma_f32_32x32x16_bf16 v[50:65], v[166:169], v[182:185], v[50:65]
	global_load_lds_dwordx4 v[228:229], off
	s_add_i32 m0, s37, 0x4000
	v_lshl_add_u64 v[228:229], v[214:215], 0, s[26:27]
	v_mfma_f32_32x32x16_bf16 v[34:49], v[166:169], v[186:189], v[34:49]
	v_mfma_f32_32x32x16_bf16 v[82:97], v[170:173], v[174:177], v[82:97]
	global_load_lds_dwordx4 v[228:229], off
	s_add_i32 m0, s37, 0x6000
	v_lshl_add_u64 v[228:229], v[214:215], 0, s[38:39]
	v_mfma_f32_32x32x16_bf16 v[66:81], v[170:173], v[178:181], v[66:81]
	v_mfma_f32_32x32x16_bf16 v[18:33], v[170:173], v[182:185], v[18:33]
	global_load_lds_dwordx4 v[228:229], off
	v_mfma_f32_32x32x16_bf16 v[2:17], v[170:173], v[186:189], v[2:17]
	v_add3_u32 v166, s100, v140, v149
	v_add3_u32 v170, s100, v142, v150
	ds_read_b128 v[166:169], v166
	v_add3_u32 v174, s100, v143, v147
	ds_read_b128 v[170:173], v170
	v_add3_u32 v178, s100, v152, v148
	ds_read_b128 v[174:177], v174 offset:32768
	v_add3_u32 v182, s100, v153, v145
	ds_read_b128 v[178:181], v178 offset:32768
	v_add3_u32 v186, s100, v156, v146
	ds_read_b128 v[182:185], v182 offset:32768
	ds_read_b128 v[186:189], v186 offset:32768
	s_waitcnt lgkmcnt(6)
	v_mfma_f32_32x32x16_bf16 v[114:129], v[190:193], v[198:201], v[114:129]
	v_mfma_f32_32x32x16_bf16 v[98:113], v[190:193], v[202:205], v[98:113]
	v_mfma_f32_32x32x16_bf16 v[50:65], v[190:193], v[206:209], v[50:65]
	v_mfma_f32_32x32x16_bf16 v[34:49], v[190:193], v[210:213], v[34:49]
	v_mfma_f32_32x32x16_bf16 v[82:97], v[194:197], v[198:201], v[82:97]
	v_mfma_f32_32x32x16_bf16 v[66:81], v[194:197], v[202:205], v[66:81]
	v_mfma_f32_32x32x16_bf16 v[18:33], v[194:197], v[206:209], v[18:33]
	v_mfma_f32_32x32x16_bf16 v[2:17], v[194:197], v[210:213], v[2:17]
	v_add3_u32 v190, s100, v140, v138
	v_add3_u32 v194, s100, v142, v139
	ds_read_b128 v[190:193], v190
	v_add3_u32 v198, s100, v143, v136
	ds_read_b128 v[194:197], v194
	v_add3_u32 v202, s100, v152, v137
	ds_read_b128 v[198:201], v198 offset:32768
	v_add3_u32 v206, s100, v153, v134
	ds_read_b128 v[202:205], v202 offset:32768
	v_add3_u32 v210, s100, v156, v135
	ds_read_b128 v[206:209], v206 offset:32768
	ds_read_b128 v[210:213], v210 offset:32768
	s_waitcnt lgkmcnt(6)
	v_mfma_f32_32x32x16_bf16 v[114:129], v[166:169], v[174:177], v[114:129]
	v_mfma_f32_32x32x16_bf16 v[98:113], v[166:169], v[178:181], v[98:113]
	v_mfma_f32_32x32x16_bf16 v[50:65], v[166:169], v[182:185], v[50:65]
	v_mfma_f32_32x32x16_bf16 v[34:49], v[166:169], v[186:189], v[34:49]
	v_mfma_f32_32x32x16_bf16 v[82:97], v[170:173], v[174:177], v[82:97]
	v_mfma_f32_32x32x16_bf16 v[66:81], v[170:173], v[178:181], v[66:81]
	v_mfma_f32_32x32x16_bf16 v[18:33], v[170:173], v[182:185], v[18:33]
	v_mfma_f32_32x32x16_bf16 v[2:17], v[170:173], v[186:189], v[2:17]
	s_add_u32 s30, s30, 0x80
	s_addc_u32 s31, s31, 0
	s_add_i32 s7, s7, 0x10000
	s_waitcnt vmcnt(0) lgkmcnt(0)
	s_barrier
	v_add3_u32 v166, s40, v140, v141
	v_add3_u32 v170, s40, v142, v144
	ds_read_b128 v[166:169], v166
	v_add3_u32 v174, s40, v143, v151
	ds_read_b128 v[170:173], v170
	v_add3_u32 v178, s40, v152, v154
	ds_read_b128 v[174:177], v174 offset:32768
	v_add3_u32 v182, s40, v153, v155
	ds_read_b128 v[178:181], v178 offset:32768
	v_add3_u32 v186, s40, v156, v164
	ds_read_b128 v[182:185], v182 offset:32768
	ds_read_b128 v[186:189], v186 offset:32768
	s_cmpk_eq_i32 s30, 0x780
	s_cbranch_scc1 .Lk439_exit
	s_add_i32 s37, s100, s3
	v_lshl_add_u64 v[214:215], v[130:131], 0, s[30:31]
	v_lshl_add_u64 v[226:227], v[132:133], 0, s[30:31]
	s_add_i32 m0, s37, 0x8000
	v_lshl_add_u64 v[228:229], v[226:227], 0, s[28:29]
	v_mfma_f32_32x32x16_bf16 v[114:129], v[190:193], v[198:201], v[114:129]
	global_load_lds_dwordx4 v[228:229], off
	s_add_i32 m0, s37, 0xa000
	v_lshl_add_u64 v[228:229], v[226:227], 0, s[24:25]
	v_mfma_f32_32x32x16_bf16 v[98:113], v[190:193], v[202:205], v[98:113]
	v_mfma_f32_32x32x16_bf16 v[50:65], v[190:193], v[206:209], v[50:65]
	global_load_lds_dwordx4 v[228:229], off
	s_add_i32 m0, s37, 0xc000
	v_lshl_add_u64 v[228:229], v[226:227], 0, s[26:27]
	v_mfma_f32_32x32x16_bf16 v[34:49], v[190:193], v[210:213], v[34:49]
	v_mfma_f32_32x32x16_bf16 v[82:97], v[194:197], v[198:201], v[82:97]
	global_load_lds_dwordx4 v[228:229], off
	s_add_i32 m0, s37, 0xe000
	v_lshl_add_u64 v[228:229], v[226:227], 0, s[38:39]
	v_mfma_f32_32x32x16_bf16 v[66:81], v[194:197], v[202:205], v[66:81]
	v_mfma_f32_32x32x16_bf16 v[18:33], v[194:197], v[206:209], v[18:33]
	global_load_lds_dwordx4 v[228:229], off
	v_mfma_f32_32x32x16_bf16 v[2:17], v[194:197], v[210:213], v[2:17]
	s_branch .LBB0_439

; DI f32x16 zero16() { f32x16 z; for (int i = 0; i < 16; ++i) z[i] = 0.f; return z; }
; DI int launder(int x) { asm volatile("" : "+v"(x)); return x; }
; template <int BK> DI int swz(int row) { constexpr int CPR = BK / 8; return (row / (16 / CPR)) % CPR; }
; DI void wait_vm0() { asm volatile("s_waitcnt vmcnt(0)" ::: "memory"); }
; template <int ROWS, int BK>
; DI void stage_tile(const bf16_t* g, int ld, char* l, int tid) {
;   constexpr int CPR = BK / 8, TOT = ROWS * CPR, N = (TOT + NT - 1) / NT;
;   const int row0 = tid / CPR, pc = tid % CPR; const int c = pc ^ swz<BK>(row0);
;   const unsigned voff = (unsigned)(row0 * ld + c * 8) * 2u;
; #pragma unroll
;   for (int i = 0; i < N; ++i) {
;     if (TOT % NT == 0 || tid + i * NT < TOT) {
;       const char* gb = (const char*)g + (size_t)i * (NT / CPR) * ld * 2;
;       __builtin_amdgcn_global_load_lds((const unsigned*)(gb + voff), (__attribute__((address_space(3))) unsigned*)(l + i * NT * 16 + __builtin_amdgcn_readfirstlane(tid >> 6) * 1024), 16, 0, 0);
;     }
;   }
; }
;     ...
;   const int tid = launder(threadIdx.x), lane = tid & 63, w = tid >> 6, wm = w % WM, wn = w / WM;
;   const int l31 = lane & 31, hh = lane >> 5;
;   f32x16 acc[2][NTW];
; #pragma unroll
;   for (int a = 0; a < 2; ++a)
; #pragma unroll
;     for (int b = 0; b < NTW; ++b) acc[a][b] = zero16();
;   const bf16_t* Ag = A + (size_t)row0 * lda; const bf16_t* Bg = Bt + (size_t)col0 * ldb;
;   const int wv = __builtin_amdgcn_readfirstlane(tid >> 6);
;   __syncthreads();
;   if (!pre) { stage_tile<BM, BK>(Ag, lda, lds, tid); stage_tile<BN, BK>(Bg, ldb, lds + ABYTES, tid); }
;   wait_vm0();
;   __syncthreads();
;   const int nk = K / BK;
;   for (int kt = 0; kt < nk; ++kt) {
;     char* cur = lds + (kt & 1) * STG; char* nxt = lds + ((kt + 1) & 1) * STG;
;     const bool more = kt + 1 < nk;
;     const bf16_t* An = Ag + (kt + 1) * BK; const bf16_t* Bn = Bg + (kt + 1) * BK;
;     if (!more) epi.pre(row0 + wm * 64, col0 + wn * (32 * NTW), lane, w, lds);
;     bf16x8 fa[2][2], fb[2][NTW];
; #pragma unroll
;     for (int mt = 0; mt < 2; ++mt) { int row = wm * 64 + mt * 32 + l31; fa[0][mt] = *(const bf16x8*)(cur + row * (BK * 2) + ((hh ^ swz<BK>(row)) << 4)); }
; #pragma unroll
;     for (int nt = 0; nt < NTW; ++nt) { int row = wn * (32 * NTW) + nt * 32 + l31; fb[0][nt] = *(const bf16x8*)(cur + ABYTES + row * (BK * 2) + ((hh ^ swz<BK>(row)) << 4)); }
.LBB0_530:
	v_readlane_b32 s2, v255, 17
	v_readlane_b32 s3, v255, 18
	s_mov_b64 s[6:7], -1
	s_and_b64 vcc, exec, s[2:3]
	s_cbranch_vccz .LBB0_615
	s_waitcnt lgkmcnt(0)
	v_mov_b32_e32 v6, v216
	v_readlane_b32 s2, v255, 46
	v_ashrrev_i32_e32 v2, 31, v6
	v_lshrrev_b32_e32 v3, 29, v2
	v_lshrrev_b32_e32 v2, 28, v2
	v_add_u32_e32 v2, v6, v2
	v_ashrrev_i32_e32 v2, 4, v2
	v_lshrrev_b32_e32 v5, 29, v2
	v_add_u32_e32 v3, v6, v3
	v_add_u32_e32 v5, v2, v5
	v_ashrrev_i32_e32 v4, 3, v3
	v_and_b32_e32 v3, 0xffffff8, v3
	v_and_b32_e32 v5, 0xffffff8, v5
	v_sub_u32_e32 v3, v6, v3
	v_sub_u32_e32 v2, v2, v5
	v_readlane_b32 s7, v255, 26
	v_readlane_b32 s3, v255, 47
	s_add_u32 s2, s42, s2
	v_xor_b32_e32 v2, v2, v3
	v_lshlrev_b32_e32 v3, s7, v4
	v_readfirstlane_b32 s7, v6
	s_addc_u32 s3, s43, s3
	v_readlane_b32 s30, v255, 27
	s_lshl_b32 s7, s7, 4
	v_lshl_add_u32 v2, v2, 4, v3
	v_mov_b32_e32 v3, v1
	v_readlane_b32 s31, v255, 28
	s_and_b32 s7, s7, 0xfffffc00
	v_readlane_b32 s36, v255, 41
	s_waitcnt vmcnt(0)
	v_lshl_add_u64 v[130:131], s[30:31], 0, v[2:3]
	s_mov_b32 m0, s7
	v_readlane_b32 s37, v255, 42
	v_readlane_b32 s40, v255, 43
	s_barrier
	global_load_lds_dwordx4 v2, s[30:31]
	v_lshl_add_u64 v[4:5], v[130:131], 0, s[36:37]
	s_add_i32 m0, s7, 0x2000
	v_readlane_b32 s41, v255, 44
	v_readlane_b32 s34, v255, 48
	global_load_lds_dwordx4 v[4:5], off
	v_lshl_add_u64 v[4:5], v[130:131], 0, s[40:41]
	s_add_i32 m0, s7, 0x4000
	v_readlane_b32 s35, v255, 49
	global_load_lds_dwordx4 v[4:5], off
	s_nop 0
	v_lshl_add_u64 v[4:5], v[130:131], 0, s[34:35]
	s_add_i32 m0, s7, 0x6000
	v_lshl_add_u64 v[132:133], s[2:3], 0, v[2:3]
	global_load_lds_dwordx4 v[4:5], off
	s_add_i32 m0, s7, 0x8000
	v_ashrrev_i32_e32 v134, 6, v6
	global_load_lds_dwordx4 v2, s[2:3]
	v_lshl_add_u64 v[2:3], v[132:133], 0, s[36:37]
	s_add_i32 m0, s7, 0xa000
	v_and_b32_e32 v4, 31, v6
	global_load_lds_dwordx4 v[2:3], off
	v_lshl_add_u64 v[2:3], v[132:133], 0, s[40:41]
	s_add_i32 m0, s7, 0xc000
	v_and_b32_e32 v0, 63, v6
	global_load_lds_dwordx4 v[2:3], off
	v_lshl_add_u64 v[2:3], v[132:133], 0, s[34:35]
	s_add_i32 m0, s7, 0xe000
	v_bfe_u32 v135, v6, 5, 1
	global_load_lds_dwordx4 v[2:3], off
	v_lshrrev_b32_e32 v2, 30, v134
	v_add_u32_e32 v2, v134, v2
	v_ashrrev_i32_e32 v3, 2, v2
	v_mul_i32_i24_e32 v5, 4, v3
	v_sub_u32_e32 v5, v134, v5
	v_lshlrev_b32_e32 v169, 6, v5
	v_lshlrev_b32_e32 v161, 7, v3
	v_or_b32_e32 v3, v169, v4
	v_bfe_u32 v5, v5, 25, 1
	v_lshlrev_b32_e32 v136, 7, v3
	v_add_u32_e32 v6, v3, v5
	v_or_b32_e32 v3, 32, v3
	v_lshlrev_b32_e32 v144, 7, v3
	v_add_u32_e32 v3, v3, v5
	v_ashrrev_i32_e32 v5, 1, v3
	v_ashrrev_i32_e32 v3, 31, v3
	v_ashrrev_i32_e32 v7, 1, v6
	v_ashrrev_i32_e32 v6, 31, v6
	v_lshrrev_b32_e32 v3, 29, v3
	v_lshrrev_b32_e32 v6, 29, v6
	v_add_u32_e32 v3, v5, v3
	v_add_u32_e32 v6, v7, v6
	v_and_b32_e32 v3, -8, v3
	v_and_b32_e32 v6, -8, v6
	v_sub_u32_e32 v3, v5, v3
	v_or_b32_e32 v4, v161, v4
	v_sub_u32_e32 v6, v7, v6
	v_xor_b32_e32 v5, v3, v135
	v_lshrrev_b32_e32 v2, 31, v2
	v_xor_b32_e32 v7, v6, v135
	v_lshlrev_b32_e32 v146, 4, v5
	v_add_u32_e32 v5, v4, v2
	v_lshlrev_b32_e32 v143, 4, v7
	v_ashrrev_i32_e32 v7, 1, v5
	v_ashrrev_i32_e32 v5, 31, v5
	v_lshrrev_b32_e32 v5, 29, v5
	v_add_u32_e32 v5, v7, v5
	v_and_b32_e32 v5, -8, v5
	v_sub_u32_e32 v5, v7, v5
	v_xor_b32_e32 v7, v5, v135
	v_lshlrev_b32_e32 v149, 4, v7
	v_or_b32_e32 v7, 32, v4
	v_lshlrev_b32_e32 v150, 7, v7
	v_add_u32_e32 v7, v7, v2
	v_ashrrev_i32_e32 v8, 1, v7
	v_ashrrev_i32_e32 v7, 31, v7
	v_lshrrev_b32_e32 v7, 29, v7
	v_add_u32_e32 v7, v8, v7
	v_and_b32_e32 v7, -8, v7
	v_sub_u32_e32 v7, v8, v7
	v_xor_b32_e32 v8, v7, v135
	v_lshlrev_b32_e32 v145, 7, v4
	v_lshlrev_b32_e32 v155, 4, v8
	v_or_b32_e32 v8, 64, v4
	v_or_b32_e32 v4, 0x60, v4
	v_lshlrev_b32_e32 v156, 7, v8
	v_add_u32_e32 v8, v8, v2
	v_add_u32_e32 v2, v4, v2
	v_lshlrev_b32_e32 v158, 7, v4
	v_ashrrev_i32_e32 v4, 1, v2
	v_ashrrev_i32_e32 v2, 31, v2
	v_lshrrev_b32_e32 v2, 29, v2
	v_add_u32_e32 v2, v4, v2
	v_and_b32_e32 v2, -8, v2
	v_sub_u32_e32 v2, v4, v2
	v_ashrrev_i32_e32 v9, 1, v8
	v_ashrrev_i32_e32 v8, 31, v8
	v_xor_b32_e32 v4, v2, v135
	v_lshrrev_b32_e32 v8, 29, v8
	v_lshlrev_b32_e32 v168, 4, v4
	v_bitop3_b32 v4, v6, v135, 2 bitop3:0x1e
	v_add_u32_e32 v8, v9, v8
	v_lshlrev_b32_e32 v166, 4, v4
	v_bitop3_b32 v4, v3, v135, 2 bitop3:0x1e
	v_and_b32_e32 v8, -8, v8
	v_lshlrev_b32_e32 v167, 4, v4
	v_bitop3_b32 v4, v5, v135, 2 bitop3:0x1e
	v_sub_u32_e32 v8, v9, v8
	v_lshlrev_b32_e32 v163, 4, v4
	v_bitop3_b32 v4, v7, v135, 2 bitop3:0x1e
	v_lshlrev_b32_e32 v164, 4, v4
	v_bitop3_b32 v4, v8, v135, 2 bitop3:0x1e
	v_lshlrev_b32_e32 v159, 4, v4
	v_bitop3_b32 v4, v2, v135, 2 bitop3:0x1e
	v_lshlrev_b32_e32 v160, 4, v4
	v_bitop3_b32 v4, v6, v135, 4 bitop3:0x1e
	v_lshlrev_b32_e32 v153, 4, v4
	v_bitop3_b32 v4, v3, v135, 4 bitop3:0x1e
	v_lshlrev_b32_e32 v154, 4, v4
	v_bitop3_b32 v4, v5, v135, 4 bitop3:0x1e
	v_lshlrev_b32_e32 v151, 4, v4
	v_bitop3_b32 v4, v7, v135, 4 bitop3:0x1e
	v_bitop3_b32 v3, v3, v135, 6 bitop3:0x1e
	v_lshlrev_b32_e32 v152, 4, v4
	v_bitop3_b32 v4, v8, v135, 4 bitop3:0x1e
	v_lshlrev_b32_e32 v142, 4, v3
	v_bitop3_b32 v3, v5, v135, 6 bitop3:0x1e
	s_waitcnt vmcnt(0)
; DI f32x16 zero16() { f32x16 z; for (int i = 0; i < 16; ++i) z[i] = 0.f; return z; }
; template <int BK> DI int swz(int row) { constexpr int CPR = BK / 8; return (row / (16 / CPR)) % CPR; }
; DI void wait_vm0() { asm volatile("s_waitcnt vmcnt(0)" ::: "memory"); }
;     ...
;   f32x16 acc[2][NTW];
; #pragma unroll
;   for (int a = 0; a < 2; ++a)
; #pragma unroll
;     for (int b = 0; b < NTW; ++b) acc[a][b] = zero16();
;   const bf16_t* Ag = A + (size_t)row0 * lda; const bf16_t* Bg = Bt + (size_t)col0 * ldb;
;   const int wv = __builtin_amdgcn_readfirstlane(tid >> 6);
;   __syncthreads();
;   if (!pre) { stage_tile<BM, BK>(Ag, lda, lds, tid); stage_tile<BN, BK>(Bg, ldb, lds + ABYTES, tid); }
;   wait_vm0();
;   __syncthreads();
;   const int nk = K / BK;
;   for (int kt = 0; kt < nk; ++kt) {
;     char* cur = lds + (kt & 1) * STG; char* nxt = lds + ((kt + 1) & 1) * STG;
;     const bool more = kt + 1 < nk;
;     const bf16_t* An = Ag + (kt + 1) * BK; const bf16_t* Bn = Bg + (kt + 1) * BK;
;     if (!more) epi.pre(row0 + wm * 64, col0 + wn * (32 * NTW), lane, w, lds);
;     bf16x8 fa[2][2], fb[2][NTW];
; #pragma unroll
;     for (int mt = 0; mt < 2; ++mt) { int row = wm * 64 + mt * 32 + l31; fa[0][mt] = *(const bf16x8*)(cur + row * (BK * 2) + ((hh ^ swz<BK>(row)) << 4)); }
; #pragma unroll
;     for (int nt = 0; nt < NTW; ++nt) { int row = wn * (32 * NTW) + nt * 32 + l31; fb[0][nt] = *(const bf16x8*)(cur + ABYTES + row * (BK * 2) + ((hh ^ swz<BK>(row)) << 4)); }
; #pragma unroll
;     for (int kk = 0; kk < NKK; ++kk) {
;       if (kk + 1 < NKK) {
;         const int ch = (kk + 1) * 2 + hh;
; #pragma unroll
;         for (int mt = 0; mt < 2; ++mt) { int row = wm * 64 + mt * 32 + l31; fa[(kk + 1) & 1][mt] = *(const bf16x8*)(cur + row * (BK * 2) + ((ch ^ swz<BK>(row)) << 4)); }
; #pragma unroll
;         for (int nt = 0; nt < NTW; ++nt) { int row = wn * (32 * NTW) + nt * 32 + l31; fb[(kk + 1) & 1][nt] = *(const bf16x8*)(cur + ABYTES + row * (BK * 2) + ((ch ^ swz<BK>(row)) << 4)); }
;       }
;       if (more) {
; #pragma unroll
;         for (int q = 0; q < PPK; ++q) {
;           const int pi = kk * PPK + q;
;           if (pi < NPA) stage_piece<BM, BK>(An, lda, nxt, tid, pi, wv);
;           else if (pi < NP) stage_piece<BN, BK>(Bn, ldb, nxt + ABYTES, tid, pi - NPA, wv);
;         }
	v_lshlrev_b32_e32 v147, 4, v4
	v_bitop3_b32 v4, v2, v135, 4 bitop3:0x1e
	v_lshlrev_b32_e32 v139, 4, v3
	v_bitop3_b32 v3, v7, v135, 6 bitop3:0x1e
	v_bitop3_b32 v2, v2, v135, 6 bitop3:0x1e
	v_readfirstlane_b32 s6, v134
	v_xor_b32_e32 v9, v8, v135
	v_lshlrev_b32_e32 v148, 4, v4
	v_bitop3_b32 v4, v6, v135, 6 bitop3:0x1e
	v_lshlrev_b32_e32 v140, 4, v3
	v_bitop3_b32 v3, v8, v135, 6 bitop3:0x1e
	v_lshlrev_b32_e32 v138, 4, v2
	v_mov_b32_e32 v2, 0
	s_lshl_b32 s2, s6, 10
	s_mov_b32 s92, 64
	v_lshlrev_b32_e32 v157, 4, v9
	v_lshlrev_b32_e32 v141, 4, v4
	v_lshlrev_b32_e32 v137, 4, v3
	s_mov_b32 s3, 0x10000
	v_readlane_b32 s6, v255, 45
	v_mov_b32_e32 v3, v2
	v_mov_b32_e32 v4, v2
	v_mov_b32_e32 v5, v2
	v_mov_b32_e32 v6, v2
	v_mov_b32_e32 v7, v2
	v_mov_b32_e32 v8, v2
	v_mov_b32_e32 v9, v2
	v_mov_b32_e32 v10, v2
	v_mov_b32_e32 v11, v2
	v_mov_b32_e32 v12, v2
	v_mov_b32_e32 v13, v2
	v_mov_b32_e32 v14, v2
	v_mov_b32_e32 v15, v2
	v_mov_b32_e32 v16, v2
	v_mov_b32_e32 v17, v2
	v_mov_b32_e32 v18, v2
	v_mov_b32_e32 v19, v2
	v_mov_b32_e32 v20, v2
	v_mov_b32_e32 v21, v2
	v_mov_b32_e32 v22, v2
	v_mov_b32_e32 v23, v2
	v_mov_b32_e32 v24, v2
	v_mov_b32_e32 v25, v2
	v_mov_b32_e32 v26, v2
	v_mov_b32_e32 v27, v2
	v_mov_b32_e32 v28, v2
	v_mov_b32_e32 v29, v2
	v_mov_b32_e32 v30, v2
	v_mov_b32_e32 v31, v2
	v_mov_b32_e32 v32, v2
	v_mov_b32_e32 v33, v2
	v_mov_b32_e32 v34, v2
	v_mov_b32_e32 v35, v2
	v_mov_b32_e32 v36, v2
	v_mov_b32_e32 v37, v2
	v_mov_b32_e32 v38, v2
	v_mov_b32_e32 v39, v2
	v_mov_b32_e32 v40, v2
	v_mov_b32_e32 v41, v2
	v_mov_b32_e32 v42, v2
	v_mov_b32_e32 v43, v2
	v_mov_b32_e32 v44, v2
	v_mov_b32_e32 v45, v2
	v_mov_b32_e32 v46, v2
	v_mov_b32_e32 v47, v2
	v_mov_b32_e32 v48, v2
	v_mov_b32_e32 v49, v2
	v_mov_b32_e32 v50, v2
	v_mov_b32_e32 v51, v2
	v_mov_b32_e32 v52, v2
	v_mov_b32_e32 v53, v2
	v_mov_b32_e32 v54, v2
	v_mov_b32_e32 v55, v2
	v_mov_b32_e32 v56, v2
	v_mov_b32_e32 v57, v2
	v_mov_b32_e32 v58, v2
	v_mov_b32_e32 v59, v2
	v_mov_b32_e32 v60, v2
	v_mov_b32_e32 v61, v2
	v_mov_b32_e32 v62, v2
	v_mov_b32_e32 v63, v2
	v_mov_b32_e32 v64, v2
	v_mov_b32_e32 v65, v2
	v_mov_b32_e32 v66, v2
	v_mov_b32_e32 v67, v2
	v_mov_b32_e32 v68, v2
	v_mov_b32_e32 v69, v2
	v_mov_b32_e32 v70, v2
	v_mov_b32_e32 v71, v2
	v_mov_b32_e32 v72, v2
	v_mov_b32_e32 v73, v2
	v_mov_b32_e32 v74, v2
	v_mov_b32_e32 v75, v2
	v_mov_b32_e32 v76, v2
	v_mov_b32_e32 v77, v2
	v_mov_b32_e32 v78, v2
	v_mov_b32_e32 v79, v2
	v_mov_b32_e32 v80, v2
	v_mov_b32_e32 v81, v2
	v_mov_b32_e32 v82, v2
	v_mov_b32_e32 v83, v2
	v_mov_b32_e32 v84, v2
	v_mov_b32_e32 v85, v2
	v_mov_b32_e32 v86, v2
	v_mov_b32_e32 v87, v2
	v_mov_b32_e32 v88, v2
	v_mov_b32_e32 v89, v2
	v_mov_b32_e32 v90, v2
	v_mov_b32_e32 v91, v2
	v_mov_b32_e32 v92, v2
	v_mov_b32_e32 v93, v2
	v_mov_b32_e32 v94, v2
	v_mov_b32_e32 v95, v2
	v_mov_b32_e32 v96, v2
	v_mov_b32_e32 v97, v2
	v_mov_b32_e32 v98, v2
	v_mov_b32_e32 v99, v2
	v_mov_b32_e32 v100, v2
	v_mov_b32_e32 v101, v2
	v_mov_b32_e32 v102, v2
	v_mov_b32_e32 v103, v2
	v_mov_b32_e32 v104, v2
	v_mov_b32_e32 v105, v2
	v_mov_b32_e32 v106, v2
	v_mov_b32_e32 v107, v2
	v_mov_b32_e32 v108, v2
	v_mov_b32_e32 v109, v2
	v_mov_b32_e32 v110, v2
	v_mov_b32_e32 v111, v2
	v_mov_b32_e32 v112, v2
	v_mov_b32_e32 v113, v2
	v_mov_b32_e32 v114, v2
	v_mov_b32_e32 v115, v2
	v_mov_b32_e32 v116, v2
	v_mov_b32_e32 v117, v2
	v_mov_b32_e32 v118, v2
	v_mov_b32_e32 v119, v2
	v_mov_b32_e32 v120, v2
	v_mov_b32_e32 v121, v2
	v_mov_b32_e32 v122, v2
	v_mov_b32_e32 v123, v2
	v_mov_b32_e32 v124, v2
	v_mov_b32_e32 v125, v2
	v_mov_b32_e32 v126, v2
	v_mov_b32_e32 v127, v2
	v_mov_b32_e32 v128, v2
	v_mov_b32_e32 v129, v2
	s_waitcnt vmcnt(0) lgkmcnt(0)
	s_barrier
	v_add_u32_e32 v170, v136, v143
	v_add_u32_e32 v174, v144, v146
	ds_read_b128 v[170:173], v170
	v_add_u32_e32 v178, v145, v149
	ds_read_b128 v[174:177], v174
	v_add_u32_e32 v182, v150, v155
	ds_read_b128 v[178:181], v178 offset:32768
	v_add_u32_e32 v186, v156, v157
	ds_read_b128 v[182:185], v182 offset:32768
	v_add_u32_e32 v190, v158, v168
	ds_read_b128 v[186:189], v186 offset:32768
	ds_read_b128 v[190:193], v190 offset:32768
	s_and_b32 s7, s3, 0x10000
	s_add_i32 s101, s7, s2
	s_lshl_b64 s[30:31], s[92:93], 1
	v_lshl_add_u64 v[230:231], v[130:131], 0, s[30:31]
	v_lshl_add_u64 v[214:215], v[132:133], 0, s[30:31]
	s_add_i32 m0, s101, 0x8000
	v_mov_b64_e32 v[232:233], v[214:215]
	global_load_lds_dwordx4 v[232:233], off
	s_add_i32 m0, s101, 0xa000
	v_lshl_add_u64 v[232:233], v[214:215], 0, s[36:37]
	global_load_lds_dwordx4 v[232:233], off
	s_add_i32 m0, s101, 0xc000
	v_lshl_add_u64 v[232:233], v[214:215], 0, s[40:41]
	global_load_lds_dwordx4 v[232:233], off
	s_add_i32 m0, s101, 0xe000
	v_lshl_add_u64 v[232:233], v[214:215], 0, s[34:35]
	global_load_lds_dwordx4 v[232:233], off
; DI f32x16 mfma(bf16x8 a, bf16x8 b, f32x16 c) { return __builtin_amdgcn_mfma_f32_32x32x16_bf16(a, b, c, 0, 0, 0); }
; template <int BK> DI int swz(int row) { constexpr int CPR = BK / 8; return (row / (16 / CPR)) % CPR; }
; DI void wait_vm0() { asm volatile("s_waitcnt vmcnt(0)" ::: "memory"); }
;   DI void pre(int grow0, int gcol0, int lane, int w, char* lds) { xpass(0, grow0, gcol0, lane, w, lds); }
;     ...
;   for (int kt = 0; kt < nk; ++kt) {
;     char* cur = lds + (kt & 1) * STG; char* nxt = lds + ((kt + 1) & 1) * STG;
;     const bool more = kt + 1 < nk;
;     const bf16_t* An = Ag + (kt + 1) * BK; const bf16_t* Bn = Bg + (kt + 1) * BK;
;     if (!more) epi.pre(row0 + wm * 64, col0 + wn * (32 * NTW), lane, w, lds);
;     bf16x8 fa[2][2], fb[2][NTW];
; #pragma unroll
;     for (int mt = 0; mt < 2; ++mt) { int row = wm * 64 + mt * 32 + l31; fa[0][mt] = *(const bf16x8*)(cur + row * (BK * 2) + ((hh ^ swz<BK>(row)) << 4)); }
; #pragma unroll
;     for (int nt = 0; nt < NTW; ++nt) { int row = wn * (32 * NTW) + nt * 32 + l31; fb[0][nt] = *(const bf16x8*)(cur + ABYTES + row * (BK * 2) + ((hh ^ swz<BK>(row)) << 4)); }
; #pragma unroll
;     for (int kk = 0; kk < NKK; ++kk) {
;       if (kk + 1 < NKK) {
;         const int ch = (kk + 1) * 2 + hh;
; #pragma unroll
;         for (int mt = 0; mt < 2; ++mt) { int row = wm * 64 + mt * 32 + l31; fa[(kk + 1) & 1][mt] = *(const bf16x8*)(cur + row * (BK * 2) + ((ch ^ swz<BK>(row)) << 4)); }
; #pragma unroll
;         for (int nt = 0; nt < NTW; ++nt) { int row = wn * (32 * NTW) + nt * 32 + l31; fb[(kk + 1) & 1][nt] = *(const bf16x8*)(cur + ABYTES + row * (BK * 2) + ((ch ^ swz<BK>(row)) << 4)); }
;       }
;       if (more) {
; #pragma unroll
;         for (int q = 0; q < PPK; ++q) {
;           const int pi = kk * PPK + q;
;           if (pi < NPA) stage_piece<BM, BK>(An, lda, nxt, tid, pi, wv);
;           else if (pi < NP) stage_piece<BN, BK>(Bn, ldb, nxt + ABYTES, tid, pi - NPA, wv);
;         }
;       }
;       __builtin_amdgcn_s_setprio(1);
; #pragma unroll
;       for (int mt = 0; mt < 2; ++mt)
; #pragma unroll
;         for (int nt = 0; nt < NTW; ++nt) acc[mt][nt] = mfma(fa[kk & 1][mt], fb[kk & 1][nt], acc[mt][nt]);
;       __builtin_amdgcn_s_setprio(0);
;       __builtin_amdgcn_sched_barrier(0);
;     }
;     wait_vm0();
;     __syncthreads();
.LBB0_532:
	s_and_b32 s7, s3, 0x10000
	s_xor_b32 s100, s7, 0x10000
	v_add3_u32 v194, s100, v136, v166
	v_add3_u32 v198, s100, v144, v167
	ds_read_b128 v[194:197], v194
	v_add3_u32 v202, s100, v145, v163
	ds_read_b128 v[198:201], v198
	v_add3_u32 v206, s100, v150, v164
	ds_read_b128 v[202:205], v202 offset:32768
	v_add3_u32 v210, s100, v156, v159
	ds_read_b128 v[206:209], v206 offset:32768
	v_add3_u32 v226, s100, v158, v160
	ds_read_b128 v[210:213], v210 offset:32768
	ds_read_b128 v[226:229], v226 offset:32768
	s_waitcnt lgkmcnt(6)
	s_mov_b32 m0, s101
	v_mov_b64_e32 v[232:233], v[230:231]
	v_mfma_f32_32x32x16_bf16 v[114:129], v[170:173], v[178:181], v[114:129]
	global_load_lds_dwordx4 v[232:233], off
	v_mfma_f32_32x32x16_bf16 v[98:113], v[170:173], v[182:185], v[98:113]
	s_add_i32 m0, s101, 0x2000
	v_lshl_add_u64 v[232:233], v[230:231], 0, s[36:37]
	v_mfma_f32_32x32x16_bf16 v[82:97], v[170:173], v[186:189], v[82:97]
	global_load_lds_dwordx4 v[232:233], off
	v_mfma_f32_32x32x16_bf16 v[66:81], v[170:173], v[190:193], v[66:81]
	s_add_i32 m0, s101, 0x4000
	v_lshl_add_u64 v[232:233], v[230:231], 0, s[40:41]
	v_mfma_f32_32x32x16_bf16 v[50:65], v[174:177], v[178:181], v[50:65]
	global_load_lds_dwordx4 v[232:233], off
	v_mfma_f32_32x32x16_bf16 v[34:49], v[174:177], v[182:185], v[34:49]
	s_add_i32 m0, s101, 0x6000
	v_lshl_add_u64 v[232:233], v[230:231], 0, s[34:35]
	v_mfma_f32_32x32x16_bf16 v[18:33], v[174:177], v[186:189], v[18:33]
	global_load_lds_dwordx4 v[232:233], off
	v_mfma_f32_32x32x16_bf16 v[2:17], v[174:177], v[190:193], v[2:17]
	v_add3_u32 v170, s100, v136, v153
	v_add3_u32 v174, s100, v144, v154
	ds_read_b128 v[170:173], v170
	v_add3_u32 v178, s100, v145, v151
	ds_read_b128 v[174:177], v174
	v_add3_u32 v182, s100, v150, v152
	ds_read_b128 v[178:181], v178 offset:32768
	v_add3_u32 v186, s100, v156, v147
	ds_read_b128 v[182:185], v182 offset:32768
	v_add3_u32 v190, s100, v158, v148
	ds_read_b128 v[186:189], v186 offset:32768
	ds_read_b128 v[190:193], v190 offset:32768
	s_waitcnt lgkmcnt(6)
	v_mfma_f32_32x32x16_bf16 v[114:129], v[194:197], v[202:205], v[114:129]
	v_mfma_f32_32x32x16_bf16 v[98:113], v[194:197], v[206:209], v[98:113]
	v_mfma_f32_32x32x16_bf16 v[82:97], v[194:197], v[210:213], v[82:97]
	v_mfma_f32_32x32x16_bf16 v[66:81], v[194:197], v[226:229], v[66:81]
	v_mfma_f32_32x32x16_bf16 v[50:65], v[198:201], v[202:205], v[50:65]
	v_mfma_f32_32x32x16_bf16 v[34:49], v[198:201], v[206:209], v[34:49]
	v_mfma_f32_32x32x16_bf16 v[18:33], v[198:201], v[210:213], v[18:33]
	v_mfma_f32_32x32x16_bf16 v[2:17], v[198:201], v[226:229], v[2:17]
	v_add3_u32 v194, s100, v136, v141
	v_add3_u32 v198, s100, v144, v142
	ds_read_b128 v[194:197], v194
	v_add3_u32 v202, s100, v145, v139
	ds_read_b128 v[198:201], v198
	v_add3_u32 v206, s100, v150, v140
	ds_read_b128 v[202:205], v202 offset:32768
	v_add3_u32 v210, s100, v156, v137
	ds_read_b128 v[206:209], v206 offset:32768
	v_add3_u32 v226, s100, v158, v138
	ds_read_b128 v[210:213], v210 offset:32768
	ds_read_b128 v[226:229], v226 offset:32768
	s_waitcnt lgkmcnt(6)
	v_mfma_f32_32x32x16_bf16 v[114:129], v[170:173], v[178:181], v[114:129]
	v_mfma_f32_32x32x16_bf16 v[98:113], v[170:173], v[182:185], v[98:113]
	v_mfma_f32_32x32x16_bf16 v[82:97], v[170:173], v[186:189], v[82:97]
	v_mfma_f32_32x32x16_bf16 v[66:81], v[170:173], v[190:193], v[66:81]
	v_mfma_f32_32x32x16_bf16 v[50:65], v[174:177], v[178:181], v[50:65]
	v_mfma_f32_32x32x16_bf16 v[34:49], v[174:177], v[182:185], v[34:49]
	v_mfma_f32_32x32x16_bf16 v[18:33], v[174:177], v[186:189], v[18:33]
	v_mfma_f32_32x32x16_bf16 v[2:17], v[174:177], v[190:193], v[2:17]
	s_add_i32 s6, s6, -1
	s_add_i32 s92, s92, 64
	s_add_i32 s3, s3, 0x10000
	s_waitcnt vmcnt(0) lgkmcnt(0)
	s_barrier
	v_add3_u32 v170, s7, v136, v143
	v_add3_u32 v174, s7, v144, v146
	ds_read_b128 v[170:173], v170
	v_add3_u32 v178, s7, v145, v149
	ds_read_b128 v[174:177], v174
	v_add3_u32 v182, s7, v150, v155
	ds_read_b128 v[178:181], v178 offset:32768
	v_add3_u32 v186, s7, v156, v157
	ds_read_b128 v[182:185], v182 offset:32768
	v_add3_u32 v190, s7, v158, v168
	ds_read_b128 v[186:189], v186 offset:32768
	ds_read_b128 v[190:193], v190 offset:32768
	s_cmp_lg_u32 s6, 0
	s_cbranch_scc0 .Lk532_exit
	s_add_i32 s101, s100, s2
	s_lshl_b64 s[30:31], s[92:93], 1
	v_lshl_add_u64 v[230:231], v[130:131], 0, s[30:31]
	v_lshl_add_u64 v[214:215], v[132:133], 0, s[30:31]
	s_add_i32 m0, s101, 0x8000
	v_mov_b64_e32 v[232:233], v[214:215]
	v_mfma_f32_32x32x16_bf16 v[114:129], v[194:197], v[202:205], v[114:129]
	global_load_lds_dwordx4 v[232:233], off
	v_mfma_f32_32x32x16_bf16 v[98:113], v[194:197], v[206:209], v[98:113]
	s_add_i32 m0, s101, 0xa000
	v_lshl_add_u64 v[232:233], v[214:215], 0, s[36:37]
	v_mfma_f32_32x32x16_bf16 v[82:97], v[194:197], v[210:213], v[82:97]
	global_load_lds_dwordx4 v[232:233], off
	v_mfma_f32_32x32x16_bf16 v[66:81], v[194:197], v[226:229], v[66:81]
	s_add_i32 m0, s101, 0xc000
	v_lshl_add_u64 v[232:233], v[214:215], 0, s[40:41]
	v_mfma_f32_32x32x16_bf16 v[50:65], v[198:201], v[202:205], v[50:65]
	global_load_lds_dwordx4 v[232:233], off
	v_mfma_f32_32x32x16_bf16 v[34:49], v[198:201], v[206:209], v[34:49]
	s_add_i32 m0, s101, 0xe000
	v_lshl_add_u64 v[232:233], v[214:215], 0, s[34:35]
	v_mfma_f32_32x32x16_bf16 v[18:33], v[198:201], v[210:213], v[18:33]
	global_load_lds_dwordx4 v[232:233], off
	v_mfma_f32_32x32x16_bf16 v[2:17], v[198:201], v[226:229], v[2:17]
	s_branch .LBB0_532

; DI f32x16 zero16() { f32x16 z; for (int i = 0; i < 16; ++i) z[i] = 0.f; return z; }
; DI int launder(int x) { asm volatile("" : "+v"(x)); return x; }
; template <int BK> DI int swz(int row) { constexpr int CPR = BK / 8; return (row / (16 / CPR)) % CPR; }
; DI void wait_vm0() { asm volatile("s_waitcnt vmcnt(0)" ::: "memory"); }
;   DI void pre(int grow0, int gcol0, int lane, int w, char* lds) { xpass(0, grow0, gcol0, lane, w, lds); }
;     ...
;   const int tid = launder(threadIdx.x), lane = tid & 63, w = tid >> 6, wm = w % WM, wn = w / WM;
;   const int l31 = lane & 31, hh = lane >> 5;
;   f32x16 acc[2][NTW];
; #pragma unroll
;   for (int a = 0; a < 2; ++a)
; #pragma unroll
;     for (int b = 0; b < NTW; ++b) acc[a][b] = zero16();
;   const bf16_t* Ag = A + (size_t)row0 * lda; const bf16_t* Bg = Bt + (size_t)col0 * ldb;
;   const int wv = __builtin_amdgcn_readfirstlane(tid >> 6);
;   __syncthreads();
;   if (!pre) { stage_tile<BM, BK>(Ag, lda, lds, tid); stage_tile<BN, BK>(Bg, ldb, lds + ABYTES, tid); }
;   wait_vm0();
;   __syncthreads();
;   const int nk = K / BK;
;   for (int kt = 0; kt < nk; ++kt) {
;     char* cur = lds + (kt & 1) * STG; char* nxt = lds + ((kt + 1) & 1) * STG;
;     const bool more = kt + 1 < nk;
;     const bf16_t* An = Ag + (kt + 1) * BK; const bf16_t* Bn = Bg + (kt + 1) * BK;
;     if (!more) epi.pre(row0 + wm * 64, col0 + wn * (32 * NTW), lane, w, lds);
;     bf16x8 fa[2][2], fb[2][NTW];
; #pragma unroll
;     for (int mt = 0; mt < 2; ++mt) { int row = wm * 64 + mt * 32 + l31; fa[0][mt] = *(const bf16x8*)(cur + row * (BK * 2) + ((hh ^ swz<BK>(row)) << 4)); }
; #pragma unroll
;     for (int nt = 0; nt < NTW; ++nt) { int row = wn * (32 * NTW) + nt * 32 + l31; fb[0][nt] = *(const bf16x8*)(cur + ABYTES + row * (BK * 2) + ((hh ^ swz<BK>(row)) << 4)); }
; __global__ void __launch_bounds__(NT) fwd_megakernel(Params p) {
;     ...
;         for (int t = blockIdx.x; t < 256; t += gridDim.x) {
;           int layer = t >> 6, pm = t & 7, pn = (t >> 3) & 7;
;           EpiXkv e{p.Kx + (size_t)layer * 2048 * D_, p.Vxt + (size_t)layer * 32 * 256 * 256};
;           gemm_tile<4, 64>(p.memb, D_, p.wxkv[layer], D_, D_, pm * 256, pn * 256, lds, e);
.LBB0_626:
	s_lshl_b32 s2, s37, 11
	s_ashr_i32 s6, s40, 6
	s_and_b32 s41, s2, 0x380000
	s_lshl_b32 s2, s36, 11
	s_ashr_i32 s7, s6, 31
	s_and_b32 s35, s2, 0x380000
	s_lshl_b64 s[2:3], s[6:7], 3
	s_add_u32 s2, s0, s2
	s_addc_u32 s3, s1, s3
	v_mov_b32_e32 v4, v216
	s_load_dwordx2 s[30:31], s[2:3], 0x1d8
	s_lshl_b32 s2, s40, 8
	s_and_b32 s2, s2, 0x700
	v_ashrrev_i32_e32 v0, 6, v4
	s_lshl_b32 s3, s40, 5
	v_lshrrev_b32_e32 v2, 30, v0
	s_and_b32 s3, s3, 0x700
	s_waitcnt lgkmcnt(0)
	v_add_u32_e32 v6, v0, v2
	s_lshl_b32 s34, s2, 11
	v_ashrrev_i32_e32 v7, 2, v6
	s_add_u32 s42, s14, s34
	v_mul_i32_i24_e32 v2, 4, v7
	s_addc_u32 s43, s15, 0
	s_lshl_b32 s34, s3, 11
	v_sub_u32_e32 v9, v0, v2
	s_add_u32 s44, s30, s34
	v_readfirstlane_b32 s34, v0
	v_ashrrev_i32_e32 v0, 31, v4
	v_lshrrev_b32_e32 v2, 29, v0
	v_lshrrev_b32_e32 v0, 28, v0
	v_add_u32_e32 v0, v4, v0
	v_ashrrev_i32_e32 v0, 4, v0
	v_lshrrev_b32_e32 v5, 29, v0
	v_add_u32_e32 v2, v4, v2
	v_add_u32_e32 v5, v0, v5
	v_and_b32_e32 v3, 0xffffff8, v2
	v_and_b32_e32 v5, 0xffffff8, v5
	v_sub_u32_e32 v3, v4, v3
	v_sub_u32_e32 v0, v0, v5
	v_lshlrev_b32_e32 v2, 8, v2
	v_readfirstlane_b32 s46, v4
	s_addc_u32 s45, s31, 0
	v_xor_b32_e32 v0, v0, v3
	v_and_b32_e32 v2, 0xfffff800, v2
	s_lshl_b32 s46, s46, 4
	v_lshl_add_u32 v0, v0, 4, v2
	s_and_b32 s46, s46, 0xfffffc00
	v_lshl_add_u64 v[2:3], s[42:43], 0, v[0:1]
	s_mov_b32 m0, s46
	v_lshrrev_b32_e32 v8, 5, v4
	v_and_b32_e32 v10, 31, v4
	v_bfe_u32 v11, v4, 5, 1
	s_waitcnt vmcnt(0)
	s_barrier
	global_load_lds_dwordx4 v0, s[42:43]
	v_lshl_add_u64 v[4:5], v[2:3], 0, s[58:59]
	s_add_i32 m0, s46, 0x2000
	s_lshl_b32 s34, s34, 10
	global_load_lds_dwordx4 v[4:5], off
	v_lshl_add_u64 v[4:5], v[2:3], 0, s[48:49]
	s_add_i32 m0, s46, 0x4000
	v_lshl_add_u64 v[2:3], v[2:3], 0, s[50:51]
	global_load_lds_dwordx4 v[4:5], off
	s_add_i32 m0, s46, 0x6000
	s_nop 0
	global_load_lds_dwordx4 v[2:3], off
	v_lshl_add_u64 v[2:3], s[44:45], 0, v[0:1]
	s_add_i32 m0, s46, 0x8000
	v_lshl_add_u64 v[4:5], v[2:3], 0, s[58:59]
	global_load_lds_dwordx4 v0, s[44:45]
	s_add_i32 m0, s46, 0xa000
	s_nop 0
	global_load_lds_dwordx4 v[4:5], off
	v_lshl_add_u64 v[4:5], v[2:3], 0, s[48:49]
	s_add_i32 m0, s46, 0xc000
	v_lshl_add_u64 v[2:3], v[2:3], 0, s[50:51]
	global_load_lds_dwordx4 v[4:5], off
	s_add_i32 m0, s46, 0xe000
	v_bfe_u32 v4, v9, 25, 1
	global_load_lds_dwordx4 v[2:3], off
	v_lshlrev_b32_e32 v2, 6, v9
	v_or_b32_e32 v2, v2, v10
	v_lshlrev_b32_e32 v136, 7, v2
	v_add_u32_e32 v5, v2, v4
	v_or_b32_e32 v2, 32, v2
	v_lshlrev_b32_e32 v142, 7, v2
	v_add_u32_e32 v2, v2, v4
	v_ashrrev_i32_e32 v4, 1, v2
	v_ashrrev_i32_e32 v2, 31, v2
	v_lshrrev_b32_e32 v2, 29, v2
	v_lshl_or_b32 v3, v7, 7, v10
	v_ashrrev_i32_e32 v7, 1, v5
	v_ashrrev_i32_e32 v5, 31, v5
	v_add_u32_e32 v2, v4, v2
	v_lshrrev_b32_e32 v5, 29, v5
	v_and_b32_e32 v2, -8, v2
	v_add_u32_e32 v5, v7, v5
	v_sub_u32_e32 v2, v4, v2
	v_and_b32_e32 v5, -8, v5
	v_bitop3_b32 v4, v2, v8, 1 bitop3:0x78
	v_sub_u32_e32 v5, v7, v5
	v_lshlrev_b32_e32 v144, 4, v4
	v_lshrrev_b32_e32 v4, 31, v6
	v_bitop3_b32 v7, v5, v8, 1 bitop3:0x78
	v_add_u32_e32 v6, v3, v4
	v_lshlrev_b32_e32 v141, 4, v7
	v_ashrrev_i32_e32 v7, 1, v6
	v_ashrrev_i32_e32 v6, 31, v6
	v_lshrrev_b32_e32 v6, 29, v6
	v_add_u32_e32 v6, v7, v6
	v_and_b32_e32 v6, -8, v6
	v_sub_u32_e32 v6, v7, v6
	v_bitop3_b32 v7, v6, v8, 1 bitop3:0x78
	v_lshlrev_b32_e32 v151, 4, v7
	v_or_b32_e32 v7, 32, v3
	v_lshlrev_b32_e32 v152, 7, v7
	v_add_u32_e32 v7, v7, v4
	v_ashrrev_i32_e32 v9, 1, v7
	v_ashrrev_i32_e32 v7, 31, v7
	v_lshrrev_b32_e32 v7, 29, v7
	v_add_u32_e32 v7, v9, v7
	v_and_b32_e32 v7, -8, v7
	v_sub_u32_e32 v7, v9, v7
	v_bitop3_b32 v9, v7, v8, 1 bitop3:0x78
	v_lshlrev_b32_e32 v143, 7, v3
	v_lshlrev_b32_e32 v154, 4, v9
	v_or_b32_e32 v9, 64, v3
	v_or_b32_e32 v3, 0x60, v3
	v_lshlrev_b32_e32 v156, 7, v3
	v_add_u32_e32 v3, v3, v4
	v_lshlrev_b32_e32 v153, 7, v9
	v_add_u32_e32 v9, v9, v4
	v_ashrrev_i32_e32 v4, 1, v3
	v_ashrrev_i32_e32 v3, 31, v3
	v_lshrrev_b32_e32 v3, 29, v3
	v_add_u32_e32 v3, v4, v3
	v_and_b32_e32 v3, -8, v3
	v_sub_u32_e32 v3, v4, v3
	v_ashrrev_i32_e32 v10, 1, v9
	v_ashrrev_i32_e32 v9, 31, v9
	v_bitop3_b32 v4, v3, v8, 1 bitop3:0x78
	v_lshrrev_b32_e32 v9, 29, v9
	v_lshlrev_b32_e32 v164, 4, v4
	v_bitop3_b32 v4, v5, v11, 2 bitop3:0x1e
	v_add_u32_e32 v9, v10, v9
	v_lshlrev_b32_e32 v161, 4, v4
	v_bitop3_b32 v4, v2, v11, 2 bitop3:0x1e
	v_and_b32_e32 v9, -8, v9
	v_lshlrev_b32_e32 v163, 4, v4
	v_bitop3_b32 v4, v6, v11, 2 bitop3:0x1e
	v_sub_u32_e32 v9, v10, v9
	v_lshlrev_b32_e32 v159, 4, v4
	v_bitop3_b32 v4, v7, v11, 2 bitop3:0x1e
	v_lshlrev_b32_e32 v160, 4, v4
	v_bitop3_b32 v4, v9, v11, 2 bitop3:0x1e
	v_lshlrev_b32_e32 v157, 4, v4
	v_bitop3_b32 v4, v3, v11, 2 bitop3:0x1e
	v_lshlrev_b32_e32 v158, 4, v4
	v_bitop3_b32 v4, v5, v11, 4 bitop3:0x1e
	v_lshlrev_b32_e32 v149, 4, v4
	v_bitop3_b32 v4, v2, v11, 4 bitop3:0x1e
	v_bitop3_b32 v2, v2, v11, 6 bitop3:0x1e
	v_lshlrev_b32_e32 v150, 4, v4
	v_bitop3_b32 v4, v6, v11, 4 bitop3:0x1e
	v_lshlrev_b32_e32 v140, 4, v2
	v_bitop3_b32 v2, v6, v11, 6 bitop3:0x1e
	v_lshlrev_b32_e32 v147, 4, v4
	v_bitop3_b32 v4, v7, v11, 4 bitop3:0x1e
	v_lshlrev_b32_e32 v137, 4, v2
	v_bitop3_b32 v2, v7, v11, 6 bitop3:0x1e
	s_add_u32 s42, s14, s41
	v_lshlrev_b32_e32 v148, 4, v4
	v_bitop3_b32 v4, v9, v11, 4 bitop3:0x1e
	v_lshlrev_b32_e32 v138, 4, v2
	v_bitop3_b32 v2, v9, v11, 6 bitop3:0x1e
	s_addc_u32 s43, s15, 0
	s_waitcnt vmcnt(0)
; DI f32x16 zero16() { f32x16 z; for (int i = 0; i < 16; ++i) z[i] = 0.f; return z; }
; template <int BK> DI int swz(int row) { constexpr int CPR = BK / 8; return (row / (16 / CPR)) % CPR; }
; DI void wait_vm0() { asm volatile("s_waitcnt vmcnt(0)" ::: "memory"); }
;     ...
;   f32x16 acc[2][NTW];
; #pragma unroll
;   for (int a = 0; a < 2; ++a)
; #pragma unroll
;     for (int b = 0; b < NTW; ++b) acc[a][b] = zero16();
;   const bf16_t* Ag = A + (size_t)row0 * lda; const bf16_t* Bg = Bt + (size_t)col0 * ldb;
;   const int wv = __builtin_amdgcn_readfirstlane(tid >> 6);
;   __syncthreads();
;   if (!pre) { stage_tile<BM, BK>(Ag, lda, lds, tid); stage_tile<BN, BK>(Bg, ldb, lds + ABYTES, tid); }
;   wait_vm0();
;   __syncthreads();
;   const int nk = K / BK;
;   for (int kt = 0; kt < nk; ++kt) {
;     char* cur = lds + (kt & 1) * STG; char* nxt = lds + ((kt + 1) & 1) * STG;
;     const bool more = kt + 1 < nk;
;     const bf16_t* An = Ag + (kt + 1) * BK; const bf16_t* Bn = Bg + (kt + 1) * BK;
;     if (!more) epi.pre(row0 + wm * 64, col0 + wn * (32 * NTW), lane, w, lds);
;     bf16x8 fa[2][2], fb[2][NTW];
; #pragma unroll
;     for (int mt = 0; mt < 2; ++mt) { int row = wm * 64 + mt * 32 + l31; fa[0][mt] = *(const bf16x8*)(cur + row * (BK * 2) + ((hh ^ swz<BK>(row)) << 4)); }
; #pragma unroll
;     for (int nt = 0; nt < NTW; ++nt) { int row = wn * (32 * NTW) + nt * 32 + l31; fb[0][nt] = *(const bf16x8*)(cur + ABYTES + row * (BK * 2) + ((hh ^ swz<BK>(row)) << 4)); }
; #pragma unroll
;     for (int kk = 0; kk < NKK; ++kk) {
;       if (kk + 1 < NKK) {
;         const int ch = (kk + 1) * 2 + hh;
; #pragma unroll
;         for (int mt = 0; mt < 2; ++mt) { int row = wm * 64 + mt * 32 + l31; fa[(kk + 1) & 1][mt] = *(const bf16x8*)(cur + row * (BK * 2) + ((ch ^ swz<BK>(row)) << 4)); }
; #pragma unroll
;         for (int nt = 0; nt < NTW; ++nt) { int row = wn * (32 * NTW) + nt * 32 + l31; fb[(kk + 1) & 1][nt] = *(const bf16x8*)(cur + ABYTES + row * (BK * 2) + ((ch ^ swz<BK>(row)) << 4)); }
;       }
;       if (more) {
; #pragma unroll
;         for (int q = 0; q < PPK; ++q) {
;           const int pi = kk * PPK + q;
;           if (pi < NPA) stage_piece<BM, BK>(An, lda, nxt, tid, pi, wv);
;           else if (pi < NP) stage_piece<BN, BK>(Bn, ldb, nxt + ABYTES, tid, pi - NPA, wv);
;         }
	v_lshlrev_b32_e32 v145, 4, v4
	v_bitop3_b32 v4, v3, v11, 4 bitop3:0x1e
	v_lshlrev_b32_e32 v134, 4, v2
	v_bitop3_b32 v2, v3, v11, 6 bitop3:0x1e
	s_add_u32 s30, s30, s35
	v_bitop3_b32 v10, v9, v8, 1 bitop3:0x78
	v_lshlrev_b32_e32 v146, 4, v4
	v_bitop3_b32 v4, v5, v11, 6 bitop3:0x1e
	v_lshlrev_b32_e32 v135, 4, v2
	s_addc_u32 s31, s31, 0
	v_mov_b32_e32 v2, 0
	v_lshlrev_b32_e32 v155, 4, v10
	v_lshlrev_b32_e32 v139, 4, v4
	v_lshl_add_u64 v[130:131], s[42:43], 0, v[0:1]
	v_lshl_add_u64 v[132:133], s[30:31], 0, v[0:1]
	s_mov_b64 s[30:31], 0
	s_mov_b32 s35, 0x10000
	v_mov_b32_e32 v3, v2
	v_mov_b32_e32 v4, v2
	v_mov_b32_e32 v5, v2
	v_mov_b32_e32 v6, v2
	v_mov_b32_e32 v7, v2
	v_mov_b32_e32 v8, v2
	v_mov_b32_e32 v9, v2
	v_mov_b32_e32 v10, v2
	v_mov_b32_e32 v11, v2
	v_mov_b32_e32 v12, v2
	v_mov_b32_e32 v13, v2
	v_mov_b32_e32 v14, v2
	v_mov_b32_e32 v15, v2
	v_mov_b32_e32 v16, v2
	v_mov_b32_e32 v17, v2
	v_mov_b32_e32 v18, v2
	v_mov_b32_e32 v19, v2
	v_mov_b32_e32 v20, v2
	v_mov_b32_e32 v21, v2
	v_mov_b32_e32 v22, v2
	v_mov_b32_e32 v23, v2
	v_mov_b32_e32 v24, v2
	v_mov_b32_e32 v25, v2
	v_mov_b32_e32 v26, v2
	v_mov_b32_e32 v27, v2
	v_mov_b32_e32 v28, v2
	v_mov_b32_e32 v29, v2
	v_mov_b32_e32 v30, v2
	v_mov_b32_e32 v31, v2
	v_mov_b32_e32 v32, v2
	v_mov_b32_e32 v33, v2
	v_mov_b32_e32 v34, v2
	v_mov_b32_e32 v35, v2
	v_mov_b32_e32 v36, v2
	v_mov_b32_e32 v37, v2
	v_mov_b32_e32 v38, v2
	v_mov_b32_e32 v39, v2
	v_mov_b32_e32 v40, v2
	v_mov_b32_e32 v41, v2
	v_mov_b32_e32 v42, v2
	v_mov_b32_e32 v43, v2
	v_mov_b32_e32 v44, v2
	v_mov_b32_e32 v45, v2
	v_mov_b32_e32 v46, v2
	v_mov_b32_e32 v47, v2
	v_mov_b32_e32 v48, v2
	v_mov_b32_e32 v49, v2
	v_mov_b32_e32 v50, v2
	v_mov_b32_e32 v51, v2
	v_mov_b32_e32 v52, v2
	v_mov_b32_e32 v53, v2
	v_mov_b32_e32 v54, v2
	v_mov_b32_e32 v55, v2
	v_mov_b32_e32 v56, v2
	v_mov_b32_e32 v57, v2
	v_mov_b32_e32 v58, v2
	v_mov_b32_e32 v59, v2
	v_mov_b32_e32 v60, v2
	v_mov_b32_e32 v61, v2
	v_mov_b32_e32 v62, v2
	v_mov_b32_e32 v63, v2
	v_mov_b32_e32 v64, v2
	v_mov_b32_e32 v65, v2
	v_mov_b32_e32 v66, v2
	v_mov_b32_e32 v67, v2
	v_mov_b32_e32 v68, v2
	v_mov_b32_e32 v69, v2
	v_mov_b32_e32 v70, v2
	v_mov_b32_e32 v71, v2
	v_mov_b32_e32 v72, v2
	v_mov_b32_e32 v73, v2
	v_mov_b32_e32 v74, v2
	v_mov_b32_e32 v75, v2
	v_mov_b32_e32 v76, v2
	v_mov_b32_e32 v77, v2
	v_mov_b32_e32 v78, v2
	v_mov_b32_e32 v79, v2
	v_mov_b32_e32 v80, v2
	v_mov_b32_e32 v81, v2
	v_mov_b32_e32 v82, v2
	v_mov_b32_e32 v83, v2
	v_mov_b32_e32 v84, v2
	v_mov_b32_e32 v85, v2
	v_mov_b32_e32 v86, v2
	v_mov_b32_e32 v87, v2
	v_mov_b32_e32 v88, v2
	v_mov_b32_e32 v89, v2
	v_mov_b32_e32 v90, v2
	v_mov_b32_e32 v91, v2
	v_mov_b32_e32 v92, v2
	v_mov_b32_e32 v93, v2
	v_mov_b32_e32 v94, v2
	v_mov_b32_e32 v95, v2
	v_mov_b32_e32 v96, v2
	v_mov_b32_e32 v97, v2
	v_mov_b32_e32 v98, v2
	v_mov_b32_e32 v99, v2
	v_mov_b32_e32 v100, v2
	v_mov_b32_e32 v101, v2
	v_mov_b32_e32 v102, v2
	v_mov_b32_e32 v103, v2
	v_mov_b32_e32 v104, v2
	v_mov_b32_e32 v105, v2
	v_mov_b32_e32 v106, v2
	v_mov_b32_e32 v107, v2
	v_mov_b32_e32 v108, v2
	v_mov_b32_e32 v109, v2
	v_mov_b32_e32 v110, v2
	v_mov_b32_e32 v111, v2
	v_mov_b32_e32 v112, v2
	v_mov_b32_e32 v113, v2
	v_mov_b32_e32 v114, v2
	v_mov_b32_e32 v115, v2
	v_mov_b32_e32 v116, v2
	v_mov_b32_e32 v117, v2
	v_mov_b32_e32 v118, v2
	v_mov_b32_e32 v119, v2
	v_mov_b32_e32 v120, v2
	v_mov_b32_e32 v121, v2
	v_mov_b32_e32 v122, v2
	v_mov_b32_e32 v123, v2
	v_mov_b32_e32 v124, v2
	v_mov_b32_e32 v125, v2
	v_mov_b32_e32 v126, v2
	v_mov_b32_e32 v127, v2
	v_mov_b32_e32 v128, v2
	v_mov_b32_e32 v129, v2
	s_waitcnt vmcnt(0) lgkmcnt(0)
	s_barrier
	v_add_u32_e32 v166, v136, v141
	v_add_u32_e32 v170, v142, v144
	ds_read_b128 v[166:169], v166
	v_add_u32_e32 v174, v143, v151
	ds_read_b128 v[170:173], v170
	v_add_u32_e32 v178, v152, v154
	ds_read_b128 v[174:177], v174 offset:32768
	v_add_u32_e32 v182, v153, v155
	ds_read_b128 v[178:181], v178 offset:32768
	v_add_u32_e32 v186, v156, v164
	ds_read_b128 v[182:185], v182 offset:32768
	ds_read_b128 v[186:189], v186 offset:32768
	s_and_b32 s42, s35, 0x10000
	s_add_i32 s41, s42, s34
	v_lshl_add_u64 v[214:215], v[130:131], 0, s[30:31]
	v_lshl_add_u64 v[226:227], v[132:133], 0, s[30:31]
	s_add_i32 m0, s41, 0x8000
	v_lshl_add_u64 v[228:229], v[226:227], 0, s[28:29]
	global_load_lds_dwordx4 v[228:229], off
	s_add_i32 m0, s41, 0xa000
	v_lshl_add_u64 v[228:229], v[226:227], 0, s[24:25]
	global_load_lds_dwordx4 v[228:229], off
	s_add_i32 m0, s41, 0xc000
	v_lshl_add_u64 v[228:229], v[226:227], 0, s[26:27]
	global_load_lds_dwordx4 v[228:229], off
	s_add_i32 m0, s41, 0xe000
	v_lshl_add_u64 v[228:229], v[226:227], 0, s[38:39]
	global_load_lds_dwordx4 v[228:229], off
; DI f32x16 mfma(bf16x8 a, bf16x8 b, f32x16 c) { return __builtin_amdgcn_mfma_f32_32x32x16_bf16(a, b, c, 0, 0, 0); }
; template <int BK> DI int swz(int row) { constexpr int CPR = BK / 8; return (row / (16 / CPR)) % CPR; }
; DI void wait_vm0() { asm volatile("s_waitcnt vmcnt(0)" ::: "memory"); }
;   DI void pre(int grow0, int gcol0, int lane, int w, char* lds) { xpass(0, grow0, gcol0, lane, w, lds); }
;     ...
;   for (int kt = 0; kt < nk; ++kt) {
;     char* cur = lds + (kt & 1) * STG; char* nxt = lds + ((kt + 1) & 1) * STG;
;     const bool more = kt + 1 < nk;
;     const bf16_t* An = Ag + (kt + 1) * BK; const bf16_t* Bn = Bg + (kt + 1) * BK;
;     if (!more) epi.pre(row0 + wm * 64, col0 + wn * (32 * NTW), lane, w, lds);
;     bf16x8 fa[2][2], fb[2][NTW];
; #pragma unroll
;     for (int mt = 0; mt < 2; ++mt) { int row = wm * 64 + mt * 32 + l31; fa[0][mt] = *(const bf16x8*)(cur + row * (BK * 2) + ((hh ^ swz<BK>(row)) << 4)); }
; #pragma unroll
;     for (int nt = 0; nt < NTW; ++nt) { int row = wn * (32 * NTW) + nt * 32 + l31; fb[0][nt] = *(const bf16x8*)(cur + ABYTES + row * (BK * 2) + ((hh ^ swz<BK>(row)) << 4)); }
; #pragma unroll
;     for (int kk = 0; kk < NKK; ++kk) {
;       if (kk + 1 < NKK) {
;         const int ch = (kk + 1) * 2 + hh;
; #pragma unroll
;         for (int mt = 0; mt < 2; ++mt) { int row = wm * 64 + mt * 32 + l31; fa[(kk + 1) & 1][mt] = *(const bf16x8*)(cur + row * (BK * 2) + ((ch ^ swz<BK>(row)) << 4)); }
; #pragma unroll
;         for (int nt = 0; nt < NTW; ++nt) { int row = wn * (32 * NTW) + nt * 32 + l31; fb[(kk + 1) & 1][nt] = *(const bf16x8*)(cur + ABYTES + row * (BK * 2) + ((ch ^ swz<BK>(row)) << 4)); }
;       }
;       if (more) {
; #pragma unroll
;         for (int q = 0; q < PPK; ++q) {
;           const int pi = kk * PPK + q;
;           if (pi < NPA) stage_piece<BM, BK>(An, lda, nxt, tid, pi, wv);
;           else if (pi < NP) stage_piece<BN, BK>(Bn, ldb, nxt + ABYTES, tid, pi - NPA, wv);
;         }
;       }
;       __builtin_amdgcn_s_setprio(1);
; #pragma unroll
;       for (int mt = 0; mt < 2; ++mt)
; #pragma unroll
;         for (int nt = 0; nt < NTW; ++nt) acc[mt][nt] = mfma(fa[kk & 1][mt], fb[kk & 1][nt], acc[mt][nt]);
;       __builtin_amdgcn_s_setprio(0);
;       __builtin_amdgcn_sched_barrier(0);
;     }
;     wait_vm0();
;     __syncthreads();
.LBB0_627:
	s_and_b32 s42, s35, 0x10000
	s_xor_b32 s100, s42, 0x10000
	v_add3_u32 v190, s100, v136, v161
	v_add3_u32 v194, s100, v142, v163
	ds_read_b128 v[190:193], v190
	v_add3_u32 v198, s100, v143, v159
	ds_read_b128 v[194:197], v194
	v_add3_u32 v202, s100, v152, v160
	ds_read_b128 v[198:201], v198 offset:32768
	v_add3_u32 v206, s100, v153, v157
	ds_read_b128 v[202:205], v202 offset:32768
	v_add3_u32 v210, s100, v156, v158
	ds_read_b128 v[206:209], v206 offset:32768
	ds_read_b128 v[210:213], v210 offset:32768
	s_waitcnt lgkmcnt(6)
	s_mov_b32 m0, s41
	v_lshl_add_u64 v[228:229], v[214:215], 0, s[28:29]
	v_mfma_f32_32x32x16_bf16 v[114:129], v[166:169], v[174:177], v[114:129]
	global_load_lds_dwordx4 v[228:229], off
	s_add_i32 m0, s41, 0x2000
	v_lshl_add_u64 v[228:229], v[214:215], 0, s[24:25]
	v_mfma_f32_32x32x16_bf16 v[98:113], v[166:169], v[178:181], v[98:113]
	v_mfma_f32_32x32x16_bf16 v[82:97], v[166:169], v[182:185], v[82:97]
	global_load_lds_dwordx4 v[228:229], off
	s_add_i32 m0, s41, 0x4000
	v_lshl_add_u64 v[228:229], v[214:215], 0, s[26:27]
	v_mfma_f32_32x32x16_bf16 v[66:81], v[166:169], v[186:189], v[66:81]
	v_mfma_f32_32x32x16_bf16 v[50:65], v[170:173], v[174:177], v[50:65]
	global_load_lds_dwordx4 v[228:229], off
	s_add_i32 m0, s41, 0x6000
	v_lshl_add_u64 v[228:229], v[214:215], 0, s[38:39]
	v_mfma_f32_32x32x16_bf16 v[34:49], v[170:173], v[178:181], v[34:49]
	v_mfma_f32_32x32x16_bf16 v[18:33], v[170:173], v[182:185], v[18:33]
	global_load_lds_dwordx4 v[228:229], off
	v_mfma_f32_32x32x16_bf16 v[2:17], v[170:173], v[186:189], v[2:17]
	v_add3_u32 v166, s100, v136, v149
	v_add3_u32 v170, s100, v142, v150
	ds_read_b128 v[166:169], v166
	v_add3_u32 v174, s100, v143, v147
	ds_read_b128 v[170:173], v170
	v_add3_u32 v178, s100, v152, v148
	ds_read_b128 v[174:177], v174 offset:32768
	v_add3_u32 v182, s100, v153, v145
	ds_read_b128 v[178:181], v178 offset:32768
	v_add3_u32 v186, s100, v156, v146
	ds_read_b128 v[182:185], v182 offset:32768
	ds_read_b128 v[186:189], v186 offset:32768
	s_waitcnt lgkmcnt(6)
	v_mfma_f32_32x32x16_bf16 v[114:129], v[190:193], v[198:201], v[114:129]
	v_mfma_f32_32x32x16_bf16 v[98:113], v[190:193], v[202:205], v[98:113]
	v_mfma_f32_32x32x16_bf16 v[82:97], v[190:193], v[206:209], v[82:97]
	v_mfma_f32_32x32x16_bf16 v[66:81], v[190:193], v[210:213], v[66:81]
	v_mfma_f32_32x32x16_bf16 v[50:65], v[194:197], v[198:201], v[50:65]
	v_mfma_f32_32x32x16_bf16 v[34:49], v[194:197], v[202:205], v[34:49]
	v_mfma_f32_32x32x16_bf16 v[18:33], v[194:197], v[206:209], v[18:33]
	v_mfma_f32_32x32x16_bf16 v[2:17], v[194:197], v[210:213], v[2:17]
	v_add3_u32 v190, s100, v136, v139
	v_add3_u32 v194, s100, v142, v140
	ds_read_b128 v[190:193], v190
	v_add3_u32 v198, s100, v143, v137
	ds_read_b128 v[194:197], v194
	v_add3_u32 v202, s100, v152, v138
	ds_read_b128 v[198:201], v198 offset:32768
	v_add3_u32 v206, s100, v153, v134
	ds_read_b128 v[202:205], v202 offset:32768
	v_add3_u32 v210, s100, v156, v135
	ds_read_b128 v[206:209], v206 offset:32768
	ds_read_b128 v[210:213], v210 offset:32768
	s_waitcnt lgkmcnt(6)
	v_mfma_f32_32x32x16_bf16 v[114:129], v[166:169], v[174:177], v[114:129]
	v_mfma_f32_32x32x16_bf16 v[98:113], v[166:169], v[178:181], v[98:113]
	v_mfma_f32_32x32x16_bf16 v[82:97], v[166:169], v[182:185], v[82:97]
	v_mfma_f32_32x32x16_bf16 v[66:81], v[166:169], v[186:189], v[66:81]
	v_mfma_f32_32x32x16_bf16 v[50:65], v[170:173], v[174:177], v[50:65]
	v_mfma_f32_32x32x16_bf16 v[34:49], v[170:173], v[178:181], v[34:49]
	v_mfma_f32_32x32x16_bf16 v[18:33], v[170:173], v[182:185], v[18:33]
	v_mfma_f32_32x32x16_bf16 v[2:17], v[170:173], v[186:189], v[2:17]
	s_add_u32 s30, s30, 0x80
	s_addc_u32 s31, s31, 0
	s_add_i32 s35, s35, 0x10000
	s_waitcnt vmcnt(0) lgkmcnt(0)
	s_barrier
	v_add3_u32 v166, s42, v136, v141
	v_add3_u32 v170, s42, v142, v144
	ds_read_b128 v[166:169], v166
	v_add3_u32 v174, s42, v143, v151
	ds_read_b128 v[170:173], v170
	v_add3_u32 v178, s42, v152, v154
	ds_read_b128 v[174:177], v174 offset:32768
	v_add3_u32 v182, s42, v153, v155
	ds_read_b128 v[178:181], v178 offset:32768
	v_add3_u32 v186, s42, v156, v164
	ds_read_b128 v[182:185], v182 offset:32768
	ds_read_b128 v[186:189], v186 offset:32768
	s_cmpk_lg_i32 s30, 0x780
	s_cbranch_scc0 .Lk627_exit
	s_add_i32 s41, s100, s34
	v_lshl_add_u64 v[214:215], v[130:131], 0, s[30:31]
	v_lshl_add_u64 v[226:227], v[132:133], 0, s[30:31]
	s_add_i32 m0, s41, 0x8000
	v_lshl_add_u64 v[228:229], v[226:227], 0, s[28:29]
	v_mfma_f32_32x32x16_bf16 v[114:129], v[190:193], v[198:201], v[114:129]
	global_load_lds_dwordx4 v[228:229], off
	s_add_i32 m0, s41, 0xa000
	v_lshl_add_u64 v[228:229], v[226:227], 0, s[24:25]
	v_mfma_f32_32x32x16_bf16 v[98:113], v[190:193], v[202:205], v[98:113]
	v_mfma_f32_32x32x16_bf16 v[82:97], v[190:193], v[206:209], v[82:97]
	global_load_lds_dwordx4 v[228:229], off
	s_add_i32 m0, s41, 0xc000
	v_lshl_add_u64 v[228:229], v[226:227], 0, s[26:27]
	v_mfma_f32_32x32x16_bf16 v[66:81], v[190:193], v[210:213], v[66:81]
	v_mfma_f32_32x32x16_bf16 v[50:65], v[194:197], v[198:201], v[50:65]
	global_load_lds_dwordx4 v[228:229], off
	s_add_i32 m0, s41, 0xe000
	v_lshl_add_u64 v[228:229], v[226:227], 0, s[38:39]
	v_mfma_f32_32x32x16_bf16 v[34:49], v[194:197], v[202:205], v[34:49]
	v_mfma_f32_32x32x16_bf16 v[18:33], v[194:197], v[206:209], v[18:33]
	global_load_lds_dwordx4 v[228:229], off
	v_mfma_f32_32x32x16_bf16 v[2:17], v[194:197], v[210:213], v[2:17]
	s_branch .LBB0_627
